# LDS-DMA stages: M0 write placed before the address VALU so the VALU fills the M0 wait state (88 s_nop removed)
# speedup vs baseline: 1.0068x; 1.0068x over previous
; #define PG8_STAGE(bufoff, gbase, voff) do { _Pragma("unroll") for (int _i = 0; _i < 2; ++_i) \
;         __builtin_amdgcn_global_load_lds((const unsigned*)((const char*)(gbase) + (voff)[_i]), (PG8_LAS unsigned*)(lds + (bufoff) + ldsw + _i * 8192), 16, 0, 0); } while (0)
; #define PG8_LDA(dst, b, h) do { _Pragma("unroll") for (int m = 0; m < 4; ++m) _Pragma("unroll") for (int k = 0; k < 2; ++k) dst[m][k] = *(const PG8_LAS bf16x8*)(lds + PG8_SA(b, h) + aoff + m * 2048 + k * 1024); } while (0)
; #define PG8_LDB(dst, b, h) do { _Pragma("unroll") for (int n = 0; n < 2; ++n) _Pragma("unroll") for (int k = 0; k < 2; ++k) dst[n][k] = *(const PG8_LAS bf16x8*)(lds + PG8_SB(b, h) + boff + n * 2048 + k * 1024); } while (0)
; #define PG8_WAIT_L(n) asm volatile("s_waitcnt lgkmcnt(" #n ")" ::: "memory")
; #define PG8_BAR __builtin_amdgcn_s_barrier()
; #define PG8_SCHED __builtin_amdgcn_sched_barrier(0)
; template <class Epi, class Sched>
; __device__ __forceinline__ void gemm_phase(PG8_LAS unsigned char* lds, const Gemm g, const Sched& S, const Epi& E) {
;     ...
;         const bool has_next = S.next(ui + 1, nxt);
;         const char* nA = has_next ? (const char*)g.A + (size_t)nxt.pm * tstepA + (size_t)nxt.kc * cstep : cA; const char* nB = has_next ? (const char*)g.Bt + (size_t)nxt.pn * tstep + (size_t)nxt.kc * cstep : cB;
;         for (int t = 0; t < nt; t += 2) {
;             const bool last = (t == nt - 2);
;             const char* a1 = cA + (size_t)(t + 1) * kstep;
;             const char* a2 = last ? nA : cA + (size_t)(t + 2) * kstep; const char* b2 = last ? nB : cB + (size_t)(t + 2) * kstep;
;             const char* a3 = a2 + kstep; const char* b3 = b2 + kstep;
;             if (last && has_next) S.a_ready(nxt);
;             PG8_LDB(B0, 0, 0); PG8_SCHED; PG8_LDA(At, 0, 0); PG8_STAGE(PG8_SA(1, 1), a1 + hstep, voffA);
;             PG8_WAIT_L(8); PG8_BAR; PG8_WAIT_L(0); PG8_MMA(0, 0, At, B0); PG8_BAR; PG8_SCHED;
;             PG8_LDB(B1, 0, 1); PG8_STAGE(PG8_SB(0, 0), b2, voffB);
;             PG8_BAR; PG8_WAIT_L(0); PG8_MMA(0, 1, At, B1); PG8_BAR;
;             PG8_LDA(At, 0, 1); PG8_STAGE(PG8_SA(0, 0), a2, voffA);
;             PG8_BAR; PG8_WAIT_L(0); PG8_MMA(1, 0, At, B0); PG8_BAR; PG8_SCHED;
.LBB0_267:
	s_add_u32 s16, s16, 0x80
	s_addc_u32 s17, s17, 0
	s_add_u32 s24, s20, 0x100
	s_addc_u32 s25, s21, 0
	s_mov_b32 s20, 0
	s_add_i32 s42, s20, 2
	s_add_u32 s22, s16, 0x80
	s_addc_u32 s21, s17, 0
	s_add_i32 s43, 0, 0x10000
	v_add_u32_e32 v142, s43, v170
	ds_read_b128 v[130:133], v142
	ds_read_b128 v[134:137], v142 offset:1024
	ds_read_b128 v[138:141], v142 offset:2048
	ds_read_b128 v[142:145], v142 offset:3072
	s_cmp_eq_u32 s66, s20
	s_cselect_b32 s20, s2, s22
	s_cselect_b32 s21, s3, s21
	s_cselect_b32 s23, s13, s25
	s_cselect_b32 s22, s12, s24
	v_lshl_add_u64 v[168:169], s[16:17], 0, v[164:165]
	s_add_i32 m0, s36, 0xc000
	ds_read_b128 v[176:179], v172
	ds_read_b128 v[180:183], v172 offset:1024
	ds_read_b128 v[184:187], v172 offset:2048
	ds_read_b128 v[188:191], v172 offset:3072
	ds_read_b128 v[192:195], v172 offset:4096
	ds_read_b128 v[196:199], v172 offset:5120
	ds_read_b128 v[200:203], v172 offset:6144
	ds_read_b128 v[204:207], v172 offset:7168
	global_load_lds_dwordx4 v[168:169], off
	s_add_i32 m0, s36, 0xe000
	v_lshl_add_u64 v[168:169], s[16:17], 0, v[166:167]
	global_load_lds_dwordx4 v[168:169], off
	s_waitcnt lgkmcnt(8)
	s_barrier
	s_waitcnt lgkmcnt(7)
	v_mfma_f32_16x16x32_bf16 v[126:129], v[130:133], v[176:179], 0
	v_mfma_f32_16x16x32_bf16 v[122:125], v[138:141], v[176:179], 0
	s_waitcnt lgkmcnt(5)
	v_mfma_f32_16x16x32_bf16 v[114:117], v[130:133], v[184:187], 0
	v_mfma_f32_16x16x32_bf16 v[110:113], v[138:141], v[184:187], 0
	s_waitcnt lgkmcnt(3)
	v_mfma_f32_16x16x32_bf16 v[98:101], v[130:133], v[192:195], 0
	v_mfma_f32_16x16x32_bf16 v[94:97], v[138:141], v[192:195], 0
	s_waitcnt lgkmcnt(1)
	v_mfma_f32_16x16x32_bf16 v[82:85], v[130:133], v[200:203], 0
	v_mfma_f32_16x16x32_bf16 v[78:81], v[138:141], v[200:203], 0
	v_mfma_f32_16x16x32_bf16 v[126:129], v[134:137], v[180:183], v[126:129]
	v_mfma_f32_16x16x32_bf16 v[122:125], v[142:145], v[180:183], v[122:125]
	v_mfma_f32_16x16x32_bf16 v[114:117], v[134:137], v[188:191], v[114:117]
	v_mfma_f32_16x16x32_bf16 v[110:113], v[142:145], v[188:191], v[110:113]
	v_mfma_f32_16x16x32_bf16 v[98:101], v[134:137], v[196:199], v[98:101]
	v_mfma_f32_16x16x32_bf16 v[94:97], v[142:145], v[196:199], v[94:97]
	s_waitcnt lgkmcnt(0)
	v_mfma_f32_16x16x32_bf16 v[82:85], v[134:137], v[204:207], v[82:85]
	v_mfma_f32_16x16x32_bf16 v[78:81], v[142:145], v[204:207], v[78:81]
	s_barrier
	s_add_i32 s44, 0, 0x14000
	v_add_u32_e32 v168, s44, v170
	s_add_i32 s43, s43, s35
	ds_read_b128 v[208:211], v168
	ds_read_b128 v[212:215], v168 offset:1024
	ds_read_b128 v[216:219], v168 offset:2048
	ds_read_b128 v[234:237], v168 offset:3072
	v_lshl_add_u64 v[168:169], s[22:23], 0, v[48:49]
	s_mov_b32 m0, s43
	v_lshl_add_u64 v[224:225], s[22:23], 0, v[146:147]
	global_load_lds_dwordx4 v[168:169], off
	s_add_i32 m0, s43, 0x2000
	s_nop 0
	global_load_lds_dwordx4 v[224:225], off
	s_barrier
	s_waitcnt lgkmcnt(3)
	v_mfma_f32_16x16x32_bf16 v[118:121], v[208:211], v[176:179], 0
	s_waitcnt lgkmcnt(1)
	v_mfma_f32_16x16x32_bf16 v[106:109], v[216:219], v[176:179], 0
	v_mfma_f32_16x16x32_bf16 v[102:105], v[208:211], v[184:187], 0
	v_mfma_f32_16x16x32_bf16 v[90:93], v[216:219], v[184:187], 0
	v_mfma_f32_16x16x32_bf16 v[86:89], v[208:211], v[192:195], 0
	v_mfma_f32_16x16x32_bf16 v[74:77], v[216:219], v[192:195], 0
	v_mfma_f32_16x16x32_bf16 v[70:73], v[208:211], v[200:203], 0
	v_mfma_f32_16x16x32_bf16 v[66:69], v[216:219], v[200:203], 0
	v_mfma_f32_16x16x32_bf16 v[118:121], v[212:215], v[180:183], v[118:121]
	s_waitcnt lgkmcnt(0)
	v_mfma_f32_16x16x32_bf16 v[106:109], v[234:237], v[180:183], v[106:109]
	v_mfma_f32_16x16x32_bf16 v[102:105], v[212:215], v[188:191], v[102:105]
	v_mfma_f32_16x16x32_bf16 v[90:93], v[234:237], v[188:191], v[90:93]
	v_mfma_f32_16x16x32_bf16 v[86:89], v[212:215], v[196:199], v[86:89]
	v_mfma_f32_16x16x32_bf16 v[74:77], v[234:237], v[196:199], v[74:77]
	v_mfma_f32_16x16x32_bf16 v[70:73], v[212:215], v[204:207], v[70:73]
	v_mfma_f32_16x16x32_bf16 v[66:69], v[234:237], v[204:207], v[66:69]
	s_mov_b32 m0, s36
	v_lshl_add_u64 v[228:229], s[20:21], 0, v[48:49]
	s_barrier
	ds_read_b128 v[176:179], v172 offset:16384
	ds_read_b128 v[180:183], v172 offset:17408
	ds_read_b128 v[184:187], v172 offset:18432
	ds_read_b128 v[188:191], v172 offset:19456
	ds_read_b128 v[192:195], v172 offset:20480
	ds_read_b128 v[196:199], v172 offset:21504
	ds_read_b128 v[200:203], v172 offset:22528
	ds_read_b128 v[204:207], v172 offset:23552
	global_load_lds_dwordx4 v[228:229], off
	s_mov_b32 m0, s37
	v_lshl_add_u64 v[238:239], s[20:21], 0, v[146:147]
	global_load_lds_dwordx4 v[238:239], off
	s_barrier
	s_waitcnt lgkmcnt(7)
	v_mfma_f32_16x16x32_bf16 v[62:65], v[130:133], v[176:179], 0
	v_mfma_f32_16x16x32_bf16 v[58:61], v[138:141], v[176:179], 0
	s_waitcnt lgkmcnt(5)
	v_mfma_f32_16x16x32_bf16 v[50:53], v[130:133], v[184:187], 0
	v_mfma_f32_16x16x32_bf16 v[44:47], v[138:141], v[184:187], 0
	s_waitcnt lgkmcnt(3)
	v_mfma_f32_16x16x32_bf16 v[32:35], v[130:133], v[192:195], 0
	v_mfma_f32_16x16x32_bf16 v[28:31], v[138:141], v[192:195], 0
	s_waitcnt lgkmcnt(1)
	v_mfma_f32_16x16x32_bf16 v[16:19], v[130:133], v[200:203], 0
	v_mfma_f32_16x16x32_bf16 v[12:15], v[138:141], v[200:203], 0
	v_mfma_f32_16x16x32_bf16 v[62:65], v[134:137], v[180:183], v[62:65]
	v_mfma_f32_16x16x32_bf16 v[58:61], v[142:145], v[180:183], v[58:61]
	v_mfma_f32_16x16x32_bf16 v[50:53], v[134:137], v[188:191], v[50:53]
	v_mfma_f32_16x16x32_bf16 v[44:47], v[142:145], v[188:191], v[44:47]
	v_mfma_f32_16x16x32_bf16 v[32:35], v[134:137], v[196:199], v[32:35]
	v_mfma_f32_16x16x32_bf16 v[28:31], v[142:145], v[196:199], v[28:31]
	s_waitcnt lgkmcnt(0)
	v_mfma_f32_16x16x32_bf16 v[16:19], v[134:137], v[204:207], v[16:19]
	v_mfma_f32_16x16x32_bf16 v[12:15], v[142:145], v[204:207], v[12:15]
	s_barrier
; #define PG8_STAGE(bufoff, gbase, voff) do { _Pragma("unroll") for (int _i = 0; _i < 2; ++_i) \
;         __builtin_amdgcn_global_load_lds((const unsigned*)((const char*)(gbase) + (voff)[_i]), (PG8_LAS unsigned*)(lds + (bufoff) + ldsw + _i * 8192), 16, 0, 0); } while (0)
; #define PG8_LDA(dst, b, h) do { _Pragma("unroll") for (int m = 0; m < 4; ++m) _Pragma("unroll") for (int k = 0; k < 2; ++k) dst[m][k] = *(const PG8_LAS bf16x8*)(lds + PG8_SA(b, h) + aoff + m * 2048 + k * 1024); } while (0)
; #define PG8_LDB(dst, b, h) do { _Pragma("unroll") for (int n = 0; n < 2; ++n) _Pragma("unroll") for (int k = 0; k < 2; ++k) dst[n][k] = *(const PG8_LAS bf16x8*)(lds + PG8_SB(b, h) + boff + n * 2048 + k * 1024); } while (0)
; #define PG8_MMA(ai, bj, At, Bt) do { __builtin_amdgcn_s_setprio(1); _Pragma("unroll") for (int m = 0; m < 4; ++m) _Pragma("unroll") for (int n = 0; n < 2; ++n) _Pragma("unroll") for (int k = 0; k < 2; ++k) \
;         acc[ai][bj][m][n] = __builtin_amdgcn_mfma_f32_16x16x32_bf16(Bt[n][k], At[m][k], acc[ai][bj][m][n], 0, 0, 0); __builtin_amdgcn_s_setprio(0); } while (0)
; #define PG8_WAIT_V(n) asm volatile("s_waitcnt vmcnt(" #n ")" ::: "memory")
; #define PG8_WAIT_L(n) asm volatile("s_waitcnt lgkmcnt(" #n ")" ::: "memory")
; #define PG8_BAR __builtin_amdgcn_s_barrier()
; #define PG8_SCHED __builtin_amdgcn_sched_barrier(0)
; template <class Epi, class Sched>
; __device__ __forceinline__ void gemm_phase(PG8_LAS unsigned char* lds, const Gemm g, const Sched& S, const Epi& E) {
;     ...
;             PG8_STAGE(PG8_SB(0, 1), b2 + hstep, voffB);
;             PG8_WAIT_V(6); PG8_BAR; PG8_MMA(1, 1, At, B1); PG8_BAR;
;             PG8_LDB(B0, 1, 0); PG8_SCHED; PG8_LDA(At, 1, 0); PG8_STAGE(PG8_SA(0, 1), a2 + hstep, voffA);
;             PG8_WAIT_L(8); PG8_BAR; PG8_WAIT_L(0); PG8_MMA(0, 0, At, B0); PG8_BAR; PG8_SCHED;
;             PG8_LDB(B1, 1, 1); PG8_STAGE(PG8_SB(1, 0), b3, voffB);
;             PG8_BAR; PG8_WAIT_L(0); PG8_MMA(0, 1, At, B1); PG8_BAR;
;             PG8_LDA(At, 1, 1); PG8_STAGE(PG8_SA(1, 0), a3, voffA);
;             PG8_BAR; PG8_WAIT_L(0); PG8_MMA(1, 0, At, B0); PG8_BAR; PG8_SCHED;
	s_add_u32 s22, s22, s10
	s_addc_u32 s23, s23, 0
	s_add_i32 s43, s44, s35
	v_lshl_add_u64 v[240:241], s[22:23], 0, v[48:49]
	s_mov_b32 m0, s43
	v_lshl_add_u64 v[242:243], s[22:23], 0, v[146:147]
	global_load_lds_dwordx4 v[240:241], off
	s_add_i32 m0, s43, 0x2000
	s_nop 0
	global_load_lds_dwordx4 v[242:243], off
	s_waitcnt vmcnt(6)
	s_barrier
	v_mfma_f32_16x16x32_bf16 v[54:57], v[208:211], v[176:179], 0
	v_mfma_f32_16x16x32_bf16 v[40:43], v[216:219], v[176:179], 0
	v_mfma_f32_16x16x32_bf16 v[36:39], v[208:211], v[184:187], 0
	v_mfma_f32_16x16x32_bf16 v[24:27], v[216:219], v[184:187], 0
	v_mfma_f32_16x16x32_bf16 v[20:23], v[208:211], v[192:195], 0
	v_mfma_f32_16x16x32_bf16 v[8:11], v[216:219], v[192:195], 0
	v_mfma_f32_16x16x32_bf16 v[4:7], v[208:211], v[200:203], 0
	v_mfma_f32_16x16x32_bf16 v[0:3], v[216:219], v[200:203], 0
	v_mfma_f32_16x16x32_bf16 v[54:57], v[212:215], v[180:183], v[54:57]
	v_mfma_f32_16x16x32_bf16 v[40:43], v[234:237], v[180:183], v[40:43]
	v_mfma_f32_16x16x32_bf16 v[36:39], v[212:215], v[188:191], v[36:39]
	v_mfma_f32_16x16x32_bf16 v[24:27], v[234:237], v[188:191], v[24:27]
	v_mfma_f32_16x16x32_bf16 v[20:23], v[212:215], v[196:199], v[20:23]
	v_mfma_f32_16x16x32_bf16 v[8:11], v[234:237], v[196:199], v[8:11]
	v_mfma_f32_16x16x32_bf16 v[4:7], v[212:215], v[204:207], v[4:7]
	v_mfma_f32_16x16x32_bf16 v[0:3], v[234:237], v[204:207], v[0:3]
	s_add_i32 s22, 0, 0x18000
	v_add_u32_e32 v142, s22, v170
	s_barrier
	ds_read_b128 v[130:133], v142
	ds_read_b128 v[134:137], v142 offset:1024
	ds_read_b128 v[138:141], v142 offset:2048
	ds_read_b128 v[142:145], v142 offset:3072
	s_add_u32 s20, s20, s10
	s_addc_u32 s21, s21, 0
	s_mov_b32 m0, s38
	v_lshl_add_u64 v[208:209], s[20:21], 0, v[48:49]
	ds_read_b128 v[176:179], v172 offset:32768
	ds_read_b128 v[180:183], v172 offset:33792
	ds_read_b128 v[184:187], v172 offset:34816
	ds_read_b128 v[188:191], v172 offset:35840
	ds_read_b128 v[192:195], v172 offset:36864
	ds_read_b128 v[196:199], v172 offset:37888
	ds_read_b128 v[200:203], v172 offset:38912
	ds_read_b128 v[204:207], v172 offset:39936
	global_load_lds_dwordx4 v[208:209], off
	s_mov_b32 m0, s39
	v_lshl_add_u64 v[208:209], s[20:21], 0, v[146:147]
	global_load_lds_dwordx4 v[208:209], off
	s_waitcnt lgkmcnt(8)
	s_barrier
	s_waitcnt lgkmcnt(7)
	v_mfma_f32_16x16x32_bf16 v[126:129], v[130:133], v[176:179], v[126:129]
	v_mfma_f32_16x16x32_bf16 v[122:125], v[138:141], v[176:179], v[122:125]
	s_waitcnt lgkmcnt(5)
	v_mfma_f32_16x16x32_bf16 v[114:117], v[130:133], v[184:187], v[114:117]
	v_mfma_f32_16x16x32_bf16 v[110:113], v[138:141], v[184:187], v[110:113]
	s_waitcnt lgkmcnt(3)
	v_mfma_f32_16x16x32_bf16 v[98:101], v[130:133], v[192:195], v[98:101]
	v_mfma_f32_16x16x32_bf16 v[94:97], v[138:141], v[192:195], v[94:97]
	s_waitcnt lgkmcnt(1)
	v_mfma_f32_16x16x32_bf16 v[82:85], v[130:133], v[200:203], v[82:85]
	v_mfma_f32_16x16x32_bf16 v[78:81], v[138:141], v[200:203], v[78:81]
	v_mfma_f32_16x16x32_bf16 v[126:129], v[134:137], v[180:183], v[126:129]
	v_mfma_f32_16x16x32_bf16 v[122:125], v[142:145], v[180:183], v[122:125]
	v_mfma_f32_16x16x32_bf16 v[114:117], v[134:137], v[188:191], v[114:117]
	v_mfma_f32_16x16x32_bf16 v[110:113], v[142:145], v[188:191], v[110:113]
	v_mfma_f32_16x16x32_bf16 v[98:101], v[134:137], v[196:199], v[98:101]
	v_mfma_f32_16x16x32_bf16 v[94:97], v[142:145], v[196:199], v[94:97]
	s_waitcnt lgkmcnt(0)
	v_mfma_f32_16x16x32_bf16 v[82:85], v[134:137], v[204:207], v[82:85]
	v_mfma_f32_16x16x32_bf16 v[78:81], v[142:145], v[204:207], v[78:81]
	s_barrier
	s_add_i32 s20, 0, 0x1c000
	s_add_i32 s21, s22, s35
	v_add_u32_e32 v173, s20, v170
	v_lshl_add_u64 v[168:169], v[168:169], 0, s[0:1]
	s_mov_b32 m0, s21
	ds_read_b128 v[208:211], v173
	ds_read_b128 v[212:215], v173 offset:1024
	ds_read_b128 v[216:219], v173 offset:2048
	ds_read_b128 v[234:237], v173 offset:3072
	global_load_lds_dwordx4 v[168:169], off
	s_add_i32 m0, s21, 0x2000
	v_lshl_add_u64 v[168:169], v[224:225], 0, s[0:1]
	global_load_lds_dwordx4 v[168:169], off
	s_barrier
	s_waitcnt lgkmcnt(3)
	v_mfma_f32_16x16x32_bf16 v[118:121], v[208:211], v[176:179], v[118:121]
	s_waitcnt lgkmcnt(1)
	v_mfma_f32_16x16x32_bf16 v[106:109], v[216:219], v[176:179], v[106:109]
	v_mfma_f32_16x16x32_bf16 v[102:105], v[208:211], v[184:187], v[102:105]
	v_mfma_f32_16x16x32_bf16 v[90:93], v[216:219], v[184:187], v[90:93]
	v_mfma_f32_16x16x32_bf16 v[86:89], v[208:211], v[192:195], v[86:89]
	v_mfma_f32_16x16x32_bf16 v[74:77], v[216:219], v[192:195], v[74:77]
	v_mfma_f32_16x16x32_bf16 v[70:73], v[208:211], v[200:203], v[70:73]
	v_mfma_f32_16x16x32_bf16 v[66:69], v[216:219], v[200:203], v[66:69]
	v_mfma_f32_16x16x32_bf16 v[118:121], v[212:215], v[180:183], v[118:121]
	s_waitcnt lgkmcnt(0)
	v_mfma_f32_16x16x32_bf16 v[106:109], v[234:237], v[180:183], v[106:109]
	v_mfma_f32_16x16x32_bf16 v[102:105], v[212:215], v[188:191], v[102:105]
	v_mfma_f32_16x16x32_bf16 v[90:93], v[234:237], v[188:191], v[90:93]
	v_mfma_f32_16x16x32_bf16 v[86:89], v[212:215], v[196:199], v[86:89]
	v_mfma_f32_16x16x32_bf16 v[74:77], v[234:237], v[196:199], v[74:77]
	v_mfma_f32_16x16x32_bf16 v[70:73], v[212:215], v[204:207], v[70:73]
	v_mfma_f32_16x16x32_bf16 v[66:69], v[234:237], v[204:207], v[66:69]
	s_mov_b32 m0, s64
	v_lshl_add_u64 v[168:169], v[228:229], 0, s[0:1]
	s_barrier
	ds_read_b128 v[176:179], v172 offset:49152
	ds_read_b128 v[180:183], v172 offset:50176
	ds_read_b128 v[184:187], v172 offset:51200
	ds_read_b128 v[188:191], v172 offset:52224
	ds_read_b128 v[192:195], v172 offset:53248
	ds_read_b128 v[196:199], v172 offset:54272
	ds_read_b128 v[200:203], v172 offset:55296
	ds_read_b128 v[204:207], v172 offset:56320
	global_load_lds_dwordx4 v[168:169], off
	s_mov_b32 m0, s65
	v_lshl_add_u64 v[168:169], v[238:239], 0, s[0:1]
	global_load_lds_dwordx4 v[168:169], off
	s_barrier
; #define PG8_STAGE(bufoff, gbase, voff) do { _Pragma("unroll") for (int _i = 0; _i < 2; ++_i) \
;         __builtin_amdgcn_global_load_lds((const unsigned*)((const char*)(gbase) + (voff)[_i]), (PG8_LAS unsigned*)(lds + (bufoff) + ldsw + _i * 8192), 16, 0, 0); } while (0)
; #define PG8_LDA(dst, b, h) do { _Pragma("unroll") for (int m = 0; m < 4; ++m) _Pragma("unroll") for (int k = 0; k < 2; ++k) dst[m][k] = *(const PG8_LAS bf16x8*)(lds + PG8_SA(b, h) + aoff + m * 2048 + k * 1024); } while (0)
; #define PG8_LDB(dst, b, h) do { _Pragma("unroll") for (int n = 0; n < 2; ++n) _Pragma("unroll") for (int k = 0; k < 2; ++k) dst[n][k] = *(const PG8_LAS bf16x8*)(lds + PG8_SB(b, h) + boff + n * 2048 + k * 1024); } while (0)
; #define PG8_MMA(ai, bj, At, Bt) do { __builtin_amdgcn_s_setprio(1); _Pragma("unroll") for (int m = 0; m < 4; ++m) _Pragma("unroll") for (int n = 0; n < 2; ++n) _Pragma("unroll") for (int k = 0; k < 2; ++k) \
;         acc[ai][bj][m][n] = __builtin_amdgcn_mfma_f32_16x16x32_bf16(Bt[n][k], At[m][k], acc[ai][bj][m][n], 0, 0, 0); __builtin_amdgcn_s_setprio(0); } while (0)
; #define PG8_WAIT_V(n) asm volatile("s_waitcnt vmcnt(" #n ")" ::: "memory")
; #define PG8_WAIT_L(n) asm volatile("s_waitcnt lgkmcnt(" #n ")" ::: "memory")
; #define PG8_BAR __builtin_amdgcn_s_barrier()
; #define PG8_SCHED __builtin_amdgcn_sched_barrier(0)
; template <class Epi, class Sched>
; __device__ __forceinline__ void gemm_phase(PG8_LAS unsigned char* lds, const Gemm g, const Sched& S, const Epi& E) {
;     ...
;             const char* a1 = cA + (size_t)(t + 1) * kstep;
;             const char* a2 = last ? nA : cA + (size_t)(t + 2) * kstep; const char* b2 = last ? nB : cB + (size_t)(t + 2) * kstep;
;             const char* a3 = a2 + kstep; const char* b3 = b2 + kstep;
;             if (last && has_next) S.a_ready(nxt);
;             PG8_LDB(B0, 0, 0); PG8_SCHED; PG8_LDA(At, 0, 0); PG8_STAGE(PG8_SA(1, 1), a1 + hstep, voffA);
;             PG8_WAIT_L(8); PG8_BAR; PG8_WAIT_L(0); PG8_MMA(0, 0, At, B0); PG8_BAR; PG8_SCHED;
;     ...
;             PG8_BAR; PG8_WAIT_L(0); PG8_MMA(1, 0, At, B0); PG8_BAR; PG8_SCHED;
;             PG8_STAGE(PG8_SB(1, 1), b3 + hstep, voffB);
;             PG8_WAIT_V(6); PG8_BAR; PG8_MMA(1, 1, At, B1); PG8_BAR;
	s_waitcnt lgkmcnt(7)
	v_mfma_f32_16x16x32_bf16 v[62:65], v[130:133], v[176:179], v[62:65]
	v_mfma_f32_16x16x32_bf16 v[58:61], v[138:141], v[176:179], v[58:61]
	s_waitcnt lgkmcnt(5)
	v_mfma_f32_16x16x32_bf16 v[50:53], v[130:133], v[184:187], v[50:53]
	v_mfma_f32_16x16x32_bf16 v[44:47], v[138:141], v[184:187], v[44:47]
	s_waitcnt lgkmcnt(3)
	v_mfma_f32_16x16x32_bf16 v[32:35], v[130:133], v[192:195], v[32:35]
	v_mfma_f32_16x16x32_bf16 v[28:31], v[138:141], v[192:195], v[28:31]
	s_waitcnt lgkmcnt(1)
	v_mfma_f32_16x16x32_bf16 v[16:19], v[130:133], v[200:203], v[16:19]
	v_mfma_f32_16x16x32_bf16 v[12:15], v[138:141], v[200:203], v[12:15]
	v_mfma_f32_16x16x32_bf16 v[62:65], v[134:137], v[180:183], v[62:65]
	v_mfma_f32_16x16x32_bf16 v[58:61], v[142:145], v[180:183], v[58:61]
	v_mfma_f32_16x16x32_bf16 v[50:53], v[134:137], v[188:191], v[50:53]
	v_mfma_f32_16x16x32_bf16 v[44:47], v[142:145], v[188:191], v[44:47]
	v_mfma_f32_16x16x32_bf16 v[32:35], v[134:137], v[196:199], v[32:35]
	v_mfma_f32_16x16x32_bf16 v[28:31], v[142:145], v[196:199], v[28:31]
	s_waitcnt lgkmcnt(0)
	v_mfma_f32_16x16x32_bf16 v[16:19], v[134:137], v[204:207], v[16:19]
	v_mfma_f32_16x16x32_bf16 v[12:15], v[142:145], v[204:207], v[12:15]
	s_barrier
	s_add_i32 s20, s20, s35
	s_mov_b32 m0, s20
	v_lshl_add_u64 v[130:131], v[240:241], 0, s[0:1]
	global_load_lds_dwordx4 v[130:131], off
	s_add_i32 m0, s20, 0x2000
	v_lshl_add_u64 v[130:131], v[242:243], 0, s[0:1]
	global_load_lds_dwordx4 v[130:131], off
	s_waitcnt vmcnt(6)
	s_barrier
	v_mfma_f32_16x16x32_bf16 v[54:57], v[208:211], v[176:179], v[54:57]
	v_mfma_f32_16x16x32_bf16 v[40:43], v[216:219], v[176:179], v[40:43]
	v_mfma_f32_16x16x32_bf16 v[36:39], v[208:211], v[184:187], v[36:39]
	v_mfma_f32_16x16x32_bf16 v[24:27], v[216:219], v[184:187], v[24:27]
	v_mfma_f32_16x16x32_bf16 v[20:23], v[208:211], v[192:195], v[20:23]
	v_mfma_f32_16x16x32_bf16 v[8:11], v[216:219], v[192:195], v[8:11]
	v_mfma_f32_16x16x32_bf16 v[4:7], v[208:211], v[200:203], v[4:7]
	v_mfma_f32_16x16x32_bf16 v[0:3], v[216:219], v[200:203], v[0:3]
	v_mfma_f32_16x16x32_bf16 v[54:57], v[212:215], v[180:183], v[54:57]
	v_mfma_f32_16x16x32_bf16 v[40:43], v[234:237], v[180:183], v[40:43]
	v_mfma_f32_16x16x32_bf16 v[36:39], v[212:215], v[188:191], v[36:39]
	v_mfma_f32_16x16x32_bf16 v[24:27], v[234:237], v[188:191], v[24:27]
	v_mfma_f32_16x16x32_bf16 v[20:23], v[212:215], v[196:199], v[20:23]
	v_mfma_f32_16x16x32_bf16 v[8:11], v[234:237], v[196:199], v[8:11]
	v_mfma_f32_16x16x32_bf16 v[4:7], v[212:215], v[204:207], v[4:7]
	v_mfma_f32_16x16x32_bf16 v[0:3], v[234:237], v[204:207], v[0:3]
	s_add_u32 s16, s16, 0x100
	s_addc_u32 s17, s17, 0
	s_add_u32 s24, s24, 0x100
	s_addc_u32 s25, s25, 0
	s_cmp_ge_u32 s42, s54
	s_mov_b32 s20, s42
	s_barrier
	s_cbranch_scc1 .Lkpeel_exit_268
.LBB0_268:
	s_add_i32 s42, s20, 2
	s_add_u32 s22, s16, 0x80
	s_addc_u32 s21, s17, 0
	s_add_i32 s43, 0, 0x10000
	v_add_u32_e32 v142, s43, v170
	ds_read_b128 v[130:133], v142
	ds_read_b128 v[134:137], v142 offset:1024
	ds_read_b128 v[138:141], v142 offset:2048
	ds_read_b128 v[142:145], v142 offset:3072
	s_cmp_eq_u32 s66, s20
	s_cselect_b32 s20, s2, s22
	s_cselect_b32 s21, s3, s21
	s_cselect_b32 s23, s13, s25
	s_cselect_b32 s22, s12, s24
	v_lshl_add_u64 v[168:169], s[16:17], 0, v[164:165]
	s_add_i32 m0, s36, 0xc000
	ds_read_b128 v[176:179], v172
	ds_read_b128 v[180:183], v172 offset:1024
	ds_read_b128 v[184:187], v172 offset:2048
	ds_read_b128 v[188:191], v172 offset:3072
	ds_read_b128 v[192:195], v172 offset:4096
	ds_read_b128 v[196:199], v172 offset:5120
	ds_read_b128 v[200:203], v172 offset:6144
	ds_read_b128 v[204:207], v172 offset:7168
	global_load_lds_dwordx4 v[168:169], off
	s_add_i32 m0, s36, 0xe000
	v_lshl_add_u64 v[168:169], s[16:17], 0, v[166:167]
	global_load_lds_dwordx4 v[168:169], off
	s_waitcnt lgkmcnt(8)
	s_barrier
	s_waitcnt lgkmcnt(7)
	v_mfma_f32_16x16x32_bf16 v[126:129], v[130:133], v[176:179], v[126:129]
	v_mfma_f32_16x16x32_bf16 v[122:125], v[138:141], v[176:179], v[122:125]
	s_waitcnt lgkmcnt(5)
	v_mfma_f32_16x16x32_bf16 v[114:117], v[130:133], v[184:187], v[114:117]
	v_mfma_f32_16x16x32_bf16 v[110:113], v[138:141], v[184:187], v[110:113]
	s_waitcnt lgkmcnt(3)
	v_mfma_f32_16x16x32_bf16 v[98:101], v[130:133], v[192:195], v[98:101]
	v_mfma_f32_16x16x32_bf16 v[94:97], v[138:141], v[192:195], v[94:97]
	s_waitcnt lgkmcnt(1)
	v_mfma_f32_16x16x32_bf16 v[82:85], v[130:133], v[200:203], v[82:85]
	v_mfma_f32_16x16x32_bf16 v[78:81], v[138:141], v[200:203], v[78:81]
	v_mfma_f32_16x16x32_bf16 v[126:129], v[134:137], v[180:183], v[126:129]
	v_mfma_f32_16x16x32_bf16 v[122:125], v[142:145], v[180:183], v[122:125]
	v_mfma_f32_16x16x32_bf16 v[114:117], v[134:137], v[188:191], v[114:117]
	v_mfma_f32_16x16x32_bf16 v[110:113], v[142:145], v[188:191], v[110:113]
	v_mfma_f32_16x16x32_bf16 v[98:101], v[134:137], v[196:199], v[98:101]
	v_mfma_f32_16x16x32_bf16 v[94:97], v[142:145], v[196:199], v[94:97]
	s_waitcnt lgkmcnt(0)
	v_mfma_f32_16x16x32_bf16 v[82:85], v[134:137], v[204:207], v[82:85]
	v_mfma_f32_16x16x32_bf16 v[78:81], v[142:145], v[204:207], v[78:81]
	s_barrier
	s_add_i32 s44, 0, 0x14000
	v_add_u32_e32 v168, s44, v170
	s_add_i32 s43, s43, s35
	ds_read_b128 v[208:211], v168
	ds_read_b128 v[212:215], v168 offset:1024
	ds_read_b128 v[216:219], v168 offset:2048
	ds_read_b128 v[234:237], v168 offset:3072
	v_lshl_add_u64 v[168:169], s[22:23], 0, v[48:49]
	s_mov_b32 m0, s43
	v_lshl_add_u64 v[224:225], s[22:23], 0, v[146:147]
	global_load_lds_dwordx4 v[168:169], off
	s_add_i32 m0, s43, 0x2000
	s_nop 0
	global_load_lds_dwordx4 v[224:225], off
	s_barrier
; #define PG8_STAGE(bufoff, gbase, voff) do { _Pragma("unroll") for (int _i = 0; _i < 2; ++_i) \
;         __builtin_amdgcn_global_load_lds((const unsigned*)((const char*)(gbase) + (voff)[_i]), (PG8_LAS unsigned*)(lds + (bufoff) + ldsw + _i * 8192), 16, 0, 0); } while (0)
; #define PG8_LDA(dst, b, h) do { _Pragma("unroll") for (int m = 0; m < 4; ++m) _Pragma("unroll") for (int k = 0; k < 2; ++k) dst[m][k] = *(const PG8_LAS bf16x8*)(lds + PG8_SA(b, h) + aoff + m * 2048 + k * 1024); } while (0)
; #define PG8_LDB(dst, b, h) do { _Pragma("unroll") for (int n = 0; n < 2; ++n) _Pragma("unroll") for (int k = 0; k < 2; ++k) dst[n][k] = *(const PG8_LAS bf16x8*)(lds + PG8_SB(b, h) + boff + n * 2048 + k * 1024); } while (0)
; #define PG8_MMA(ai, bj, At, Bt) do { __builtin_amdgcn_s_setprio(1); _Pragma("unroll") for (int m = 0; m < 4; ++m) _Pragma("unroll") for (int n = 0; n < 2; ++n) _Pragma("unroll") for (int k = 0; k < 2; ++k) \
;         acc[ai][bj][m][n] = __builtin_amdgcn_mfma_f32_16x16x32_bf16(Bt[n][k], At[m][k], acc[ai][bj][m][n], 0, 0, 0); __builtin_amdgcn_s_setprio(0); } while (0)
; #define PG8_WAIT_V(n) asm volatile("s_waitcnt vmcnt(" #n ")" ::: "memory")
; #define PG8_WAIT_L(n) asm volatile("s_waitcnt lgkmcnt(" #n ")" ::: "memory")
; #define PG8_BAR __builtin_amdgcn_s_barrier()
; #define PG8_SCHED __builtin_amdgcn_sched_barrier(0)
; template <class Epi, class Sched>
; __device__ __forceinline__ void gemm_phase(PG8_LAS unsigned char* lds, const Gemm g, const Sched& S, const Epi& E) {
;     ...
;             PG8_LDB(B1, 0, 1); PG8_STAGE(PG8_SB(0, 0), b2, voffB);
;             PG8_BAR; PG8_WAIT_L(0); PG8_MMA(0, 1, At, B1); PG8_BAR;
;             PG8_LDA(At, 0, 1); PG8_STAGE(PG8_SA(0, 0), a2, voffA);
;             PG8_BAR; PG8_WAIT_L(0); PG8_MMA(1, 0, At, B0); PG8_BAR; PG8_SCHED;
;             PG8_STAGE(PG8_SB(0, 1), b2 + hstep, voffB);
;             PG8_WAIT_V(6); PG8_BAR; PG8_MMA(1, 1, At, B1); PG8_BAR;
;             PG8_LDB(B0, 1, 0); PG8_SCHED; PG8_LDA(At, 1, 0); PG8_STAGE(PG8_SA(0, 1), a2 + hstep, voffA);
;             PG8_WAIT_L(8); PG8_BAR; PG8_WAIT_L(0); PG8_MMA(0, 0, At, B0); PG8_BAR; PG8_SCHED;
	s_waitcnt lgkmcnt(3)
	v_mfma_f32_16x16x32_bf16 v[118:121], v[208:211], v[176:179], v[118:121]
	s_waitcnt lgkmcnt(1)
	v_mfma_f32_16x16x32_bf16 v[106:109], v[216:219], v[176:179], v[106:109]
	v_mfma_f32_16x16x32_bf16 v[102:105], v[208:211], v[184:187], v[102:105]
	v_mfma_f32_16x16x32_bf16 v[90:93], v[216:219], v[184:187], v[90:93]
	v_mfma_f32_16x16x32_bf16 v[86:89], v[208:211], v[192:195], v[86:89]
	v_mfma_f32_16x16x32_bf16 v[74:77], v[216:219], v[192:195], v[74:77]
	v_mfma_f32_16x16x32_bf16 v[70:73], v[208:211], v[200:203], v[70:73]
	v_mfma_f32_16x16x32_bf16 v[66:69], v[216:219], v[200:203], v[66:69]
	v_mfma_f32_16x16x32_bf16 v[118:121], v[212:215], v[180:183], v[118:121]
	s_waitcnt lgkmcnt(0)
	v_mfma_f32_16x16x32_bf16 v[106:109], v[234:237], v[180:183], v[106:109]
	v_mfma_f32_16x16x32_bf16 v[102:105], v[212:215], v[188:191], v[102:105]
	v_mfma_f32_16x16x32_bf16 v[90:93], v[234:237], v[188:191], v[90:93]
	v_mfma_f32_16x16x32_bf16 v[86:89], v[212:215], v[196:199], v[86:89]
	v_mfma_f32_16x16x32_bf16 v[74:77], v[234:237], v[196:199], v[74:77]
	v_mfma_f32_16x16x32_bf16 v[70:73], v[212:215], v[204:207], v[70:73]
	v_mfma_f32_16x16x32_bf16 v[66:69], v[234:237], v[204:207], v[66:69]
	s_mov_b32 m0, s36
	v_lshl_add_u64 v[228:229], s[20:21], 0, v[48:49]
	s_barrier
	ds_read_b128 v[176:179], v172 offset:16384
	ds_read_b128 v[180:183], v172 offset:17408
	ds_read_b128 v[184:187], v172 offset:18432
	ds_read_b128 v[188:191], v172 offset:19456
	ds_read_b128 v[192:195], v172 offset:20480
	ds_read_b128 v[196:199], v172 offset:21504
	ds_read_b128 v[200:203], v172 offset:22528
	ds_read_b128 v[204:207], v172 offset:23552
	global_load_lds_dwordx4 v[228:229], off
	s_mov_b32 m0, s37
	v_lshl_add_u64 v[238:239], s[20:21], 0, v[146:147]
	global_load_lds_dwordx4 v[238:239], off
	s_barrier
	s_waitcnt lgkmcnt(7)
	v_mfma_f32_16x16x32_bf16 v[62:65], v[130:133], v[176:179], v[62:65]
	v_mfma_f32_16x16x32_bf16 v[58:61], v[138:141], v[176:179], v[58:61]
	s_waitcnt lgkmcnt(5)
	v_mfma_f32_16x16x32_bf16 v[50:53], v[130:133], v[184:187], v[50:53]
	v_mfma_f32_16x16x32_bf16 v[44:47], v[138:141], v[184:187], v[44:47]
	s_waitcnt lgkmcnt(3)
	v_mfma_f32_16x16x32_bf16 v[32:35], v[130:133], v[192:195], v[32:35]
	v_mfma_f32_16x16x32_bf16 v[28:31], v[138:141], v[192:195], v[28:31]
	s_waitcnt lgkmcnt(1)
	v_mfma_f32_16x16x32_bf16 v[16:19], v[130:133], v[200:203], v[16:19]
	v_mfma_f32_16x16x32_bf16 v[12:15], v[138:141], v[200:203], v[12:15]
	v_mfma_f32_16x16x32_bf16 v[62:65], v[134:137], v[180:183], v[62:65]
	v_mfma_f32_16x16x32_bf16 v[58:61], v[142:145], v[180:183], v[58:61]
	v_mfma_f32_16x16x32_bf16 v[50:53], v[134:137], v[188:191], v[50:53]
	v_mfma_f32_16x16x32_bf16 v[44:47], v[142:145], v[188:191], v[44:47]
	v_mfma_f32_16x16x32_bf16 v[32:35], v[134:137], v[196:199], v[32:35]
	v_mfma_f32_16x16x32_bf16 v[28:31], v[142:145], v[196:199], v[28:31]
	s_waitcnt lgkmcnt(0)
	v_mfma_f32_16x16x32_bf16 v[16:19], v[134:137], v[204:207], v[16:19]
	v_mfma_f32_16x16x32_bf16 v[12:15], v[142:145], v[204:207], v[12:15]
	s_barrier
	s_add_u32 s22, s22, s10
	s_addc_u32 s23, s23, 0
	s_add_i32 s43, s44, s35
	v_lshl_add_u64 v[240:241], s[22:23], 0, v[48:49]
	s_mov_b32 m0, s43
	v_lshl_add_u64 v[242:243], s[22:23], 0, v[146:147]
	global_load_lds_dwordx4 v[240:241], off
	s_add_i32 m0, s43, 0x2000
	s_nop 0
	global_load_lds_dwordx4 v[242:243], off
	s_waitcnt vmcnt(6)
	s_barrier
	v_mfma_f32_16x16x32_bf16 v[54:57], v[208:211], v[176:179], v[54:57]
	v_mfma_f32_16x16x32_bf16 v[40:43], v[216:219], v[176:179], v[40:43]
	v_mfma_f32_16x16x32_bf16 v[36:39], v[208:211], v[184:187], v[36:39]
	v_mfma_f32_16x16x32_bf16 v[24:27], v[216:219], v[184:187], v[24:27]
	v_mfma_f32_16x16x32_bf16 v[20:23], v[208:211], v[192:195], v[20:23]
	v_mfma_f32_16x16x32_bf16 v[8:11], v[216:219], v[192:195], v[8:11]
	v_mfma_f32_16x16x32_bf16 v[4:7], v[208:211], v[200:203], v[4:7]
	v_mfma_f32_16x16x32_bf16 v[0:3], v[216:219], v[200:203], v[0:3]
	v_mfma_f32_16x16x32_bf16 v[54:57], v[212:215], v[180:183], v[54:57]
	v_mfma_f32_16x16x32_bf16 v[40:43], v[234:237], v[180:183], v[40:43]
	v_mfma_f32_16x16x32_bf16 v[36:39], v[212:215], v[188:191], v[36:39]
	v_mfma_f32_16x16x32_bf16 v[24:27], v[234:237], v[188:191], v[24:27]
	v_mfma_f32_16x16x32_bf16 v[20:23], v[212:215], v[196:199], v[20:23]
	v_mfma_f32_16x16x32_bf16 v[8:11], v[234:237], v[196:199], v[8:11]
	v_mfma_f32_16x16x32_bf16 v[4:7], v[212:215], v[204:207], v[4:7]
	v_mfma_f32_16x16x32_bf16 v[0:3], v[234:237], v[204:207], v[0:3]
	s_add_i32 s22, 0, 0x18000
	v_add_u32_e32 v142, s22, v170
	s_barrier
	ds_read_b128 v[130:133], v142
	ds_read_b128 v[134:137], v142 offset:1024
	ds_read_b128 v[138:141], v142 offset:2048
	ds_read_b128 v[142:145], v142 offset:3072
	s_add_u32 s20, s20, s10
	s_addc_u32 s21, s21, 0
	s_mov_b32 m0, s38
	v_lshl_add_u64 v[208:209], s[20:21], 0, v[48:49]
	ds_read_b128 v[176:179], v172 offset:32768
	ds_read_b128 v[180:183], v172 offset:33792
	ds_read_b128 v[184:187], v172 offset:34816
	ds_read_b128 v[188:191], v172 offset:35840
	ds_read_b128 v[192:195], v172 offset:36864
	ds_read_b128 v[196:199], v172 offset:37888
	ds_read_b128 v[200:203], v172 offset:38912
	ds_read_b128 v[204:207], v172 offset:39936
	global_load_lds_dwordx4 v[208:209], off
	s_mov_b32 m0, s39
	v_lshl_add_u64 v[208:209], s[20:21], 0, v[146:147]
	global_load_lds_dwordx4 v[208:209], off
	s_waitcnt lgkmcnt(8)
	s_barrier
; #define PG8_STAGE(bufoff, gbase, voff) do { _Pragma("unroll") for (int _i = 0; _i < 2; ++_i) \
;         __builtin_amdgcn_global_load_lds((const unsigned*)((const char*)(gbase) + (voff)[_i]), (PG8_LAS unsigned*)(lds + (bufoff) + ldsw + _i * 8192), 16, 0, 0); } while (0)
; #define PG8_LDA(dst, b, h) do { _Pragma("unroll") for (int m = 0; m < 4; ++m) _Pragma("unroll") for (int k = 0; k < 2; ++k) dst[m][k] = *(const PG8_LAS bf16x8*)(lds + PG8_SA(b, h) + aoff + m * 2048 + k * 1024); } while (0)
; #define PG8_LDB(dst, b, h) do { _Pragma("unroll") for (int n = 0; n < 2; ++n) _Pragma("unroll") for (int k = 0; k < 2; ++k) dst[n][k] = *(const PG8_LAS bf16x8*)(lds + PG8_SB(b, h) + boff + n * 2048 + k * 1024); } while (0)
; #define PG8_MMA(ai, bj, At, Bt) do { __builtin_amdgcn_s_setprio(1); _Pragma("unroll") for (int m = 0; m < 4; ++m) _Pragma("unroll") for (int n = 0; n < 2; ++n) _Pragma("unroll") for (int k = 0; k < 2; ++k) \
;         acc[ai][bj][m][n] = __builtin_amdgcn_mfma_f32_16x16x32_bf16(Bt[n][k], At[m][k], acc[ai][bj][m][n], 0, 0, 0); __builtin_amdgcn_s_setprio(0); } while (0)
; #define PG8_WAIT_V(n) asm volatile("s_waitcnt vmcnt(" #n ")" ::: "memory")
; #define PG8_WAIT_L(n) asm volatile("s_waitcnt lgkmcnt(" #n ")" ::: "memory")
; #define PG8_BAR __builtin_amdgcn_s_barrier()
; #define PG8_SCHED __builtin_amdgcn_sched_barrier(0)
; template <class Epi, class Sched>
; __device__ __forceinline__ void gemm_phase(PG8_LAS unsigned char* lds, const Gemm g, const Sched& S, const Epi& E) {
;     ...
;             PG8_WAIT_L(8); PG8_BAR; PG8_WAIT_L(0); PG8_MMA(0, 0, At, B0); PG8_BAR; PG8_SCHED;
;             PG8_LDB(B1, 1, 1); PG8_STAGE(PG8_SB(1, 0), b3, voffB);
;             PG8_BAR; PG8_WAIT_L(0); PG8_MMA(0, 1, At, B1); PG8_BAR;
;             PG8_LDA(At, 1, 1); PG8_STAGE(PG8_SA(1, 0), a3, voffA);
;             PG8_BAR; PG8_WAIT_L(0); PG8_MMA(1, 0, At, B0); PG8_BAR; PG8_SCHED;
;             PG8_STAGE(PG8_SB(1, 1), b3 + hstep, voffB);
;             PG8_WAIT_V(6); PG8_BAR; PG8_MMA(1, 1, At, B1); PG8_BAR;
	s_waitcnt lgkmcnt(7)
	v_mfma_f32_16x16x32_bf16 v[126:129], v[130:133], v[176:179], v[126:129]
	v_mfma_f32_16x16x32_bf16 v[122:125], v[138:141], v[176:179], v[122:125]
	s_waitcnt lgkmcnt(5)
	v_mfma_f32_16x16x32_bf16 v[114:117], v[130:133], v[184:187], v[114:117]
	v_mfma_f32_16x16x32_bf16 v[110:113], v[138:141], v[184:187], v[110:113]
	s_waitcnt lgkmcnt(3)
	v_mfma_f32_16x16x32_bf16 v[98:101], v[130:133], v[192:195], v[98:101]
	v_mfma_f32_16x16x32_bf16 v[94:97], v[138:141], v[192:195], v[94:97]
	s_waitcnt lgkmcnt(1)
	v_mfma_f32_16x16x32_bf16 v[82:85], v[130:133], v[200:203], v[82:85]
	v_mfma_f32_16x16x32_bf16 v[78:81], v[138:141], v[200:203], v[78:81]
	v_mfma_f32_16x16x32_bf16 v[126:129], v[134:137], v[180:183], v[126:129]
	v_mfma_f32_16x16x32_bf16 v[122:125], v[142:145], v[180:183], v[122:125]
	v_mfma_f32_16x16x32_bf16 v[114:117], v[134:137], v[188:191], v[114:117]
	v_mfma_f32_16x16x32_bf16 v[110:113], v[142:145], v[188:191], v[110:113]
	v_mfma_f32_16x16x32_bf16 v[98:101], v[134:137], v[196:199], v[98:101]
	v_mfma_f32_16x16x32_bf16 v[94:97], v[142:145], v[196:199], v[94:97]
	s_waitcnt lgkmcnt(0)
	v_mfma_f32_16x16x32_bf16 v[82:85], v[134:137], v[204:207], v[82:85]
	v_mfma_f32_16x16x32_bf16 v[78:81], v[142:145], v[204:207], v[78:81]
	s_barrier
	s_add_i32 s20, 0, 0x1c000
	s_add_i32 s21, s22, s35
	v_add_u32_e32 v173, s20, v170
	v_lshl_add_u64 v[168:169], v[168:169], 0, s[0:1]
	s_mov_b32 m0, s21
	ds_read_b128 v[208:211], v173
	ds_read_b128 v[212:215], v173 offset:1024
	ds_read_b128 v[216:219], v173 offset:2048
	ds_read_b128 v[234:237], v173 offset:3072
	global_load_lds_dwordx4 v[168:169], off
	s_add_i32 m0, s21, 0x2000
	v_lshl_add_u64 v[168:169], v[224:225], 0, s[0:1]
	global_load_lds_dwordx4 v[168:169], off
	s_barrier
	s_waitcnt lgkmcnt(3)
	v_mfma_f32_16x16x32_bf16 v[118:121], v[208:211], v[176:179], v[118:121]
	s_waitcnt lgkmcnt(1)
	v_mfma_f32_16x16x32_bf16 v[106:109], v[216:219], v[176:179], v[106:109]
	v_mfma_f32_16x16x32_bf16 v[102:105], v[208:211], v[184:187], v[102:105]
	v_mfma_f32_16x16x32_bf16 v[90:93], v[216:219], v[184:187], v[90:93]
	v_mfma_f32_16x16x32_bf16 v[86:89], v[208:211], v[192:195], v[86:89]
	v_mfma_f32_16x16x32_bf16 v[74:77], v[216:219], v[192:195], v[74:77]
	v_mfma_f32_16x16x32_bf16 v[70:73], v[208:211], v[200:203], v[70:73]
	v_mfma_f32_16x16x32_bf16 v[66:69], v[216:219], v[200:203], v[66:69]
	v_mfma_f32_16x16x32_bf16 v[118:121], v[212:215], v[180:183], v[118:121]
	s_waitcnt lgkmcnt(0)
	v_mfma_f32_16x16x32_bf16 v[106:109], v[234:237], v[180:183], v[106:109]
	v_mfma_f32_16x16x32_bf16 v[102:105], v[212:215], v[188:191], v[102:105]
	v_mfma_f32_16x16x32_bf16 v[90:93], v[234:237], v[188:191], v[90:93]
	v_mfma_f32_16x16x32_bf16 v[86:89], v[212:215], v[196:199], v[86:89]
	v_mfma_f32_16x16x32_bf16 v[74:77], v[234:237], v[196:199], v[74:77]
	v_mfma_f32_16x16x32_bf16 v[70:73], v[212:215], v[204:207], v[70:73]
	v_mfma_f32_16x16x32_bf16 v[66:69], v[234:237], v[204:207], v[66:69]
	s_mov_b32 m0, s64
	v_lshl_add_u64 v[168:169], v[228:229], 0, s[0:1]
	s_barrier
	ds_read_b128 v[176:179], v172 offset:49152
	ds_read_b128 v[180:183], v172 offset:50176
	ds_read_b128 v[184:187], v172 offset:51200
	ds_read_b128 v[188:191], v172 offset:52224
	ds_read_b128 v[192:195], v172 offset:53248
	ds_read_b128 v[196:199], v172 offset:54272
	ds_read_b128 v[200:203], v172 offset:55296
	ds_read_b128 v[204:207], v172 offset:56320
	global_load_lds_dwordx4 v[168:169], off
	s_mov_b32 m0, s65
	v_lshl_add_u64 v[168:169], v[238:239], 0, s[0:1]
	global_load_lds_dwordx4 v[168:169], off
	s_barrier
	s_waitcnt lgkmcnt(7)
	v_mfma_f32_16x16x32_bf16 v[62:65], v[130:133], v[176:179], v[62:65]
	v_mfma_f32_16x16x32_bf16 v[58:61], v[138:141], v[176:179], v[58:61]
	s_waitcnt lgkmcnt(5)
	v_mfma_f32_16x16x32_bf16 v[50:53], v[130:133], v[184:187], v[50:53]
	v_mfma_f32_16x16x32_bf16 v[44:47], v[138:141], v[184:187], v[44:47]
	s_waitcnt lgkmcnt(3)
	v_mfma_f32_16x16x32_bf16 v[32:35], v[130:133], v[192:195], v[32:35]
	v_mfma_f32_16x16x32_bf16 v[28:31], v[138:141], v[192:195], v[28:31]
	s_waitcnt lgkmcnt(1)
	v_mfma_f32_16x16x32_bf16 v[16:19], v[130:133], v[200:203], v[16:19]
	v_mfma_f32_16x16x32_bf16 v[12:15], v[138:141], v[200:203], v[12:15]
	v_mfma_f32_16x16x32_bf16 v[62:65], v[134:137], v[180:183], v[62:65]
	v_mfma_f32_16x16x32_bf16 v[58:61], v[142:145], v[180:183], v[58:61]
	v_mfma_f32_16x16x32_bf16 v[50:53], v[134:137], v[188:191], v[50:53]
	v_mfma_f32_16x16x32_bf16 v[44:47], v[142:145], v[188:191], v[44:47]
	v_mfma_f32_16x16x32_bf16 v[32:35], v[134:137], v[196:199], v[32:35]
	v_mfma_f32_16x16x32_bf16 v[28:31], v[142:145], v[196:199], v[28:31]
	s_waitcnt lgkmcnt(0)
	v_mfma_f32_16x16x32_bf16 v[16:19], v[134:137], v[204:207], v[16:19]
	v_mfma_f32_16x16x32_bf16 v[12:15], v[142:145], v[204:207], v[12:15]
	s_barrier
	s_add_i32 s20, s20, s35
	s_mov_b32 m0, s20
	v_lshl_add_u64 v[130:131], v[240:241], 0, s[0:1]
	global_load_lds_dwordx4 v[130:131], off
	s_add_i32 m0, s20, 0x2000
	v_lshl_add_u64 v[130:131], v[242:243], 0, s[0:1]
	global_load_lds_dwordx4 v[130:131], off
	s_waitcnt vmcnt(6)
	s_barrier
	v_mfma_f32_16x16x32_bf16 v[54:57], v[208:211], v[176:179], v[54:57]
	v_mfma_f32_16x16x32_bf16 v[40:43], v[216:219], v[176:179], v[40:43]
	v_mfma_f32_16x16x32_bf16 v[36:39], v[208:211], v[184:187], v[36:39]
	v_mfma_f32_16x16x32_bf16 v[24:27], v[216:219], v[184:187], v[24:27]
	v_mfma_f32_16x16x32_bf16 v[20:23], v[208:211], v[192:195], v[20:23]
	v_mfma_f32_16x16x32_bf16 v[8:11], v[216:219], v[192:195], v[8:11]
	v_mfma_f32_16x16x32_bf16 v[4:7], v[208:211], v[200:203], v[4:7]
	v_mfma_f32_16x16x32_bf16 v[0:3], v[216:219], v[200:203], v[0:3]
	v_mfma_f32_16x16x32_bf16 v[54:57], v[212:215], v[180:183], v[54:57]
	v_mfma_f32_16x16x32_bf16 v[40:43], v[234:237], v[180:183], v[40:43]
	v_mfma_f32_16x16x32_bf16 v[36:39], v[212:215], v[188:191], v[36:39]
	v_mfma_f32_16x16x32_bf16 v[24:27], v[234:237], v[188:191], v[24:27]
	v_mfma_f32_16x16x32_bf16 v[20:23], v[212:215], v[196:199], v[20:23]
	v_mfma_f32_16x16x32_bf16 v[8:11], v[234:237], v[196:199], v[8:11]
	v_mfma_f32_16x16x32_bf16 v[4:7], v[212:215], v[204:207], v[4:7]
	v_mfma_f32_16x16x32_bf16 v[0:3], v[234:237], v[204:207], v[0:3]
	s_add_u32 s16, s16, 0x100
	s_addc_u32 s17, s17, 0
	s_add_u32 s24, s24, 0x100
	s_addc_u32 s25, s25, 0
	s_cmp_ge_u32 s42, s54
	s_mov_b32 s20, s42
	s_barrier
	s_cbranch_scc0 .LBB0_268

; #define PG8_STAGE(bufoff, gbase, voff) do { _Pragma("unroll") for (int _i = 0; _i < 2; ++_i) \
;         __builtin_amdgcn_global_load_lds((const unsigned*)((const char*)(gbase) + (voff)[_i]), (PG8_LAS unsigned*)(lds + (bufoff) + ldsw + _i * 8192), 16, 0, 0); } while (0)
; #define PG8_LDA(dst, b, h) do { _Pragma("unroll") for (int m = 0; m < 4; ++m) _Pragma("unroll") for (int k = 0; k < 2; ++k) dst[m][k] = *(const PG8_LAS bf16x8*)(lds + PG8_SA(b, h) + aoff + m * 2048 + k * 1024); } while (0)
; #define PG8_LDB(dst, b, h) do { _Pragma("unroll") for (int n = 0; n < 2; ++n) _Pragma("unroll") for (int k = 0; k < 2; ++k) dst[n][k] = *(const PG8_LAS bf16x8*)(lds + PG8_SB(b, h) + boff + n * 2048 + k * 1024); } while (0)
; #define PG8_WAIT_L(n) asm volatile("s_waitcnt lgkmcnt(" #n ")" ::: "memory")
; #define PG8_BAR __builtin_amdgcn_s_barrier()
; #define PG8_SCHED __builtin_amdgcn_sched_barrier(0)
; template <class Epi, class Sched>
; __device__ __forceinline__ void gemm_phase(PG8_LAS unsigned char* lds, const Gemm g, const Sched& S, const Epi& E) {
;     ...
;         const bool has_next = S.next(ui + 1, nxt);
;         const char* nA = has_next ? (const char*)g.A + (size_t)nxt.pm * tstepA + (size_t)nxt.kc * cstep : cA; const char* nB = has_next ? (const char*)g.Bt + (size_t)nxt.pn * tstep + (size_t)nxt.kc * cstep : cB;
;         for (int t = 0; t < nt; t += 2) {
;             const bool last = (t == nt - 2);
;             const char* a1 = cA + (size_t)(t + 1) * kstep;
;             const char* a2 = last ? nA : cA + (size_t)(t + 2) * kstep; const char* b2 = last ? nB : cB + (size_t)(t + 2) * kstep;
;             const char* a3 = a2 + kstep; const char* b3 = b2 + kstep;
;             if (last && has_next) S.a_ready(nxt);
;             PG8_LDB(B0, 0, 0); PG8_SCHED; PG8_LDA(At, 0, 0); PG8_STAGE(PG8_SA(1, 1), a1 + hstep, voffA);
;             PG8_WAIT_L(8); PG8_BAR; PG8_WAIT_L(0); PG8_MMA(0, 0, At, B0); PG8_BAR; PG8_SCHED;
;             PG8_LDB(B1, 0, 1); PG8_STAGE(PG8_SB(0, 0), b2, voffB);
;             PG8_BAR; PG8_WAIT_L(0); PG8_MMA(0, 1, At, B1); PG8_BAR;
;             PG8_LDA(At, 0, 1); PG8_STAGE(PG8_SA(0, 0), a2, voffA);
;             PG8_BAR; PG8_WAIT_L(0); PG8_MMA(1, 0, At, B0); PG8_BAR; PG8_SCHED;
.LBB0_287:
	s_add_u32 s20, s20, 0x80
	s_addc_u32 s21, s21, 0
	s_add_u32 s3, s22, 0x100
	s_addc_u32 s40, s23, 0
	s_mov_b32 s22, 0
	s_add_i32 s41, s22, 2
	s_add_u32 s24, s20, 0x80
	s_addc_u32 s23, s21, 0
	s_add_i32 s63, 0, 0x10000
	v_add_u32_e32 v155, s63, v152
	ds_read_b128 v[156:159], v155
	ds_read_b128 v[160:163], v155 offset:1024
	ds_read_b128 v[164:167], v155 offset:2048
	ds_read_b128 v[168:171], v155 offset:3072
	s_cmp_eq_u32 s55, s22
	s_cselect_b32 s22, s12, s24
	s_cselect_b32 s23, s13, s23
	s_cselect_b32 s25, s17, s40
	s_cselect_b32 s24, s16, s3
	v_lshl_add_u64 v[172:173], s[20:21], 0, v[148:149]
	s_add_i32 m0, s43, 0xc000
	ds_read_b128 v[176:179], v154
	ds_read_b128 v[180:183], v154 offset:1024
	ds_read_b128 v[184:187], v154 offset:2048
	ds_read_b128 v[188:191], v154 offset:3072
	ds_read_b128 v[192:195], v154 offset:4096
	ds_read_b128 v[196:199], v154 offset:5120
	ds_read_b128 v[200:203], v154 offset:6144
	ds_read_b128 v[204:207], v154 offset:7168
	global_load_lds_dwordx4 v[172:173], off
	s_add_i32 m0, s43, 0xe000
	v_lshl_add_u64 v[172:173], s[20:21], 0, v[150:151]
	global_load_lds_dwordx4 v[172:173], off
	s_waitcnt lgkmcnt(8)
	s_barrier
	s_waitcnt lgkmcnt(7)
	v_mfma_f32_16x16x32_bf16 v[126:129], v[156:159], v[176:179], 0
	v_mfma_f32_16x16x32_bf16 v[122:125], v[164:167], v[176:179], 0
	s_waitcnt lgkmcnt(5)
	v_mfma_f32_16x16x32_bf16 v[118:121], v[156:159], v[184:187], 0
	v_mfma_f32_16x16x32_bf16 v[114:117], v[164:167], v[184:187], 0
	s_waitcnt lgkmcnt(3)
	v_mfma_f32_16x16x32_bf16 v[110:113], v[156:159], v[192:195], 0
	v_mfma_f32_16x16x32_bf16 v[106:109], v[164:167], v[192:195], 0
	s_waitcnt lgkmcnt(1)
	v_mfma_f32_16x16x32_bf16 v[98:101], v[156:159], v[200:203], 0
	v_mfma_f32_16x16x32_bf16 v[90:93], v[164:167], v[200:203], 0
	v_mfma_f32_16x16x32_bf16 v[126:129], v[160:163], v[180:183], v[126:129]
	v_mfma_f32_16x16x32_bf16 v[122:125], v[168:171], v[180:183], v[122:125]
	v_mfma_f32_16x16x32_bf16 v[118:121], v[160:163], v[188:191], v[118:121]
	v_mfma_f32_16x16x32_bf16 v[114:117], v[168:171], v[188:191], v[114:117]
	v_mfma_f32_16x16x32_bf16 v[110:113], v[160:163], v[196:199], v[110:113]
	v_mfma_f32_16x16x32_bf16 v[106:109], v[168:171], v[196:199], v[106:109]
	s_waitcnt lgkmcnt(0)
	v_mfma_f32_16x16x32_bf16 v[98:101], v[160:163], v[204:207], v[98:101]
	v_mfma_f32_16x16x32_bf16 v[90:93], v[168:171], v[204:207], v[90:93]
	s_barrier
	s_add_i32 s64, 0, 0x14000
	s_add_i32 s63, s63, s37
	v_add_u32_e32 v155, s64, v152
	v_lshl_add_u64 v[172:173], s[24:25], 0, v[48:49]
	s_mov_b32 m0, s63
	ds_read_b128 v[208:211], v155
	ds_read_b128 v[212:215], v155 offset:1024
	ds_read_b128 v[216:219], v155 offset:2048
	ds_read_b128 v[234:237], v155 offset:3072
	global_load_lds_dwordx4 v[172:173], off
	s_add_i32 m0, s63, 0x2000
	v_lshl_add_u64 v[224:225], s[24:25], 0, v[130:131]
	global_load_lds_dwordx4 v[224:225], off
	s_barrier
	s_waitcnt lgkmcnt(3)
	v_mfma_f32_16x16x32_bf16 v[102:105], v[208:211], v[176:179], 0
	s_waitcnt lgkmcnt(1)
	v_mfma_f32_16x16x32_bf16 v[94:97], v[216:219], v[176:179], 0
	v_mfma_f32_16x16x32_bf16 v[86:89], v[208:211], v[184:187], 0
	v_mfma_f32_16x16x32_bf16 v[82:85], v[216:219], v[184:187], 0
	v_mfma_f32_16x16x32_bf16 v[78:81], v[208:211], v[192:195], 0
	v_mfma_f32_16x16x32_bf16 v[74:77], v[216:219], v[192:195], 0
	v_mfma_f32_16x16x32_bf16 v[70:73], v[208:211], v[200:203], 0
	v_mfma_f32_16x16x32_bf16 v[66:69], v[216:219], v[200:203], 0
	v_mfma_f32_16x16x32_bf16 v[102:105], v[212:215], v[180:183], v[102:105]
	s_waitcnt lgkmcnt(0)
	v_mfma_f32_16x16x32_bf16 v[94:97], v[234:237], v[180:183], v[94:97]
	v_mfma_f32_16x16x32_bf16 v[86:89], v[212:215], v[188:191], v[86:89]
	v_mfma_f32_16x16x32_bf16 v[82:85], v[234:237], v[188:191], v[82:85]
	v_mfma_f32_16x16x32_bf16 v[78:81], v[212:215], v[196:199], v[78:81]
	v_mfma_f32_16x16x32_bf16 v[74:77], v[234:237], v[196:199], v[74:77]
	v_mfma_f32_16x16x32_bf16 v[70:73], v[212:215], v[204:207], v[70:73]
	v_mfma_f32_16x16x32_bf16 v[66:69], v[234:237], v[204:207], v[66:69]
	s_mov_b32 m0, s43
	v_lshl_add_u64 v[228:229], s[22:23], 0, v[48:49]
	s_barrier
	ds_read_b128 v[176:179], v154 offset:16384
	ds_read_b128 v[180:183], v154 offset:17408
	ds_read_b128 v[184:187], v154 offset:18432
	ds_read_b128 v[188:191], v154 offset:19456
	ds_read_b128 v[192:195], v154 offset:20480
	ds_read_b128 v[196:199], v154 offset:21504
	ds_read_b128 v[200:203], v154 offset:22528
	ds_read_b128 v[204:207], v154 offset:23552
	global_load_lds_dwordx4 v[228:229], off
	s_mov_b32 m0, s44
	v_lshl_add_u64 v[238:239], s[22:23], 0, v[130:131]
	global_load_lds_dwordx4 v[238:239], off
	s_barrier
	s_waitcnt lgkmcnt(7)
	v_mfma_f32_16x16x32_bf16 v[62:65], v[156:159], v[176:179], 0
	v_mfma_f32_16x16x32_bf16 v[58:61], v[164:167], v[176:179], 0
	s_waitcnt lgkmcnt(5)
	v_mfma_f32_16x16x32_bf16 v[54:57], v[156:159], v[184:187], 0
	v_mfma_f32_16x16x32_bf16 v[50:53], v[164:167], v[184:187], 0
	s_waitcnt lgkmcnt(3)
	v_mfma_f32_16x16x32_bf16 v[44:47], v[156:159], v[192:195], 0
	v_mfma_f32_16x16x32_bf16 v[40:43], v[164:167], v[192:195], 0
	s_waitcnt lgkmcnt(1)
	v_mfma_f32_16x16x32_bf16 v[32:35], v[156:159], v[200:203], 0
	v_mfma_f32_16x16x32_bf16 v[24:27], v[164:167], v[200:203], 0
	v_mfma_f32_16x16x32_bf16 v[62:65], v[160:163], v[180:183], v[62:65]
	v_mfma_f32_16x16x32_bf16 v[58:61], v[168:171], v[180:183], v[58:61]
	v_mfma_f32_16x16x32_bf16 v[54:57], v[160:163], v[188:191], v[54:57]
	v_mfma_f32_16x16x32_bf16 v[50:53], v[168:171], v[188:191], v[50:53]
	v_mfma_f32_16x16x32_bf16 v[44:47], v[160:163], v[196:199], v[44:47]
	v_mfma_f32_16x16x32_bf16 v[40:43], v[168:171], v[196:199], v[40:43]
	s_waitcnt lgkmcnt(0)
	v_mfma_f32_16x16x32_bf16 v[32:35], v[160:163], v[204:207], v[32:35]
	v_mfma_f32_16x16x32_bf16 v[24:27], v[168:171], v[204:207], v[24:27]
	s_barrier
; #define PG8_STAGE(bufoff, gbase, voff) do { _Pragma("unroll") for (int _i = 0; _i < 2; ++_i) \
;         __builtin_amdgcn_global_load_lds((const unsigned*)((const char*)(gbase) + (voff)[_i]), (PG8_LAS unsigned*)(lds + (bufoff) + ldsw + _i * 8192), 16, 0, 0); } while (0)
; #define PG8_LDA(dst, b, h) do { _Pragma("unroll") for (int m = 0; m < 4; ++m) _Pragma("unroll") for (int k = 0; k < 2; ++k) dst[m][k] = *(const PG8_LAS bf16x8*)(lds + PG8_SA(b, h) + aoff + m * 2048 + k * 1024); } while (0)
; #define PG8_LDB(dst, b, h) do { _Pragma("unroll") for (int n = 0; n < 2; ++n) _Pragma("unroll") for (int k = 0; k < 2; ++k) dst[n][k] = *(const PG8_LAS bf16x8*)(lds + PG8_SB(b, h) + boff + n * 2048 + k * 1024); } while (0)
; #define PG8_MMA(ai, bj, At, Bt) do { __builtin_amdgcn_s_setprio(1); _Pragma("unroll") for (int m = 0; m < 4; ++m) _Pragma("unroll") for (int n = 0; n < 2; ++n) _Pragma("unroll") for (int k = 0; k < 2; ++k) \
;         acc[ai][bj][m][n] = __builtin_amdgcn_mfma_f32_16x16x32_bf16(Bt[n][k], At[m][k], acc[ai][bj][m][n], 0, 0, 0); __builtin_amdgcn_s_setprio(0); } while (0)
; #define PG8_WAIT_V(n) asm volatile("s_waitcnt vmcnt(" #n ")" ::: "memory")
; #define PG8_WAIT_L(n) asm volatile("s_waitcnt lgkmcnt(" #n ")" ::: "memory")
; #define PG8_BAR __builtin_amdgcn_s_barrier()
; #define PG8_SCHED __builtin_amdgcn_sched_barrier(0)
; template <class Epi, class Sched>
; __device__ __forceinline__ void gemm_phase(PG8_LAS unsigned char* lds, const Gemm g, const Sched& S, const Epi& E) {
;     ...
;             PG8_STAGE(PG8_SB(0, 1), b2 + hstep, voffB);
;             PG8_WAIT_V(6); PG8_BAR; PG8_MMA(1, 1, At, B1); PG8_BAR;
;             PG8_LDB(B0, 1, 0); PG8_SCHED; PG8_LDA(At, 1, 0); PG8_STAGE(PG8_SA(0, 1), a2 + hstep, voffA);
;             PG8_WAIT_L(8); PG8_BAR; PG8_WAIT_L(0); PG8_MMA(0, 0, At, B0); PG8_BAR; PG8_SCHED;
;             PG8_LDB(B1, 1, 1); PG8_STAGE(PG8_SB(1, 0), b3, voffB);
;             PG8_BAR; PG8_WAIT_L(0); PG8_MMA(0, 1, At, B1); PG8_BAR;
;             PG8_LDA(At, 1, 1); PG8_STAGE(PG8_SA(1, 0), a3, voffA);
;             PG8_BAR; PG8_WAIT_L(0); PG8_MMA(1, 0, At, B0); PG8_BAR; PG8_SCHED;
	s_add_u32 s24, s24, s10
	s_addc_u32 s25, s25, 0
	s_add_i32 s63, s64, s37
	v_lshl_add_u64 v[240:241], s[24:25], 0, v[48:49]
	s_mov_b32 m0, s63
	v_lshl_add_u64 v[242:243], s[24:25], 0, v[130:131]
	global_load_lds_dwordx4 v[240:241], off
	s_add_i32 m0, s63, 0x2000
	s_nop 0
	global_load_lds_dwordx4 v[242:243], off
	s_waitcnt vmcnt(6)
	s_barrier
	v_mfma_f32_16x16x32_bf16 v[36:39], v[208:211], v[176:179], 0
	v_mfma_f32_16x16x32_bf16 v[28:31], v[216:219], v[176:179], 0
	v_mfma_f32_16x16x32_bf16 v[20:23], v[208:211], v[184:187], 0
	v_mfma_f32_16x16x32_bf16 v[16:19], v[216:219], v[184:187], 0
	v_mfma_f32_16x16x32_bf16 v[12:15], v[208:211], v[192:195], 0
	v_mfma_f32_16x16x32_bf16 v[8:11], v[216:219], v[192:195], 0
	v_mfma_f32_16x16x32_bf16 v[4:7], v[208:211], v[200:203], 0
	v_mfma_f32_16x16x32_bf16 v[0:3], v[216:219], v[200:203], 0
	v_mfma_f32_16x16x32_bf16 v[36:39], v[212:215], v[180:183], v[36:39]
	v_mfma_f32_16x16x32_bf16 v[28:31], v[234:237], v[180:183], v[28:31]
	v_mfma_f32_16x16x32_bf16 v[20:23], v[212:215], v[188:191], v[20:23]
	v_mfma_f32_16x16x32_bf16 v[16:19], v[234:237], v[188:191], v[16:19]
	v_mfma_f32_16x16x32_bf16 v[12:15], v[212:215], v[196:199], v[12:15]
	v_mfma_f32_16x16x32_bf16 v[8:11], v[234:237], v[196:199], v[8:11]
	v_mfma_f32_16x16x32_bf16 v[4:7], v[212:215], v[204:207], v[4:7]
	v_mfma_f32_16x16x32_bf16 v[0:3], v[234:237], v[204:207], v[0:3]
	s_add_i32 s24, 0, 0x18000
	v_add_u32_e32 v155, s24, v152
	s_barrier
	ds_read_b128 v[156:159], v155
	ds_read_b128 v[160:163], v155 offset:1024
	ds_read_b128 v[164:167], v155 offset:2048
	ds_read_b128 v[168:171], v155 offset:3072
	s_add_u32 s22, s22, s10
	s_addc_u32 s23, s23, 0
	s_mov_b32 m0, s46
	v_lshl_add_u64 v[208:209], s[22:23], 0, v[48:49]
	ds_read_b128 v[176:179], v154 offset:32768
	ds_read_b128 v[180:183], v154 offset:33792
	ds_read_b128 v[184:187], v154 offset:34816
	ds_read_b128 v[188:191], v154 offset:35840
	ds_read_b128 v[192:195], v154 offset:36864
	ds_read_b128 v[196:199], v154 offset:37888
	ds_read_b128 v[200:203], v154 offset:38912
	ds_read_b128 v[204:207], v154 offset:39936
	global_load_lds_dwordx4 v[208:209], off
	s_mov_b32 m0, s47
	v_lshl_add_u64 v[208:209], s[22:23], 0, v[130:131]
	global_load_lds_dwordx4 v[208:209], off
	s_waitcnt lgkmcnt(8)
	s_barrier
	s_waitcnt lgkmcnt(7)
	v_mfma_f32_16x16x32_bf16 v[126:129], v[156:159], v[176:179], v[126:129]
	v_mfma_f32_16x16x32_bf16 v[122:125], v[164:167], v[176:179], v[122:125]
	s_waitcnt lgkmcnt(5)
	v_mfma_f32_16x16x32_bf16 v[118:121], v[156:159], v[184:187], v[118:121]
	v_mfma_f32_16x16x32_bf16 v[114:117], v[164:167], v[184:187], v[114:117]
	s_waitcnt lgkmcnt(3)
	v_mfma_f32_16x16x32_bf16 v[110:113], v[156:159], v[192:195], v[110:113]
	v_mfma_f32_16x16x32_bf16 v[106:109], v[164:167], v[192:195], v[106:109]
	s_waitcnt lgkmcnt(1)
	v_mfma_f32_16x16x32_bf16 v[98:101], v[156:159], v[200:203], v[98:101]
	v_mfma_f32_16x16x32_bf16 v[90:93], v[164:167], v[200:203], v[90:93]
	v_mfma_f32_16x16x32_bf16 v[126:129], v[160:163], v[180:183], v[126:129]
	v_mfma_f32_16x16x32_bf16 v[122:125], v[168:171], v[180:183], v[122:125]
	v_mfma_f32_16x16x32_bf16 v[118:121], v[160:163], v[188:191], v[118:121]
	v_mfma_f32_16x16x32_bf16 v[114:117], v[168:171], v[188:191], v[114:117]
	v_mfma_f32_16x16x32_bf16 v[110:113], v[160:163], v[196:199], v[110:113]
	v_mfma_f32_16x16x32_bf16 v[106:109], v[168:171], v[196:199], v[106:109]
	s_waitcnt lgkmcnt(0)
	v_mfma_f32_16x16x32_bf16 v[98:101], v[160:163], v[204:207], v[98:101]
	v_mfma_f32_16x16x32_bf16 v[90:93], v[168:171], v[204:207], v[90:93]
	s_barrier
	s_add_i32 s22, 0, 0x1c000
	s_add_i32 s23, s24, s37
	v_add_u32_e32 v155, s22, v152
	v_lshl_add_u64 v[172:173], v[172:173], 0, s[0:1]
	s_mov_b32 m0, s23
	ds_read_b128 v[208:211], v155
	ds_read_b128 v[212:215], v155 offset:1024
	ds_read_b128 v[216:219], v155 offset:2048
	ds_read_b128 v[234:237], v155 offset:3072
	global_load_lds_dwordx4 v[172:173], off
	s_add_i32 m0, s23, 0x2000
	v_lshl_add_u64 v[172:173], v[224:225], 0, s[0:1]
	global_load_lds_dwordx4 v[172:173], off
	s_barrier
	s_waitcnt lgkmcnt(3)
	v_mfma_f32_16x16x32_bf16 v[102:105], v[208:211], v[176:179], v[102:105]
	s_waitcnt lgkmcnt(1)
	v_mfma_f32_16x16x32_bf16 v[94:97], v[216:219], v[176:179], v[94:97]
	v_mfma_f32_16x16x32_bf16 v[86:89], v[208:211], v[184:187], v[86:89]
	v_mfma_f32_16x16x32_bf16 v[82:85], v[216:219], v[184:187], v[82:85]
	v_mfma_f32_16x16x32_bf16 v[78:81], v[208:211], v[192:195], v[78:81]
	v_mfma_f32_16x16x32_bf16 v[74:77], v[216:219], v[192:195], v[74:77]
	v_mfma_f32_16x16x32_bf16 v[70:73], v[208:211], v[200:203], v[70:73]
	v_mfma_f32_16x16x32_bf16 v[66:69], v[216:219], v[200:203], v[66:69]
	v_mfma_f32_16x16x32_bf16 v[102:105], v[212:215], v[180:183], v[102:105]
	s_waitcnt lgkmcnt(0)
	v_mfma_f32_16x16x32_bf16 v[94:97], v[234:237], v[180:183], v[94:97]
	v_mfma_f32_16x16x32_bf16 v[86:89], v[212:215], v[188:191], v[86:89]
	v_mfma_f32_16x16x32_bf16 v[82:85], v[234:237], v[188:191], v[82:85]
	v_mfma_f32_16x16x32_bf16 v[78:81], v[212:215], v[196:199], v[78:81]
	v_mfma_f32_16x16x32_bf16 v[74:77], v[234:237], v[196:199], v[74:77]
	v_mfma_f32_16x16x32_bf16 v[70:73], v[212:215], v[204:207], v[70:73]
	v_mfma_f32_16x16x32_bf16 v[66:69], v[234:237], v[204:207], v[66:69]
	s_mov_b32 m0, s50
	v_lshl_add_u64 v[172:173], v[228:229], 0, s[0:1]
	s_barrier
	ds_read_b128 v[176:179], v154 offset:49152
	ds_read_b128 v[180:183], v154 offset:50176
	ds_read_b128 v[184:187], v154 offset:51200
	ds_read_b128 v[188:191], v154 offset:52224
	ds_read_b128 v[192:195], v154 offset:53248
	ds_read_b128 v[196:199], v154 offset:54272
	ds_read_b128 v[200:203], v154 offset:55296
	ds_read_b128 v[204:207], v154 offset:56320
	global_load_lds_dwordx4 v[172:173], off
	s_mov_b32 m0, s51
	v_lshl_add_u64 v[172:173], v[238:239], 0, s[0:1]
	global_load_lds_dwordx4 v[172:173], off
	s_barrier
; #define PG8_STAGE(bufoff, gbase, voff) do { _Pragma("unroll") for (int _i = 0; _i < 2; ++_i) \
;         __builtin_amdgcn_global_load_lds((const unsigned*)((const char*)(gbase) + (voff)[_i]), (PG8_LAS unsigned*)(lds + (bufoff) + ldsw + _i * 8192), 16, 0, 0); } while (0)
; #define PG8_LDA(dst, b, h) do { _Pragma("unroll") for (int m = 0; m < 4; ++m) _Pragma("unroll") for (int k = 0; k < 2; ++k) dst[m][k] = *(const PG8_LAS bf16x8*)(lds + PG8_SA(b, h) + aoff + m * 2048 + k * 1024); } while (0)
; #define PG8_LDB(dst, b, h) do { _Pragma("unroll") for (int n = 0; n < 2; ++n) _Pragma("unroll") for (int k = 0; k < 2; ++k) dst[n][k] = *(const PG8_LAS bf16x8*)(lds + PG8_SB(b, h) + boff + n * 2048 + k * 1024); } while (0)
; #define PG8_MMA(ai, bj, At, Bt) do { __builtin_amdgcn_s_setprio(1); _Pragma("unroll") for (int m = 0; m < 4; ++m) _Pragma("unroll") for (int n = 0; n < 2; ++n) _Pragma("unroll") for (int k = 0; k < 2; ++k) \
;         acc[ai][bj][m][n] = __builtin_amdgcn_mfma_f32_16x16x32_bf16(Bt[n][k], At[m][k], acc[ai][bj][m][n], 0, 0, 0); __builtin_amdgcn_s_setprio(0); } while (0)
; #define PG8_WAIT_V(n) asm volatile("s_waitcnt vmcnt(" #n ")" ::: "memory")
; #define PG8_WAIT_L(n) asm volatile("s_waitcnt lgkmcnt(" #n ")" ::: "memory")
; #define PG8_BAR __builtin_amdgcn_s_barrier()
; #define PG8_SCHED __builtin_amdgcn_sched_barrier(0)
; template <class Epi, class Sched>
; __device__ __forceinline__ void gemm_phase(PG8_LAS unsigned char* lds, const Gemm g, const Sched& S, const Epi& E) {
;     ...
;             const char* a1 = cA + (size_t)(t + 1) * kstep;
;             const char* a2 = last ? nA : cA + (size_t)(t + 2) * kstep; const char* b2 = last ? nB : cB + (size_t)(t + 2) * kstep;
;             const char* a3 = a2 + kstep; const char* b3 = b2 + kstep;
;             if (last && has_next) S.a_ready(nxt);
;             PG8_LDB(B0, 0, 0); PG8_SCHED; PG8_LDA(At, 0, 0); PG8_STAGE(PG8_SA(1, 1), a1 + hstep, voffA);
;             PG8_WAIT_L(8); PG8_BAR; PG8_WAIT_L(0); PG8_MMA(0, 0, At, B0); PG8_BAR; PG8_SCHED;
;     ...
;             PG8_BAR; PG8_WAIT_L(0); PG8_MMA(1, 0, At, B0); PG8_BAR; PG8_SCHED;
;             PG8_STAGE(PG8_SB(1, 1), b3 + hstep, voffB);
;             PG8_WAIT_V(6); PG8_BAR; PG8_MMA(1, 1, At, B1); PG8_BAR;
	s_waitcnt lgkmcnt(7)
	v_mfma_f32_16x16x32_bf16 v[62:65], v[156:159], v[176:179], v[62:65]
	v_mfma_f32_16x16x32_bf16 v[58:61], v[164:167], v[176:179], v[58:61]
	s_waitcnt lgkmcnt(5)
	v_mfma_f32_16x16x32_bf16 v[54:57], v[156:159], v[184:187], v[54:57]
	v_mfma_f32_16x16x32_bf16 v[50:53], v[164:167], v[184:187], v[50:53]
	s_waitcnt lgkmcnt(3)
	v_mfma_f32_16x16x32_bf16 v[44:47], v[156:159], v[192:195], v[44:47]
	v_mfma_f32_16x16x32_bf16 v[40:43], v[164:167], v[192:195], v[40:43]
	s_waitcnt lgkmcnt(1)
	v_mfma_f32_16x16x32_bf16 v[32:35], v[156:159], v[200:203], v[32:35]
	v_mfma_f32_16x16x32_bf16 v[24:27], v[164:167], v[200:203], v[24:27]
	v_mfma_f32_16x16x32_bf16 v[62:65], v[160:163], v[180:183], v[62:65]
	v_mfma_f32_16x16x32_bf16 v[58:61], v[168:171], v[180:183], v[58:61]
	v_mfma_f32_16x16x32_bf16 v[54:57], v[160:163], v[188:191], v[54:57]
	v_mfma_f32_16x16x32_bf16 v[50:53], v[168:171], v[188:191], v[50:53]
	v_mfma_f32_16x16x32_bf16 v[44:47], v[160:163], v[196:199], v[44:47]
	v_mfma_f32_16x16x32_bf16 v[40:43], v[168:171], v[196:199], v[40:43]
	s_waitcnt lgkmcnt(0)
	v_mfma_f32_16x16x32_bf16 v[32:35], v[160:163], v[204:207], v[32:35]
	v_mfma_f32_16x16x32_bf16 v[24:27], v[168:171], v[204:207], v[24:27]
	s_barrier
	s_add_i32 s22, s22, s37
	s_mov_b32 m0, s22
	v_lshl_add_u64 v[156:157], v[240:241], 0, s[0:1]
	global_load_lds_dwordx4 v[156:157], off
	s_add_i32 m0, s22, 0x2000
	v_lshl_add_u64 v[156:157], v[242:243], 0, s[0:1]
	global_load_lds_dwordx4 v[156:157], off
	s_waitcnt vmcnt(6)
	s_barrier
	v_mfma_f32_16x16x32_bf16 v[36:39], v[208:211], v[176:179], v[36:39]
	v_mfma_f32_16x16x32_bf16 v[28:31], v[216:219], v[176:179], v[28:31]
	v_mfma_f32_16x16x32_bf16 v[20:23], v[208:211], v[184:187], v[20:23]
	v_mfma_f32_16x16x32_bf16 v[16:19], v[216:219], v[184:187], v[16:19]
	v_mfma_f32_16x16x32_bf16 v[12:15], v[208:211], v[192:195], v[12:15]
	v_mfma_f32_16x16x32_bf16 v[8:11], v[216:219], v[192:195], v[8:11]
	v_mfma_f32_16x16x32_bf16 v[4:7], v[208:211], v[200:203], v[4:7]
	v_mfma_f32_16x16x32_bf16 v[0:3], v[216:219], v[200:203], v[0:3]
	v_mfma_f32_16x16x32_bf16 v[36:39], v[212:215], v[180:183], v[36:39]
	v_mfma_f32_16x16x32_bf16 v[28:31], v[234:237], v[180:183], v[28:31]
	v_mfma_f32_16x16x32_bf16 v[20:23], v[212:215], v[188:191], v[20:23]
	v_mfma_f32_16x16x32_bf16 v[16:19], v[234:237], v[188:191], v[16:19]
	v_mfma_f32_16x16x32_bf16 v[12:15], v[212:215], v[196:199], v[12:15]
	v_mfma_f32_16x16x32_bf16 v[8:11], v[234:237], v[196:199], v[8:11]
	v_mfma_f32_16x16x32_bf16 v[4:7], v[212:215], v[204:207], v[4:7]
	v_mfma_f32_16x16x32_bf16 v[0:3], v[234:237], v[204:207], v[0:3]
	s_add_u32 s20, s20, 0x100
	s_addc_u32 s21, s21, 0
	s_add_u32 s3, s3, 0x100
	s_addc_u32 s40, s40, 0
	s_cmp_ge_u32 s41, s54
	s_mov_b32 s22, s41
	s_barrier
	s_cbranch_scc1 .Lkpeel_exit_288
.LBB0_288:
	s_add_i32 s41, s22, 2
	s_add_u32 s24, s20, 0x80
	s_addc_u32 s23, s21, 0
	s_add_i32 s63, 0, 0x10000
	v_add_u32_e32 v155, s63, v152
	ds_read_b128 v[156:159], v155
	ds_read_b128 v[160:163], v155 offset:1024
	ds_read_b128 v[164:167], v155 offset:2048
	ds_read_b128 v[168:171], v155 offset:3072
	s_cmp_eq_u32 s55, s22
	s_cselect_b32 s22, s12, s24
	s_cselect_b32 s23, s13, s23
	s_cselect_b32 s25, s17, s40
	s_cselect_b32 s24, s16, s3
	v_lshl_add_u64 v[172:173], s[20:21], 0, v[148:149]
	s_add_i32 m0, s43, 0xc000
	ds_read_b128 v[176:179], v154
	ds_read_b128 v[180:183], v154 offset:1024
	ds_read_b128 v[184:187], v154 offset:2048
	ds_read_b128 v[188:191], v154 offset:3072
	ds_read_b128 v[192:195], v154 offset:4096
	ds_read_b128 v[196:199], v154 offset:5120
	ds_read_b128 v[200:203], v154 offset:6144
	ds_read_b128 v[204:207], v154 offset:7168
	global_load_lds_dwordx4 v[172:173], off
	s_add_i32 m0, s43, 0xe000
	v_lshl_add_u64 v[172:173], s[20:21], 0, v[150:151]
	global_load_lds_dwordx4 v[172:173], off
	s_waitcnt lgkmcnt(8)
	s_barrier
	s_waitcnt lgkmcnt(7)
	v_mfma_f32_16x16x32_bf16 v[126:129], v[156:159], v[176:179], v[126:129]
	v_mfma_f32_16x16x32_bf16 v[122:125], v[164:167], v[176:179], v[122:125]
	s_waitcnt lgkmcnt(5)
	v_mfma_f32_16x16x32_bf16 v[118:121], v[156:159], v[184:187], v[118:121]
	v_mfma_f32_16x16x32_bf16 v[114:117], v[164:167], v[184:187], v[114:117]
	s_waitcnt lgkmcnt(3)
	v_mfma_f32_16x16x32_bf16 v[110:113], v[156:159], v[192:195], v[110:113]
	v_mfma_f32_16x16x32_bf16 v[106:109], v[164:167], v[192:195], v[106:109]
	s_waitcnt lgkmcnt(1)
	v_mfma_f32_16x16x32_bf16 v[98:101], v[156:159], v[200:203], v[98:101]
	v_mfma_f32_16x16x32_bf16 v[90:93], v[164:167], v[200:203], v[90:93]
	v_mfma_f32_16x16x32_bf16 v[126:129], v[160:163], v[180:183], v[126:129]
	v_mfma_f32_16x16x32_bf16 v[122:125], v[168:171], v[180:183], v[122:125]
	v_mfma_f32_16x16x32_bf16 v[118:121], v[160:163], v[188:191], v[118:121]
	v_mfma_f32_16x16x32_bf16 v[114:117], v[168:171], v[188:191], v[114:117]
	v_mfma_f32_16x16x32_bf16 v[110:113], v[160:163], v[196:199], v[110:113]
	v_mfma_f32_16x16x32_bf16 v[106:109], v[168:171], v[196:199], v[106:109]
	s_waitcnt lgkmcnt(0)
	v_mfma_f32_16x16x32_bf16 v[98:101], v[160:163], v[204:207], v[98:101]
	v_mfma_f32_16x16x32_bf16 v[90:93], v[168:171], v[204:207], v[90:93]
	s_barrier
	s_add_i32 s64, 0, 0x14000
	s_add_i32 s63, s63, s37
	v_add_u32_e32 v155, s64, v152
	v_lshl_add_u64 v[172:173], s[24:25], 0, v[48:49]
	s_mov_b32 m0, s63
	ds_read_b128 v[208:211], v155
	ds_read_b128 v[212:215], v155 offset:1024
	ds_read_b128 v[216:219], v155 offset:2048
	ds_read_b128 v[234:237], v155 offset:3072
	global_load_lds_dwordx4 v[172:173], off
	s_add_i32 m0, s63, 0x2000
	v_lshl_add_u64 v[224:225], s[24:25], 0, v[130:131]
	global_load_lds_dwordx4 v[224:225], off
	s_barrier
; #define PG8_STAGE(bufoff, gbase, voff) do { _Pragma("unroll") for (int _i = 0; _i < 2; ++_i) \
;         __builtin_amdgcn_global_load_lds((const unsigned*)((const char*)(gbase) + (voff)[_i]), (PG8_LAS unsigned*)(lds + (bufoff) + ldsw + _i * 8192), 16, 0, 0); } while (0)
; #define PG8_LDA(dst, b, h) do { _Pragma("unroll") for (int m = 0; m < 4; ++m) _Pragma("unroll") for (int k = 0; k < 2; ++k) dst[m][k] = *(const PG8_LAS bf16x8*)(lds + PG8_SA(b, h) + aoff + m * 2048 + k * 1024); } while (0)
; #define PG8_LDB(dst, b, h) do { _Pragma("unroll") for (int n = 0; n < 2; ++n) _Pragma("unroll") for (int k = 0; k < 2; ++k) dst[n][k] = *(const PG8_LAS bf16x8*)(lds + PG8_SB(b, h) + boff + n * 2048 + k * 1024); } while (0)
; #define PG8_MMA(ai, bj, At, Bt) do { __builtin_amdgcn_s_setprio(1); _Pragma("unroll") for (int m = 0; m < 4; ++m) _Pragma("unroll") for (int n = 0; n < 2; ++n) _Pragma("unroll") for (int k = 0; k < 2; ++k) \
;         acc[ai][bj][m][n] = __builtin_amdgcn_mfma_f32_16x16x32_bf16(Bt[n][k], At[m][k], acc[ai][bj][m][n], 0, 0, 0); __builtin_amdgcn_s_setprio(0); } while (0)
; #define PG8_WAIT_V(n) asm volatile("s_waitcnt vmcnt(" #n ")" ::: "memory")
; #define PG8_WAIT_L(n) asm volatile("s_waitcnt lgkmcnt(" #n ")" ::: "memory")
; #define PG8_BAR __builtin_amdgcn_s_barrier()
; #define PG8_SCHED __builtin_amdgcn_sched_barrier(0)
; template <class Epi, class Sched>
; __device__ __forceinline__ void gemm_phase(PG8_LAS unsigned char* lds, const Gemm g, const Sched& S, const Epi& E) {
;     ...
;             PG8_BAR; PG8_WAIT_L(0); PG8_MMA(0, 1, At, B1); PG8_BAR;
;             PG8_LDA(At, 0, 1); PG8_STAGE(PG8_SA(0, 0), a2, voffA);
;             PG8_BAR; PG8_WAIT_L(0); PG8_MMA(1, 0, At, B0); PG8_BAR; PG8_SCHED;
;             PG8_STAGE(PG8_SB(0, 1), b2 + hstep, voffB);
;             PG8_WAIT_V(6); PG8_BAR; PG8_MMA(1, 1, At, B1); PG8_BAR;
;             PG8_LDB(B0, 1, 0); PG8_SCHED; PG8_LDA(At, 1, 0); PG8_STAGE(PG8_SA(0, 1), a2 + hstep, voffA);
;             PG8_WAIT_L(8); PG8_BAR; PG8_WAIT_L(0); PG8_MMA(0, 0, At, B0); PG8_BAR; PG8_SCHED;
	s_waitcnt lgkmcnt(3)
	v_mfma_f32_16x16x32_bf16 v[102:105], v[208:211], v[176:179], v[102:105]
	s_waitcnt lgkmcnt(1)
	v_mfma_f32_16x16x32_bf16 v[94:97], v[216:219], v[176:179], v[94:97]
	v_mfma_f32_16x16x32_bf16 v[86:89], v[208:211], v[184:187], v[86:89]
	v_mfma_f32_16x16x32_bf16 v[82:85], v[216:219], v[184:187], v[82:85]
	v_mfma_f32_16x16x32_bf16 v[78:81], v[208:211], v[192:195], v[78:81]
	v_mfma_f32_16x16x32_bf16 v[74:77], v[216:219], v[192:195], v[74:77]
	v_mfma_f32_16x16x32_bf16 v[70:73], v[208:211], v[200:203], v[70:73]
	v_mfma_f32_16x16x32_bf16 v[66:69], v[216:219], v[200:203], v[66:69]
	v_mfma_f32_16x16x32_bf16 v[102:105], v[212:215], v[180:183], v[102:105]
	s_waitcnt lgkmcnt(0)
	v_mfma_f32_16x16x32_bf16 v[94:97], v[234:237], v[180:183], v[94:97]
	v_mfma_f32_16x16x32_bf16 v[86:89], v[212:215], v[188:191], v[86:89]
	v_mfma_f32_16x16x32_bf16 v[82:85], v[234:237], v[188:191], v[82:85]
	v_mfma_f32_16x16x32_bf16 v[78:81], v[212:215], v[196:199], v[78:81]
	v_mfma_f32_16x16x32_bf16 v[74:77], v[234:237], v[196:199], v[74:77]
	v_mfma_f32_16x16x32_bf16 v[70:73], v[212:215], v[204:207], v[70:73]
	v_mfma_f32_16x16x32_bf16 v[66:69], v[234:237], v[204:207], v[66:69]
	s_mov_b32 m0, s43
	v_lshl_add_u64 v[228:229], s[22:23], 0, v[48:49]
	s_barrier
	ds_read_b128 v[176:179], v154 offset:16384
	ds_read_b128 v[180:183], v154 offset:17408
	ds_read_b128 v[184:187], v154 offset:18432
	ds_read_b128 v[188:191], v154 offset:19456
	ds_read_b128 v[192:195], v154 offset:20480
	ds_read_b128 v[196:199], v154 offset:21504
	ds_read_b128 v[200:203], v154 offset:22528
	ds_read_b128 v[204:207], v154 offset:23552
	global_load_lds_dwordx4 v[228:229], off
	s_mov_b32 m0, s44
	v_lshl_add_u64 v[238:239], s[22:23], 0, v[130:131]
	global_load_lds_dwordx4 v[238:239], off
	s_barrier
	s_waitcnt lgkmcnt(7)
	v_mfma_f32_16x16x32_bf16 v[62:65], v[156:159], v[176:179], v[62:65]
	v_mfma_f32_16x16x32_bf16 v[58:61], v[164:167], v[176:179], v[58:61]
	s_waitcnt lgkmcnt(5)
	v_mfma_f32_16x16x32_bf16 v[54:57], v[156:159], v[184:187], v[54:57]
	v_mfma_f32_16x16x32_bf16 v[50:53], v[164:167], v[184:187], v[50:53]
	s_waitcnt lgkmcnt(3)
	v_mfma_f32_16x16x32_bf16 v[44:47], v[156:159], v[192:195], v[44:47]
	v_mfma_f32_16x16x32_bf16 v[40:43], v[164:167], v[192:195], v[40:43]
	s_waitcnt lgkmcnt(1)
	v_mfma_f32_16x16x32_bf16 v[32:35], v[156:159], v[200:203], v[32:35]
	v_mfma_f32_16x16x32_bf16 v[24:27], v[164:167], v[200:203], v[24:27]
	v_mfma_f32_16x16x32_bf16 v[62:65], v[160:163], v[180:183], v[62:65]
	v_mfma_f32_16x16x32_bf16 v[58:61], v[168:171], v[180:183], v[58:61]
	v_mfma_f32_16x16x32_bf16 v[54:57], v[160:163], v[188:191], v[54:57]
	v_mfma_f32_16x16x32_bf16 v[50:53], v[168:171], v[188:191], v[50:53]
	v_mfma_f32_16x16x32_bf16 v[44:47], v[160:163], v[196:199], v[44:47]
	v_mfma_f32_16x16x32_bf16 v[40:43], v[168:171], v[196:199], v[40:43]
	s_waitcnt lgkmcnt(0)
	v_mfma_f32_16x16x32_bf16 v[32:35], v[160:163], v[204:207], v[32:35]
	v_mfma_f32_16x16x32_bf16 v[24:27], v[168:171], v[204:207], v[24:27]
	s_barrier
	s_add_u32 s24, s24, s10
	s_addc_u32 s25, s25, 0
	s_add_i32 s63, s64, s37
	v_lshl_add_u64 v[240:241], s[24:25], 0, v[48:49]
	s_mov_b32 m0, s63
	v_lshl_add_u64 v[242:243], s[24:25], 0, v[130:131]
	global_load_lds_dwordx4 v[240:241], off
	s_add_i32 m0, s63, 0x2000
	s_nop 0
	global_load_lds_dwordx4 v[242:243], off
	s_waitcnt vmcnt(6)
	s_barrier
	v_mfma_f32_16x16x32_bf16 v[36:39], v[208:211], v[176:179], v[36:39]
	v_mfma_f32_16x16x32_bf16 v[28:31], v[216:219], v[176:179], v[28:31]
	v_mfma_f32_16x16x32_bf16 v[20:23], v[208:211], v[184:187], v[20:23]
	v_mfma_f32_16x16x32_bf16 v[16:19], v[216:219], v[184:187], v[16:19]
	v_mfma_f32_16x16x32_bf16 v[12:15], v[208:211], v[192:195], v[12:15]
	v_mfma_f32_16x16x32_bf16 v[8:11], v[216:219], v[192:195], v[8:11]
	v_mfma_f32_16x16x32_bf16 v[4:7], v[208:211], v[200:203], v[4:7]
	v_mfma_f32_16x16x32_bf16 v[0:3], v[216:219], v[200:203], v[0:3]
	v_mfma_f32_16x16x32_bf16 v[36:39], v[212:215], v[180:183], v[36:39]
	v_mfma_f32_16x16x32_bf16 v[28:31], v[234:237], v[180:183], v[28:31]
	v_mfma_f32_16x16x32_bf16 v[20:23], v[212:215], v[188:191], v[20:23]
	v_mfma_f32_16x16x32_bf16 v[16:19], v[234:237], v[188:191], v[16:19]
	v_mfma_f32_16x16x32_bf16 v[12:15], v[212:215], v[196:199], v[12:15]
	v_mfma_f32_16x16x32_bf16 v[8:11], v[234:237], v[196:199], v[8:11]
	v_mfma_f32_16x16x32_bf16 v[4:7], v[212:215], v[204:207], v[4:7]
	v_mfma_f32_16x16x32_bf16 v[0:3], v[234:237], v[204:207], v[0:3]
	s_add_i32 s24, 0, 0x18000
	v_add_u32_e32 v155, s24, v152
	s_barrier
	ds_read_b128 v[156:159], v155
	ds_read_b128 v[160:163], v155 offset:1024
	ds_read_b128 v[164:167], v155 offset:2048
	ds_read_b128 v[168:171], v155 offset:3072
	s_add_u32 s22, s22, s10
	s_addc_u32 s23, s23, 0
	s_mov_b32 m0, s46
	v_lshl_add_u64 v[208:209], s[22:23], 0, v[48:49]
	ds_read_b128 v[176:179], v154 offset:32768
	ds_read_b128 v[180:183], v154 offset:33792
	ds_read_b128 v[184:187], v154 offset:34816
	ds_read_b128 v[188:191], v154 offset:35840
	ds_read_b128 v[192:195], v154 offset:36864
	ds_read_b128 v[196:199], v154 offset:37888
	ds_read_b128 v[200:203], v154 offset:38912
	ds_read_b128 v[204:207], v154 offset:39936
	global_load_lds_dwordx4 v[208:209], off
	s_mov_b32 m0, s47
	v_lshl_add_u64 v[208:209], s[22:23], 0, v[130:131]
	global_load_lds_dwordx4 v[208:209], off
	s_waitcnt lgkmcnt(8)
	s_barrier
; #define PG8_STAGE(bufoff, gbase, voff) do { _Pragma("unroll") for (int _i = 0; _i < 2; ++_i) \
;         __builtin_amdgcn_global_load_lds((const unsigned*)((const char*)(gbase) + (voff)[_i]), (PG8_LAS unsigned*)(lds + (bufoff) + ldsw + _i * 8192), 16, 0, 0); } while (0)
; #define PG8_LDA(dst, b, h) do { _Pragma("unroll") for (int m = 0; m < 4; ++m) _Pragma("unroll") for (int k = 0; k < 2; ++k) dst[m][k] = *(const PG8_LAS bf16x8*)(lds + PG8_SA(b, h) + aoff + m * 2048 + k * 1024); } while (0)
; #define PG8_LDB(dst, b, h) do { _Pragma("unroll") for (int n = 0; n < 2; ++n) _Pragma("unroll") for (int k = 0; k < 2; ++k) dst[n][k] = *(const PG8_LAS bf16x8*)(lds + PG8_SB(b, h) + boff + n * 2048 + k * 1024); } while (0)
; #define PG8_MMA(ai, bj, At, Bt) do { __builtin_amdgcn_s_setprio(1); _Pragma("unroll") for (int m = 0; m < 4; ++m) _Pragma("unroll") for (int n = 0; n < 2; ++n) _Pragma("unroll") for (int k = 0; k < 2; ++k) \
;         acc[ai][bj][m][n] = __builtin_amdgcn_mfma_f32_16x16x32_bf16(Bt[n][k], At[m][k], acc[ai][bj][m][n], 0, 0, 0); __builtin_amdgcn_s_setprio(0); } while (0)
; #define PG8_WAIT_V(n) asm volatile("s_waitcnt vmcnt(" #n ")" ::: "memory")
; #define PG8_WAIT_L(n) asm volatile("s_waitcnt lgkmcnt(" #n ")" ::: "memory")
; #define PG8_BAR __builtin_amdgcn_s_barrier()
; #define PG8_SCHED __builtin_amdgcn_sched_barrier(0)
; template <class Epi, class Sched>
; __device__ __forceinline__ void gemm_phase(PG8_LAS unsigned char* lds, const Gemm g, const Sched& S, const Epi& E) {
;     ...
;             PG8_WAIT_L(8); PG8_BAR; PG8_WAIT_L(0); PG8_MMA(0, 0, At, B0); PG8_BAR; PG8_SCHED;
;             PG8_LDB(B1, 1, 1); PG8_STAGE(PG8_SB(1, 0), b3, voffB);
;             PG8_BAR; PG8_WAIT_L(0); PG8_MMA(0, 1, At, B1); PG8_BAR;
;             PG8_LDA(At, 1, 1); PG8_STAGE(PG8_SA(1, 0), a3, voffA);
;             PG8_BAR; PG8_WAIT_L(0); PG8_MMA(1, 0, At, B0); PG8_BAR; PG8_SCHED;
;             PG8_STAGE(PG8_SB(1, 1), b3 + hstep, voffB);
;             PG8_WAIT_V(6); PG8_BAR; PG8_MMA(1, 1, At, B1); PG8_BAR;
;         }
	s_waitcnt lgkmcnt(7)
	v_mfma_f32_16x16x32_bf16 v[126:129], v[156:159], v[176:179], v[126:129]
	v_mfma_f32_16x16x32_bf16 v[122:125], v[164:167], v[176:179], v[122:125]
	s_waitcnt lgkmcnt(5)
	v_mfma_f32_16x16x32_bf16 v[118:121], v[156:159], v[184:187], v[118:121]
	v_mfma_f32_16x16x32_bf16 v[114:117], v[164:167], v[184:187], v[114:117]
	s_waitcnt lgkmcnt(3)
	v_mfma_f32_16x16x32_bf16 v[110:113], v[156:159], v[192:195], v[110:113]
	v_mfma_f32_16x16x32_bf16 v[106:109], v[164:167], v[192:195], v[106:109]
	s_waitcnt lgkmcnt(1)
	v_mfma_f32_16x16x32_bf16 v[98:101], v[156:159], v[200:203], v[98:101]
	v_mfma_f32_16x16x32_bf16 v[90:93], v[164:167], v[200:203], v[90:93]
	v_mfma_f32_16x16x32_bf16 v[126:129], v[160:163], v[180:183], v[126:129]
	v_mfma_f32_16x16x32_bf16 v[122:125], v[168:171], v[180:183], v[122:125]
	v_mfma_f32_16x16x32_bf16 v[118:121], v[160:163], v[188:191], v[118:121]
	v_mfma_f32_16x16x32_bf16 v[114:117], v[168:171], v[188:191], v[114:117]
	v_mfma_f32_16x16x32_bf16 v[110:113], v[160:163], v[196:199], v[110:113]
	v_mfma_f32_16x16x32_bf16 v[106:109], v[168:171], v[196:199], v[106:109]
	s_waitcnt lgkmcnt(0)
	v_mfma_f32_16x16x32_bf16 v[98:101], v[160:163], v[204:207], v[98:101]
	v_mfma_f32_16x16x32_bf16 v[90:93], v[168:171], v[204:207], v[90:93]
	s_barrier
	s_add_i32 s22, 0, 0x1c000
	s_add_i32 s23, s24, s37
	v_add_u32_e32 v155, s22, v152
	v_lshl_add_u64 v[172:173], v[172:173], 0, s[0:1]
	s_mov_b32 m0, s23
	ds_read_b128 v[208:211], v155
	ds_read_b128 v[212:215], v155 offset:1024
	ds_read_b128 v[216:219], v155 offset:2048
	ds_read_b128 v[234:237], v155 offset:3072
	global_load_lds_dwordx4 v[172:173], off
	s_add_i32 m0, s23, 0x2000
	v_lshl_add_u64 v[172:173], v[224:225], 0, s[0:1]
	global_load_lds_dwordx4 v[172:173], off
	s_barrier
	s_waitcnt lgkmcnt(3)
	v_mfma_f32_16x16x32_bf16 v[102:105], v[208:211], v[176:179], v[102:105]
	s_waitcnt lgkmcnt(1)
	v_mfma_f32_16x16x32_bf16 v[94:97], v[216:219], v[176:179], v[94:97]
	v_mfma_f32_16x16x32_bf16 v[86:89], v[208:211], v[184:187], v[86:89]
	v_mfma_f32_16x16x32_bf16 v[82:85], v[216:219], v[184:187], v[82:85]
	v_mfma_f32_16x16x32_bf16 v[78:81], v[208:211], v[192:195], v[78:81]
	v_mfma_f32_16x16x32_bf16 v[74:77], v[216:219], v[192:195], v[74:77]
	v_mfma_f32_16x16x32_bf16 v[70:73], v[208:211], v[200:203], v[70:73]
	v_mfma_f32_16x16x32_bf16 v[66:69], v[216:219], v[200:203], v[66:69]
	v_mfma_f32_16x16x32_bf16 v[102:105], v[212:215], v[180:183], v[102:105]
	s_waitcnt lgkmcnt(0)
	v_mfma_f32_16x16x32_bf16 v[94:97], v[234:237], v[180:183], v[94:97]
	v_mfma_f32_16x16x32_bf16 v[86:89], v[212:215], v[188:191], v[86:89]
	v_mfma_f32_16x16x32_bf16 v[82:85], v[234:237], v[188:191], v[82:85]
	v_mfma_f32_16x16x32_bf16 v[78:81], v[212:215], v[196:199], v[78:81]
	v_mfma_f32_16x16x32_bf16 v[74:77], v[234:237], v[196:199], v[74:77]
	v_mfma_f32_16x16x32_bf16 v[70:73], v[212:215], v[204:207], v[70:73]
	v_mfma_f32_16x16x32_bf16 v[66:69], v[234:237], v[204:207], v[66:69]
	s_mov_b32 m0, s50
	v_lshl_add_u64 v[172:173], v[228:229], 0, s[0:1]
	s_barrier
	ds_read_b128 v[176:179], v154 offset:49152
	ds_read_b128 v[180:183], v154 offset:50176
	ds_read_b128 v[184:187], v154 offset:51200
	ds_read_b128 v[188:191], v154 offset:52224
	ds_read_b128 v[192:195], v154 offset:53248
	ds_read_b128 v[196:199], v154 offset:54272
	ds_read_b128 v[200:203], v154 offset:55296
	ds_read_b128 v[204:207], v154 offset:56320
	global_load_lds_dwordx4 v[172:173], off
	s_mov_b32 m0, s51
	v_lshl_add_u64 v[172:173], v[238:239], 0, s[0:1]
	global_load_lds_dwordx4 v[172:173], off
	s_barrier
	s_waitcnt lgkmcnt(7)
	v_mfma_f32_16x16x32_bf16 v[62:65], v[156:159], v[176:179], v[62:65]
	v_mfma_f32_16x16x32_bf16 v[58:61], v[164:167], v[176:179], v[58:61]
	s_waitcnt lgkmcnt(5)
	v_mfma_f32_16x16x32_bf16 v[54:57], v[156:159], v[184:187], v[54:57]
	v_mfma_f32_16x16x32_bf16 v[50:53], v[164:167], v[184:187], v[50:53]
	s_waitcnt lgkmcnt(3)
	v_mfma_f32_16x16x32_bf16 v[44:47], v[156:159], v[192:195], v[44:47]
	v_mfma_f32_16x16x32_bf16 v[40:43], v[164:167], v[192:195], v[40:43]
	s_waitcnt lgkmcnt(1)
	v_mfma_f32_16x16x32_bf16 v[32:35], v[156:159], v[200:203], v[32:35]
	v_mfma_f32_16x16x32_bf16 v[24:27], v[164:167], v[200:203], v[24:27]
	v_mfma_f32_16x16x32_bf16 v[62:65], v[160:163], v[180:183], v[62:65]
	v_mfma_f32_16x16x32_bf16 v[58:61], v[168:171], v[180:183], v[58:61]
	v_mfma_f32_16x16x32_bf16 v[54:57], v[160:163], v[188:191], v[54:57]
	v_mfma_f32_16x16x32_bf16 v[50:53], v[168:171], v[188:191], v[50:53]
	v_mfma_f32_16x16x32_bf16 v[44:47], v[160:163], v[196:199], v[44:47]
	v_mfma_f32_16x16x32_bf16 v[40:43], v[168:171], v[196:199], v[40:43]
	s_waitcnt lgkmcnt(0)
	v_mfma_f32_16x16x32_bf16 v[32:35], v[160:163], v[204:207], v[32:35]
	v_mfma_f32_16x16x32_bf16 v[24:27], v[168:171], v[204:207], v[24:27]
	s_barrier
	s_add_i32 s22, s22, s37
	s_mov_b32 m0, s22
	v_lshl_add_u64 v[156:157], v[240:241], 0, s[0:1]
	global_load_lds_dwordx4 v[156:157], off
	s_add_i32 m0, s22, 0x2000
	v_lshl_add_u64 v[156:157], v[242:243], 0, s[0:1]
	global_load_lds_dwordx4 v[156:157], off
	s_waitcnt vmcnt(6)
	s_barrier
	v_mfma_f32_16x16x32_bf16 v[36:39], v[208:211], v[176:179], v[36:39]
	v_mfma_f32_16x16x32_bf16 v[28:31], v[216:219], v[176:179], v[28:31]
	v_mfma_f32_16x16x32_bf16 v[20:23], v[208:211], v[184:187], v[20:23]
	v_mfma_f32_16x16x32_bf16 v[16:19], v[216:219], v[184:187], v[16:19]
	v_mfma_f32_16x16x32_bf16 v[12:15], v[208:211], v[192:195], v[12:15]
	v_mfma_f32_16x16x32_bf16 v[8:11], v[216:219], v[192:195], v[8:11]
	v_mfma_f32_16x16x32_bf16 v[4:7], v[208:211], v[200:203], v[4:7]
	v_mfma_f32_16x16x32_bf16 v[0:3], v[216:219], v[200:203], v[0:3]
	v_mfma_f32_16x16x32_bf16 v[36:39], v[212:215], v[180:183], v[36:39]
	v_mfma_f32_16x16x32_bf16 v[28:31], v[234:237], v[180:183], v[28:31]
	v_mfma_f32_16x16x32_bf16 v[20:23], v[212:215], v[188:191], v[20:23]
	v_mfma_f32_16x16x32_bf16 v[16:19], v[234:237], v[188:191], v[16:19]
	v_mfma_f32_16x16x32_bf16 v[12:15], v[212:215], v[196:199], v[12:15]
	v_mfma_f32_16x16x32_bf16 v[8:11], v[234:237], v[196:199], v[8:11]
	v_mfma_f32_16x16x32_bf16 v[4:7], v[212:215], v[204:207], v[4:7]
	v_mfma_f32_16x16x32_bf16 v[0:3], v[234:237], v[204:207], v[0:3]
	s_add_u32 s20, s20, 0x100
	s_addc_u32 s21, s21, 0
	s_add_u32 s3, s3, 0x100
	s_addc_u32 s40, s40, 0
	s_cmp_ge_u32 s41, s54
	s_mov_b32 s22, s41
	s_barrier
	s_cbranch_scc0 .LBB0_288

; #define PG8_STAGE(bufoff, gbase, voff) do { _Pragma("unroll") for (int _i = 0; _i < 2; ++_i) \
;         __builtin_amdgcn_global_load_lds((const unsigned*)((const char*)(gbase) + (voff)[_i]), (PG8_LAS unsigned*)(lds + (bufoff) + ldsw + _i * 8192), 16, 0, 0); } while (0)
; #define PG8_LDA(dst, b, h) do { _Pragma("unroll") for (int m = 0; m < 4; ++m) _Pragma("unroll") for (int k = 0; k < 2; ++k) dst[m][k] = *(const PG8_LAS bf16x8*)(lds + PG8_SA(b, h) + aoff + m * 2048 + k * 1024); } while (0)
; #define PG8_LDB(dst, b, h) do { _Pragma("unroll") for (int n = 0; n < 2; ++n) _Pragma("unroll") for (int k = 0; k < 2; ++k) dst[n][k] = *(const PG8_LAS bf16x8*)(lds + PG8_SB(b, h) + boff + n * 2048 + k * 1024); } while (0)
; #define PG8_WAIT_L(n) asm volatile("s_waitcnt lgkmcnt(" #n ")" ::: "memory")
; #define PG8_BAR __builtin_amdgcn_s_barrier()
; #define PG8_SCHED __builtin_amdgcn_sched_barrier(0)
; template <class Epi, class Sched>
; __device__ __forceinline__ void gemm_phase(PG8_LAS unsigned char* lds, const Gemm g, const Sched& S, const Epi& E) {
;     ...
;         const bool has_next = S.next(ui + 1, nxt);
;         const char* nA = has_next ? (const char*)g.A + (size_t)nxt.pm * tstepA + (size_t)nxt.kc * cstep : cA; const char* nB = has_next ? (const char*)g.Bt + (size_t)nxt.pn * tstep + (size_t)nxt.kc * cstep : cB;
;         for (int t = 0; t < nt; t += 2) {
;             const bool last = (t == nt - 2);
;             const char* a1 = cA + (size_t)(t + 1) * kstep;
;             const char* a2 = last ? nA : cA + (size_t)(t + 2) * kstep; const char* b2 = last ? nB : cB + (size_t)(t + 2) * kstep;
;             const char* a3 = a2 + kstep; const char* b3 = b2 + kstep;
;             if (last && has_next) S.a_ready(nxt);
;             PG8_LDB(B0, 0, 0); PG8_SCHED; PG8_LDA(At, 0, 0); PG8_STAGE(PG8_SA(1, 1), a1 + hstep, voffA);
;             PG8_WAIT_L(8); PG8_BAR; PG8_WAIT_L(0); PG8_MMA(0, 0, At, B0); PG8_BAR; PG8_SCHED;
;             PG8_LDB(B1, 0, 1); PG8_STAGE(PG8_SB(0, 0), b2, voffB);
;             PG8_BAR; PG8_WAIT_L(0); PG8_MMA(0, 1, At, B1); PG8_BAR;
;             PG8_LDA(At, 0, 1); PG8_STAGE(PG8_SA(0, 0), a2, voffA);
;             PG8_BAR; PG8_WAIT_L(0); PG8_MMA(1, 0, At, B0); PG8_BAR; PG8_SCHED;
.LBB0_319:
	v_mov_b64_e32 v[0:1], s[56:57]
	s_ashr_i32 s25, s24, 31
	v_cmp_lt_i64_e32 vcc, s[26:27], v[0:1]
	s_lshl_b64 s[26:27], s[24:25], 19
	s_add_u32 s26, s8, s26
	s_addc_u32 s27, s9, s27
	s_and_b64 s[28:29], vcc, exec
	s_cselect_b32 s25, s27, s31
	s_cselect_b32 s56, s26, s30
	s_ashr_i32 s23, s22, 31
	s_lshl_b64 s[28:29], s[22:23], 19
	s_add_u32 s28, s6, s28
	s_addc_u32 s29, s7, s29
	s_and_b64 s[36:37], vcc, exec
	s_cselect_b32 s23, s29, s35
	s_cselect_b32 s57, s28, s34
	s_add_u32 s30, s30, 0x40080
	s_addc_u32 s31, s31, 0
	s_add_u32 s59, s34, 0x100
	s_addc_u32 s63, s35, 0
	s_mov_b32 s64, -2
	s_add_u32 s34, s30, 0xfffc0080
	s_addc_u32 s35, s31, -1
	s_add_i32 s65, 0, 0x10000
	v_add_u32_e32 v140, s65, v143
	ds_read_b128 v[146:149], v140
	ds_read_b128 v[150:153], v140 offset:1024
	ds_read_b128 v[154:157], v140 offset:2048
	ds_read_b128 v[158:161], v140 offset:3072
	s_cmp_eq_u32 s64, 12
	s_cselect_b32 s37, s25, s35
	s_cselect_b32 s36, s56, s34
	s_cselect_b32 s35, s23, s63
	s_cselect_b32 s34, s57, s59
	v_lshl_add_u64 v[140:141], s[30:31], 0, v[136:137]
	s_add_i32 m0, s21, 0xc000
	ds_read_b128 v[162:165], v145
	ds_read_b128 v[166:169], v145 offset:1024
	ds_read_b128 v[170:173], v145 offset:2048
	ds_read_b128 v[176:179], v145 offset:3072
	ds_read_b128 v[180:183], v145 offset:4096
	ds_read_b128 v[184:187], v145 offset:5120
	ds_read_b128 v[188:191], v145 offset:6144
	ds_read_b128 v[192:195], v145 offset:7168
	global_load_lds_dwordx4 v[140:141], off
	s_add_i32 m0, s21, 0xe000
	v_lshl_add_u64 v[140:141], s[30:31], 0, v[138:139]
	global_load_lds_dwordx4 v[140:141], off
	s_waitcnt lgkmcnt(8)
	s_barrier
	s_waitcnt lgkmcnt(7)
	v_mfma_f32_16x16x32_bf16 v[126:129], v[146:149], v[162:165], 0
	v_mfma_f32_16x16x32_bf16 v[122:125], v[154:157], v[162:165], 0
	s_waitcnt lgkmcnt(5)
	v_mfma_f32_16x16x32_bf16 v[118:121], v[146:149], v[170:173], 0
	v_mfma_f32_16x16x32_bf16 v[110:113], v[154:157], v[170:173], 0
	s_waitcnt lgkmcnt(3)
	v_mfma_f32_16x16x32_bf16 v[102:105], v[146:149], v[180:183], 0
	v_mfma_f32_16x16x32_bf16 v[94:97], v[154:157], v[180:183], 0
	s_waitcnt lgkmcnt(1)
	v_mfma_f32_16x16x32_bf16 v[86:89], v[146:149], v[188:191], 0
	v_mfma_f32_16x16x32_bf16 v[78:81], v[154:157], v[188:191], 0
	v_mfma_f32_16x16x32_bf16 v[126:129], v[150:153], v[166:169], v[126:129]
	v_mfma_f32_16x16x32_bf16 v[122:125], v[158:161], v[166:169], v[122:125]
	v_mfma_f32_16x16x32_bf16 v[118:121], v[150:153], v[176:179], v[118:121]
	v_mfma_f32_16x16x32_bf16 v[110:113], v[158:161], v[176:179], v[110:113]
	v_mfma_f32_16x16x32_bf16 v[102:105], v[150:153], v[184:187], v[102:105]
	v_mfma_f32_16x16x32_bf16 v[94:97], v[158:161], v[184:187], v[94:97]
	s_waitcnt lgkmcnt(0)
	v_mfma_f32_16x16x32_bf16 v[86:89], v[150:153], v[192:195], v[86:89]
	v_mfma_f32_16x16x32_bf16 v[78:81], v[158:161], v[192:195], v[78:81]
	s_barrier
	s_add_i32 s68, 0, 0x14000
	v_add_u32_e32 v140, s68, v143
	s_add_i32 s65, s65, s13
	ds_read_b128 v[196:199], v140
	ds_read_b128 v[200:203], v140 offset:1024
	ds_read_b128 v[204:207], v140 offset:2048
	ds_read_b128 v[208:211], v140 offset:3072
	v_lshl_add_u64 v[140:141], s[34:35], 0, v[48:49]
	s_mov_b32 m0, s65
	v_lshl_add_u64 v[212:213], s[34:35], 0, v[130:131]
	global_load_lds_dwordx4 v[140:141], off
	s_add_i32 m0, s65, 0x2000
	s_nop 0
	global_load_lds_dwordx4 v[212:213], off
	s_barrier
	s_waitcnt lgkmcnt(3)
	v_mfma_f32_16x16x32_bf16 v[114:117], v[196:199], v[162:165], 0
	s_waitcnt lgkmcnt(1)
	v_mfma_f32_16x16x32_bf16 v[106:109], v[204:207], v[162:165], 0
	v_mfma_f32_16x16x32_bf16 v[98:101], v[196:199], v[170:173], 0
	v_mfma_f32_16x16x32_bf16 v[90:93], v[204:207], v[170:173], 0
	v_mfma_f32_16x16x32_bf16 v[82:85], v[196:199], v[180:183], 0
	v_mfma_f32_16x16x32_bf16 v[74:77], v[204:207], v[180:183], 0
	v_mfma_f32_16x16x32_bf16 v[70:73], v[196:199], v[188:191], 0
	v_mfma_f32_16x16x32_bf16 v[66:69], v[204:207], v[188:191], 0
	v_mfma_f32_16x16x32_bf16 v[114:117], v[200:203], v[166:169], v[114:117]
	s_waitcnt lgkmcnt(0)
	v_mfma_f32_16x16x32_bf16 v[106:109], v[208:211], v[166:169], v[106:109]
	v_mfma_f32_16x16x32_bf16 v[98:101], v[200:203], v[176:179], v[98:101]
	v_mfma_f32_16x16x32_bf16 v[90:93], v[208:211], v[176:179], v[90:93]
	v_mfma_f32_16x16x32_bf16 v[82:85], v[200:203], v[184:187], v[82:85]
	v_mfma_f32_16x16x32_bf16 v[74:77], v[208:211], v[184:187], v[74:77]
	v_mfma_f32_16x16x32_bf16 v[70:73], v[200:203], v[192:195], v[70:73]
	v_mfma_f32_16x16x32_bf16 v[66:69], v[208:211], v[192:195], v[66:69]
	s_mov_b32 m0, s21
	v_lshl_add_u64 v[214:215], s[36:37], 0, v[134:135]
	s_barrier
	ds_read_b128 v[162:165], v145 offset:16384
	ds_read_b128 v[166:169], v145 offset:17408
	ds_read_b128 v[170:173], v145 offset:18432
	ds_read_b128 v[176:179], v145 offset:19456
	ds_read_b128 v[180:183], v145 offset:20480
	ds_read_b128 v[184:187], v145 offset:21504
	ds_read_b128 v[188:191], v145 offset:22528
	ds_read_b128 v[192:195], v145 offset:23552
	global_load_lds_dwordx4 v[214:215], off
	s_mov_b32 m0, s46
	v_lshl_add_u64 v[216:217], s[36:37], 0, v[132:133]
	global_load_lds_dwordx4 v[216:217], off
	s_barrier
	s_waitcnt lgkmcnt(7)
	v_mfma_f32_16x16x32_bf16 v[62:65], v[146:149], v[162:165], 0
	v_mfma_f32_16x16x32_bf16 v[58:61], v[154:157], v[162:165], 0
	s_waitcnt lgkmcnt(5)
	v_mfma_f32_16x16x32_bf16 v[54:57], v[146:149], v[170:173], 0
	v_mfma_f32_16x16x32_bf16 v[44:47], v[154:157], v[170:173], 0
	s_waitcnt lgkmcnt(3)
	v_mfma_f32_16x16x32_bf16 v[36:39], v[146:149], v[180:183], 0
	v_mfma_f32_16x16x32_bf16 v[28:31], v[154:157], v[180:183], 0
	s_waitcnt lgkmcnt(1)
	v_mfma_f32_16x16x32_bf16 v[20:23], v[146:149], v[188:191], 0
	v_mfma_f32_16x16x32_bf16 v[12:15], v[154:157], v[188:191], 0
	v_mfma_f32_16x16x32_bf16 v[62:65], v[150:153], v[166:169], v[62:65]
	v_mfma_f32_16x16x32_bf16 v[58:61], v[158:161], v[166:169], v[58:61]
	v_mfma_f32_16x16x32_bf16 v[54:57], v[150:153], v[176:179], v[54:57]
	v_mfma_f32_16x16x32_bf16 v[44:47], v[158:161], v[176:179], v[44:47]
	v_mfma_f32_16x16x32_bf16 v[36:39], v[150:153], v[184:187], v[36:39]
	v_mfma_f32_16x16x32_bf16 v[28:31], v[158:161], v[184:187], v[28:31]
	s_waitcnt lgkmcnt(0)
	v_mfma_f32_16x16x32_bf16 v[20:23], v[150:153], v[192:195], v[20:23]
	v_mfma_f32_16x16x32_bf16 v[12:15], v[158:161], v[192:195], v[12:15]
	s_barrier
; #define PG8_STAGE(bufoff, gbase, voff) do { _Pragma("unroll") for (int _i = 0; _i < 2; ++_i) \
;         __builtin_amdgcn_global_load_lds((const unsigned*)((const char*)(gbase) + (voff)[_i]), (PG8_LAS unsigned*)(lds + (bufoff) + ldsw + _i * 8192), 16, 0, 0); } while (0)
; #define PG8_LDA(dst, b, h) do { _Pragma("unroll") for (int m = 0; m < 4; ++m) _Pragma("unroll") for (int k = 0; k < 2; ++k) dst[m][k] = *(const PG8_LAS bf16x8*)(lds + PG8_SA(b, h) + aoff + m * 2048 + k * 1024); } while (0)
; #define PG8_LDB(dst, b, h) do { _Pragma("unroll") for (int n = 0; n < 2; ++n) _Pragma("unroll") for (int k = 0; k < 2; ++k) dst[n][k] = *(const PG8_LAS bf16x8*)(lds + PG8_SB(b, h) + boff + n * 2048 + k * 1024); } while (0)
; #define PG8_MMA(ai, bj, At, Bt) do { __builtin_amdgcn_s_setprio(1); _Pragma("unroll") for (int m = 0; m < 4; ++m) _Pragma("unroll") for (int n = 0; n < 2; ++n) _Pragma("unroll") for (int k = 0; k < 2; ++k) \
;         acc[ai][bj][m][n] = __builtin_amdgcn_mfma_f32_16x16x32_bf16(Bt[n][k], At[m][k], acc[ai][bj][m][n], 0, 0, 0); __builtin_amdgcn_s_setprio(0); } while (0)
; #define PG8_WAIT_V(n) asm volatile("s_waitcnt vmcnt(" #n ")" ::: "memory")
; #define PG8_WAIT_L(n) asm volatile("s_waitcnt lgkmcnt(" #n ")" ::: "memory")
; #define PG8_BAR __builtin_amdgcn_s_barrier()
; #define PG8_SCHED __builtin_amdgcn_sched_barrier(0)
; template <class Epi, class Sched>
; __device__ __forceinline__ void gemm_phase(PG8_LAS unsigned char* lds, const Gemm g, const Sched& S, const Epi& E) {
;     ...
;             PG8_STAGE(PG8_SB(0, 1), b2 + hstep, voffB);
;             PG8_WAIT_V(6); PG8_BAR; PG8_MMA(1, 1, At, B1); PG8_BAR;
;             PG8_LDB(B0, 1, 0); PG8_SCHED; PG8_LDA(At, 1, 0); PG8_STAGE(PG8_SA(0, 1), a2 + hstep, voffA);
;             PG8_WAIT_L(8); PG8_BAR; PG8_WAIT_L(0); PG8_MMA(0, 0, At, B0); PG8_BAR; PG8_SCHED;
;             PG8_LDB(B1, 1, 1); PG8_STAGE(PG8_SB(1, 0), b3, voffB);
;             PG8_BAR; PG8_WAIT_L(0); PG8_MMA(0, 1, At, B1); PG8_BAR;
;             PG8_LDA(At, 1, 1); PG8_STAGE(PG8_SA(1, 0), a3, voffA);
	s_add_u32 s66, s34, 0x40000
	s_addc_u32 s67, s35, 0
	s_add_i32 s65, s68, s13
	s_mov_b32 m0, s65
	v_lshl_add_u64 v[146:147], s[66:67], 0, v[48:49]
	global_load_lds_dwordx4 v[146:147], off
	s_add_i32 m0, s65, 0x2000
	v_lshl_add_u64 v[146:147], s[66:67], 0, v[130:131]
	global_load_lds_dwordx4 v[146:147], off
	s_waitcnt vmcnt(6)
	s_barrier
	v_mfma_f32_16x16x32_bf16 v[50:53], v[196:199], v[162:165], 0
	v_mfma_f32_16x16x32_bf16 v[40:43], v[204:207], v[162:165], 0
	v_mfma_f32_16x16x32_bf16 v[32:35], v[196:199], v[170:173], 0
	v_mfma_f32_16x16x32_bf16 v[24:27], v[204:207], v[170:173], 0
	v_mfma_f32_16x16x32_bf16 v[16:19], v[196:199], v[180:183], 0
	v_mfma_f32_16x16x32_bf16 v[8:11], v[204:207], v[180:183], 0
	v_mfma_f32_16x16x32_bf16 v[4:7], v[196:199], v[188:191], 0
	v_mfma_f32_16x16x32_bf16 v[0:3], v[204:207], v[188:191], 0
	v_mfma_f32_16x16x32_bf16 v[50:53], v[200:203], v[166:169], v[50:53]
	v_mfma_f32_16x16x32_bf16 v[40:43], v[208:211], v[166:169], v[40:43]
	v_mfma_f32_16x16x32_bf16 v[32:35], v[200:203], v[176:179], v[32:35]
	v_mfma_f32_16x16x32_bf16 v[24:27], v[208:211], v[176:179], v[24:27]
	v_mfma_f32_16x16x32_bf16 v[16:19], v[200:203], v[184:187], v[16:19]
	v_mfma_f32_16x16x32_bf16 v[8:11], v[208:211], v[184:187], v[8:11]
	v_mfma_f32_16x16x32_bf16 v[4:7], v[200:203], v[192:195], v[4:7]
	v_mfma_f32_16x16x32_bf16 v[0:3], v[208:211], v[192:195], v[0:3]
	s_add_i32 s65, 0, 0x18000
	v_add_u32_e32 v158, s65, v143
	s_barrier
	ds_read_b128 v[146:149], v158
	ds_read_b128 v[150:153], v158 offset:1024
	ds_read_b128 v[154:157], v158 offset:2048
	ds_read_b128 v[158:161], v158 offset:3072
	s_add_u32 s36, s36, 0x40000
	s_addc_u32 s37, s37, 0
	s_mov_b32 m0, s47
	v_lshl_add_u64 v[196:197], s[36:37], 0, v[134:135]
	ds_read_b128 v[162:165], v145 offset:32768
	ds_read_b128 v[166:169], v145 offset:33792
	ds_read_b128 v[170:173], v145 offset:34816
	ds_read_b128 v[176:179], v145 offset:35840
	ds_read_b128 v[180:183], v145 offset:36864
	ds_read_b128 v[184:187], v145 offset:37888
	ds_read_b128 v[188:191], v145 offset:38912
	ds_read_b128 v[192:195], v145 offset:39936
	global_load_lds_dwordx4 v[196:197], off
	s_mov_b32 m0, s48
	v_lshl_add_u64 v[196:197], s[36:37], 0, v[132:133]
	global_load_lds_dwordx4 v[196:197], off
	s_waitcnt lgkmcnt(8)
	s_barrier
	s_waitcnt lgkmcnt(7)
	v_mfma_f32_16x16x32_bf16 v[126:129], v[146:149], v[162:165], v[126:129]
	v_mfma_f32_16x16x32_bf16 v[122:125], v[154:157], v[162:165], v[122:125]
	s_waitcnt lgkmcnt(5)
	v_mfma_f32_16x16x32_bf16 v[118:121], v[146:149], v[170:173], v[118:121]
	v_mfma_f32_16x16x32_bf16 v[110:113], v[154:157], v[170:173], v[110:113]
	s_waitcnt lgkmcnt(3)
	v_mfma_f32_16x16x32_bf16 v[102:105], v[146:149], v[180:183], v[102:105]
	v_mfma_f32_16x16x32_bf16 v[94:97], v[154:157], v[180:183], v[94:97]
	s_waitcnt lgkmcnt(1)
	v_mfma_f32_16x16x32_bf16 v[86:89], v[146:149], v[188:191], v[86:89]
	v_mfma_f32_16x16x32_bf16 v[78:81], v[154:157], v[188:191], v[78:81]
	v_mfma_f32_16x16x32_bf16 v[126:129], v[150:153], v[166:169], v[126:129]
	v_mfma_f32_16x16x32_bf16 v[122:125], v[158:161], v[166:169], v[122:125]
	v_mfma_f32_16x16x32_bf16 v[118:121], v[150:153], v[176:179], v[118:121]
	v_mfma_f32_16x16x32_bf16 v[110:113], v[158:161], v[176:179], v[110:113]
	v_mfma_f32_16x16x32_bf16 v[102:105], v[150:153], v[184:187], v[102:105]
	v_mfma_f32_16x16x32_bf16 v[94:97], v[158:161], v[184:187], v[94:97]
	s_waitcnt lgkmcnt(0)
	v_mfma_f32_16x16x32_bf16 v[86:89], v[150:153], v[192:195], v[86:89]
	v_mfma_f32_16x16x32_bf16 v[78:81], v[158:161], v[192:195], v[78:81]
	s_barrier
	s_add_i32 s36, 0, 0x1c000
	s_add_i32 s37, s65, s13
	v_add_u32_e32 v175, s36, v143
	v_lshl_add_u64 v[140:141], v[140:141], 0, s[0:1]
	s_mov_b32 m0, s37
	ds_read_b128 v[196:199], v175
	ds_read_b128 v[200:203], v175 offset:1024
	ds_read_b128 v[204:207], v175 offset:2048
	ds_read_b128 v[208:211], v175 offset:3072
	global_load_lds_dwordx4 v[140:141], off
	s_add_i32 m0, s37, 0x2000
	v_lshl_add_u64 v[140:141], v[212:213], 0, s[0:1]
	global_load_lds_dwordx4 v[140:141], off
	s_barrier
	s_waitcnt lgkmcnt(3)
	v_mfma_f32_16x16x32_bf16 v[114:117], v[196:199], v[162:165], v[114:117]
	s_waitcnt lgkmcnt(1)
	v_mfma_f32_16x16x32_bf16 v[106:109], v[204:207], v[162:165], v[106:109]
	v_mfma_f32_16x16x32_bf16 v[98:101], v[196:199], v[170:173], v[98:101]
	v_mfma_f32_16x16x32_bf16 v[90:93], v[204:207], v[170:173], v[90:93]
	v_mfma_f32_16x16x32_bf16 v[82:85], v[196:199], v[180:183], v[82:85]
	v_mfma_f32_16x16x32_bf16 v[74:77], v[204:207], v[180:183], v[74:77]
	v_mfma_f32_16x16x32_bf16 v[70:73], v[196:199], v[188:191], v[70:73]
	v_mfma_f32_16x16x32_bf16 v[66:69], v[204:207], v[188:191], v[66:69]
	v_mfma_f32_16x16x32_bf16 v[114:117], v[200:203], v[166:169], v[114:117]
	s_waitcnt lgkmcnt(0)
	v_mfma_f32_16x16x32_bf16 v[106:109], v[208:211], v[166:169], v[106:109]
	v_mfma_f32_16x16x32_bf16 v[98:101], v[200:203], v[176:179], v[98:101]
	v_mfma_f32_16x16x32_bf16 v[90:93], v[208:211], v[176:179], v[90:93]
	v_mfma_f32_16x16x32_bf16 v[82:85], v[200:203], v[184:187], v[82:85]
	v_mfma_f32_16x16x32_bf16 v[74:77], v[208:211], v[184:187], v[74:77]
	v_mfma_f32_16x16x32_bf16 v[70:73], v[200:203], v[192:195], v[70:73]
	v_mfma_f32_16x16x32_bf16 v[66:69], v[208:211], v[192:195], v[66:69]
	s_mov_b32 m0, s49
	v_lshl_add_u64 v[140:141], v[214:215], 0, s[0:1]
	s_barrier
	ds_read_b128 v[162:165], v145 offset:49152
	ds_read_b128 v[166:169], v145 offset:50176
	ds_read_b128 v[170:173], v145 offset:51200
	ds_read_b128 v[176:179], v145 offset:52224
	ds_read_b128 v[180:183], v145 offset:53248
	ds_read_b128 v[184:187], v145 offset:54272
	ds_read_b128 v[188:191], v145 offset:55296
	ds_read_b128 v[192:195], v145 offset:56320
	global_load_lds_dwordx4 v[140:141], off
	s_mov_b32 m0, s50
	v_lshl_add_u64 v[140:141], v[216:217], 0, s[0:1]
	global_load_lds_dwordx4 v[140:141], off
	s_barrier
; #define PG8_STAGE(bufoff, gbase, voff) do { _Pragma("unroll") for (int _i = 0; _i < 2; ++_i) \
;         __builtin_amdgcn_global_load_lds((const unsigned*)((const char*)(gbase) + (voff)[_i]), (PG8_LAS unsigned*)(lds + (bufoff) + ldsw + _i * 8192), 16, 0, 0); } while (0)
; #define PG8_LDA(dst, b, h) do { _Pragma("unroll") for (int m = 0; m < 4; ++m) _Pragma("unroll") for (int k = 0; k < 2; ++k) dst[m][k] = *(const PG8_LAS bf16x8*)(lds + PG8_SA(b, h) + aoff + m * 2048 + k * 1024); } while (0)
; #define PG8_LDB(dst, b, h) do { _Pragma("unroll") for (int n = 0; n < 2; ++n) _Pragma("unroll") for (int k = 0; k < 2; ++k) dst[n][k] = *(const PG8_LAS bf16x8*)(lds + PG8_SB(b, h) + boff + n * 2048 + k * 1024); } while (0)
; #define PG8_WAIT_V(n) asm volatile("s_waitcnt vmcnt(" #n ")" ::: "memory")
; #define PG8_WAIT_L(n) asm volatile("s_waitcnt lgkmcnt(" #n ")" ::: "memory")
; #define PG8_BAR __builtin_amdgcn_s_barrier()
; #define PG8_SCHED __builtin_amdgcn_sched_barrier(0)
; template <class Epi, class Sched>
; __device__ __forceinline__ void gemm_phase(PG8_LAS unsigned char* lds, const Gemm g, const Sched& S, const Epi& E) {
;     ...
;             PG8_LDB(B0, 0, 0); PG8_SCHED; PG8_LDA(At, 0, 0); PG8_STAGE(PG8_SA(1, 1), a1 + hstep, voffA);
;             PG8_WAIT_L(8); PG8_BAR; PG8_WAIT_L(0); PG8_MMA(0, 0, At, B0); PG8_BAR; PG8_SCHED;
;             PG8_LDB(B1, 0, 1); PG8_STAGE(PG8_SB(0, 0), b2, voffB);
;             PG8_BAR; PG8_WAIT_L(0); PG8_MMA(0, 1, At, B1); PG8_BAR;
;             PG8_LDA(At, 0, 1); PG8_STAGE(PG8_SA(0, 0), a2, voffA);
;             PG8_BAR; PG8_WAIT_L(0); PG8_MMA(1, 0, At, B0); PG8_BAR; PG8_SCHED;
;             PG8_STAGE(PG8_SB(0, 1), b2 + hstep, voffB);
;             PG8_WAIT_V(6); PG8_BAR; PG8_MMA(1, 1, At, B1); PG8_BAR;
;             PG8_LDB(B0, 1, 0); PG8_SCHED; PG8_LDA(At, 1, 0); PG8_STAGE(PG8_SA(0, 1), a2 + hstep, voffA);
;             PG8_WAIT_L(8); PG8_BAR; PG8_WAIT_L(0); PG8_MMA(0, 0, At, B0); PG8_BAR; PG8_SCHED;
;             PG8_LDB(B1, 1, 1); PG8_STAGE(PG8_SB(1, 0), b3, voffB);
;             PG8_BAR; PG8_WAIT_L(0); PG8_MMA(0, 1, At, B1); PG8_BAR;
;             PG8_LDA(At, 1, 1); PG8_STAGE(PG8_SA(1, 0), a3, voffA);
;             PG8_BAR; PG8_WAIT_L(0); PG8_MMA(1, 0, At, B0); PG8_BAR; PG8_SCHED;
;             PG8_STAGE(PG8_SB(1, 1), b3 + hstep, voffB);
;             PG8_WAIT_V(6); PG8_BAR; PG8_MMA(1, 1, At, B1); PG8_BAR;
	s_waitcnt lgkmcnt(7)
	v_mfma_f32_16x16x32_bf16 v[62:65], v[146:149], v[162:165], v[62:65]
	v_mfma_f32_16x16x32_bf16 v[58:61], v[154:157], v[162:165], v[58:61]
	s_waitcnt lgkmcnt(5)
	v_mfma_f32_16x16x32_bf16 v[54:57], v[146:149], v[170:173], v[54:57]
	v_mfma_f32_16x16x32_bf16 v[44:47], v[154:157], v[170:173], v[44:47]
	s_waitcnt lgkmcnt(3)
	v_mfma_f32_16x16x32_bf16 v[36:39], v[146:149], v[180:183], v[36:39]
	v_mfma_f32_16x16x32_bf16 v[28:31], v[154:157], v[180:183], v[28:31]
	s_waitcnt lgkmcnt(1)
	v_mfma_f32_16x16x32_bf16 v[20:23], v[146:149], v[188:191], v[20:23]
	v_mfma_f32_16x16x32_bf16 v[12:15], v[154:157], v[188:191], v[12:15]
	v_mfma_f32_16x16x32_bf16 v[62:65], v[150:153], v[166:169], v[62:65]
	v_mfma_f32_16x16x32_bf16 v[58:61], v[158:161], v[166:169], v[58:61]
	v_mfma_f32_16x16x32_bf16 v[54:57], v[150:153], v[176:179], v[54:57]
	v_mfma_f32_16x16x32_bf16 v[44:47], v[158:161], v[176:179], v[44:47]
	v_mfma_f32_16x16x32_bf16 v[36:39], v[150:153], v[184:187], v[36:39]
	v_mfma_f32_16x16x32_bf16 v[28:31], v[158:161], v[184:187], v[28:31]
	s_waitcnt lgkmcnt(0)
	v_mfma_f32_16x16x32_bf16 v[20:23], v[150:153], v[192:195], v[20:23]
	v_mfma_f32_16x16x32_bf16 v[12:15], v[158:161], v[192:195], v[12:15]
	s_barrier
	s_add_u32 s34, s34, 0x40080
	s_addc_u32 s35, s35, 0
	s_add_i32 s36, s36, s13
	s_mov_b32 m0, s36
	v_lshl_add_u64 v[140:141], s[34:35], 0, v[48:49]
	global_load_lds_dwordx4 v[140:141], off
	s_add_i32 m0, s36, 0x2000
	v_lshl_add_u64 v[140:141], s[34:35], 0, v[130:131]
	global_load_lds_dwordx4 v[140:141], off
	s_waitcnt vmcnt(6)
	s_barrier
	v_mfma_f32_16x16x32_bf16 v[50:53], v[196:199], v[162:165], v[50:53]
	v_mfma_f32_16x16x32_bf16 v[40:43], v[204:207], v[162:165], v[40:43]
	v_mfma_f32_16x16x32_bf16 v[32:35], v[196:199], v[170:173], v[32:35]
	v_mfma_f32_16x16x32_bf16 v[24:27], v[204:207], v[170:173], v[24:27]
	v_mfma_f32_16x16x32_bf16 v[16:19], v[196:199], v[180:183], v[16:19]
	v_mfma_f32_16x16x32_bf16 v[8:11], v[204:207], v[180:183], v[8:11]
	v_mfma_f32_16x16x32_bf16 v[4:7], v[196:199], v[188:191], v[4:7]
	v_mfma_f32_16x16x32_bf16 v[0:3], v[204:207], v[188:191], v[0:3]
	v_mfma_f32_16x16x32_bf16 v[50:53], v[200:203], v[166:169], v[50:53]
	v_mfma_f32_16x16x32_bf16 v[40:43], v[208:211], v[166:169], v[40:43]
	v_mfma_f32_16x16x32_bf16 v[32:35], v[200:203], v[176:179], v[32:35]
	v_mfma_f32_16x16x32_bf16 v[24:27], v[208:211], v[176:179], v[24:27]
	v_mfma_f32_16x16x32_bf16 v[16:19], v[200:203], v[184:187], v[16:19]
	v_mfma_f32_16x16x32_bf16 v[8:11], v[208:211], v[184:187], v[8:11]
	v_mfma_f32_16x16x32_bf16 v[4:7], v[200:203], v[192:195], v[4:7]
	v_mfma_f32_16x16x32_bf16 v[0:3], v[208:211], v[192:195], v[0:3]
	s_add_i32 s64, s64, 2
	s_add_u32 s30, s30, 0x100
	s_addc_u32 s31, s31, 0
	s_add_u32 s59, s59, 0x100
	s_addc_u32 s63, s63, 0
	s_cmp_gt_u32 s64, 13
	s_barrier
	s_cbranch_scc1 .Lkpeel_exit_320
.LBB0_320:
	s_add_u32 s34, s30, 0xfffc0080
	s_addc_u32 s35, s31, -1
	s_add_i32 s65, 0, 0x10000
	v_add_u32_e32 v140, s65, v143
	ds_read_b128 v[146:149], v140
	ds_read_b128 v[150:153], v140 offset:1024
	ds_read_b128 v[154:157], v140 offset:2048
	ds_read_b128 v[158:161], v140 offset:3072
	s_cmp_eq_u32 s64, 12
	s_cselect_b32 s37, s25, s35
	s_cselect_b32 s36, s56, s34
	s_cselect_b32 s35, s23, s63
	s_cselect_b32 s34, s57, s59
	v_lshl_add_u64 v[140:141], s[30:31], 0, v[136:137]
	s_add_i32 m0, s21, 0xc000
	ds_read_b128 v[162:165], v145
	ds_read_b128 v[166:169], v145 offset:1024
	ds_read_b128 v[170:173], v145 offset:2048
	ds_read_b128 v[176:179], v145 offset:3072
	ds_read_b128 v[180:183], v145 offset:4096
	ds_read_b128 v[184:187], v145 offset:5120
	ds_read_b128 v[188:191], v145 offset:6144
	ds_read_b128 v[192:195], v145 offset:7168
	global_load_lds_dwordx4 v[140:141], off
	s_add_i32 m0, s21, 0xe000
	v_lshl_add_u64 v[140:141], s[30:31], 0, v[138:139]
	global_load_lds_dwordx4 v[140:141], off
	s_waitcnt lgkmcnt(8)
	s_barrier
	s_waitcnt lgkmcnt(7)
	v_mfma_f32_16x16x32_bf16 v[126:129], v[146:149], v[162:165], v[126:129]
	v_mfma_f32_16x16x32_bf16 v[122:125], v[154:157], v[162:165], v[122:125]
	s_waitcnt lgkmcnt(5)
	v_mfma_f32_16x16x32_bf16 v[118:121], v[146:149], v[170:173], v[118:121]
	v_mfma_f32_16x16x32_bf16 v[110:113], v[154:157], v[170:173], v[110:113]
	s_waitcnt lgkmcnt(3)
	v_mfma_f32_16x16x32_bf16 v[102:105], v[146:149], v[180:183], v[102:105]
	v_mfma_f32_16x16x32_bf16 v[94:97], v[154:157], v[180:183], v[94:97]
	s_waitcnt lgkmcnt(1)
	v_mfma_f32_16x16x32_bf16 v[86:89], v[146:149], v[188:191], v[86:89]
	v_mfma_f32_16x16x32_bf16 v[78:81], v[154:157], v[188:191], v[78:81]
	v_mfma_f32_16x16x32_bf16 v[126:129], v[150:153], v[166:169], v[126:129]
	v_mfma_f32_16x16x32_bf16 v[122:125], v[158:161], v[166:169], v[122:125]
	v_mfma_f32_16x16x32_bf16 v[118:121], v[150:153], v[176:179], v[118:121]
	v_mfma_f32_16x16x32_bf16 v[110:113], v[158:161], v[176:179], v[110:113]
	v_mfma_f32_16x16x32_bf16 v[102:105], v[150:153], v[184:187], v[102:105]
	v_mfma_f32_16x16x32_bf16 v[94:97], v[158:161], v[184:187], v[94:97]
	s_waitcnt lgkmcnt(0)
	v_mfma_f32_16x16x32_bf16 v[86:89], v[150:153], v[192:195], v[86:89]
	v_mfma_f32_16x16x32_bf16 v[78:81], v[158:161], v[192:195], v[78:81]
	s_barrier
	s_add_i32 s68, 0, 0x14000
	v_add_u32_e32 v140, s68, v143
	s_add_i32 s65, s65, s13
	ds_read_b128 v[196:199], v140
	ds_read_b128 v[200:203], v140 offset:1024
	ds_read_b128 v[204:207], v140 offset:2048
	ds_read_b128 v[208:211], v140 offset:3072
	v_lshl_add_u64 v[140:141], s[34:35], 0, v[48:49]
	s_mov_b32 m0, s65
	v_lshl_add_u64 v[212:213], s[34:35], 0, v[130:131]
	global_load_lds_dwordx4 v[140:141], off
	s_add_i32 m0, s65, 0x2000
	s_nop 0
	global_load_lds_dwordx4 v[212:213], off
	s_barrier
; #define PG8_STAGE(bufoff, gbase, voff) do { _Pragma("unroll") for (int _i = 0; _i < 2; ++_i) \
;         __builtin_amdgcn_global_load_lds((const unsigned*)((const char*)(gbase) + (voff)[_i]), (PG8_LAS unsigned*)(lds + (bufoff) + ldsw + _i * 8192), 16, 0, 0); } while (0)
; #define PG8_LDA(dst, b, h) do { _Pragma("unroll") for (int m = 0; m < 4; ++m) _Pragma("unroll") for (int k = 0; k < 2; ++k) dst[m][k] = *(const PG8_LAS bf16x8*)(lds + PG8_SA(b, h) + aoff + m * 2048 + k * 1024); } while (0)
; #define PG8_LDB(dst, b, h) do { _Pragma("unroll") for (int n = 0; n < 2; ++n) _Pragma("unroll") for (int k = 0; k < 2; ++k) dst[n][k] = *(const PG8_LAS bf16x8*)(lds + PG8_SB(b, h) + boff + n * 2048 + k * 1024); } while (0)
; #define PG8_MMA(ai, bj, At, Bt) do { __builtin_amdgcn_s_setprio(1); _Pragma("unroll") for (int m = 0; m < 4; ++m) _Pragma("unroll") for (int n = 0; n < 2; ++n) _Pragma("unroll") for (int k = 0; k < 2; ++k) \
;         acc[ai][bj][m][n] = __builtin_amdgcn_mfma_f32_16x16x32_bf16(Bt[n][k], At[m][k], acc[ai][bj][m][n], 0, 0, 0); __builtin_amdgcn_s_setprio(0); } while (0)
; #define PG8_WAIT_V(n) asm volatile("s_waitcnt vmcnt(" #n ")" ::: "memory")
; #define PG8_WAIT_L(n) asm volatile("s_waitcnt lgkmcnt(" #n ")" ::: "memory")
; #define PG8_BAR __builtin_amdgcn_s_barrier()
; #define PG8_SCHED __builtin_amdgcn_sched_barrier(0)
; template <class Epi, class Sched>
; __device__ __forceinline__ void gemm_phase(PG8_LAS unsigned char* lds, const Gemm g, const Sched& S, const Epi& E) {
;     ...
;             PG8_BAR; PG8_WAIT_L(0); PG8_MMA(0, 1, At, B1); PG8_BAR;
;             PG8_LDA(At, 0, 1); PG8_STAGE(PG8_SA(0, 0), a2, voffA);
;             PG8_BAR; PG8_WAIT_L(0); PG8_MMA(1, 0, At, B0); PG8_BAR; PG8_SCHED;
;             PG8_STAGE(PG8_SB(0, 1), b2 + hstep, voffB);
;             PG8_WAIT_V(6); PG8_BAR; PG8_MMA(1, 1, At, B1); PG8_BAR;
;             PG8_LDB(B0, 1, 0); PG8_SCHED; PG8_LDA(At, 1, 0); PG8_STAGE(PG8_SA(0, 1), a2 + hstep, voffA);
;             PG8_WAIT_L(8); PG8_BAR; PG8_WAIT_L(0); PG8_MMA(0, 0, At, B0); PG8_BAR; PG8_SCHED;
	s_waitcnt lgkmcnt(3)
	v_mfma_f32_16x16x32_bf16 v[114:117], v[196:199], v[162:165], v[114:117]
	s_waitcnt lgkmcnt(1)
	v_mfma_f32_16x16x32_bf16 v[106:109], v[204:207], v[162:165], v[106:109]
	v_mfma_f32_16x16x32_bf16 v[98:101], v[196:199], v[170:173], v[98:101]
	v_mfma_f32_16x16x32_bf16 v[90:93], v[204:207], v[170:173], v[90:93]
	v_mfma_f32_16x16x32_bf16 v[82:85], v[196:199], v[180:183], v[82:85]
	v_mfma_f32_16x16x32_bf16 v[74:77], v[204:207], v[180:183], v[74:77]
	v_mfma_f32_16x16x32_bf16 v[70:73], v[196:199], v[188:191], v[70:73]
	v_mfma_f32_16x16x32_bf16 v[66:69], v[204:207], v[188:191], v[66:69]
	v_mfma_f32_16x16x32_bf16 v[114:117], v[200:203], v[166:169], v[114:117]
	s_waitcnt lgkmcnt(0)
	v_mfma_f32_16x16x32_bf16 v[106:109], v[208:211], v[166:169], v[106:109]
	v_mfma_f32_16x16x32_bf16 v[98:101], v[200:203], v[176:179], v[98:101]
	v_mfma_f32_16x16x32_bf16 v[90:93], v[208:211], v[176:179], v[90:93]
	v_mfma_f32_16x16x32_bf16 v[82:85], v[200:203], v[184:187], v[82:85]
	v_mfma_f32_16x16x32_bf16 v[74:77], v[208:211], v[184:187], v[74:77]
	v_mfma_f32_16x16x32_bf16 v[70:73], v[200:203], v[192:195], v[70:73]
	v_mfma_f32_16x16x32_bf16 v[66:69], v[208:211], v[192:195], v[66:69]
	s_mov_b32 m0, s21
	v_lshl_add_u64 v[214:215], s[36:37], 0, v[134:135]
	s_barrier
	ds_read_b128 v[162:165], v145 offset:16384
	ds_read_b128 v[166:169], v145 offset:17408
	ds_read_b128 v[170:173], v145 offset:18432
	ds_read_b128 v[176:179], v145 offset:19456
	ds_read_b128 v[180:183], v145 offset:20480
	ds_read_b128 v[184:187], v145 offset:21504
	ds_read_b128 v[188:191], v145 offset:22528
	ds_read_b128 v[192:195], v145 offset:23552
	global_load_lds_dwordx4 v[214:215], off
	s_mov_b32 m0, s46
	v_lshl_add_u64 v[216:217], s[36:37], 0, v[132:133]
	global_load_lds_dwordx4 v[216:217], off
	s_barrier
	s_waitcnt lgkmcnt(7)
	v_mfma_f32_16x16x32_bf16 v[62:65], v[146:149], v[162:165], v[62:65]
	v_mfma_f32_16x16x32_bf16 v[58:61], v[154:157], v[162:165], v[58:61]
	s_waitcnt lgkmcnt(5)
	v_mfma_f32_16x16x32_bf16 v[54:57], v[146:149], v[170:173], v[54:57]
	v_mfma_f32_16x16x32_bf16 v[44:47], v[154:157], v[170:173], v[44:47]
	s_waitcnt lgkmcnt(3)
	v_mfma_f32_16x16x32_bf16 v[36:39], v[146:149], v[180:183], v[36:39]
	v_mfma_f32_16x16x32_bf16 v[28:31], v[154:157], v[180:183], v[28:31]
	s_waitcnt lgkmcnt(1)
	v_mfma_f32_16x16x32_bf16 v[20:23], v[146:149], v[188:191], v[20:23]
	v_mfma_f32_16x16x32_bf16 v[12:15], v[154:157], v[188:191], v[12:15]
	v_mfma_f32_16x16x32_bf16 v[62:65], v[150:153], v[166:169], v[62:65]
	v_mfma_f32_16x16x32_bf16 v[58:61], v[158:161], v[166:169], v[58:61]
	v_mfma_f32_16x16x32_bf16 v[54:57], v[150:153], v[176:179], v[54:57]
	v_mfma_f32_16x16x32_bf16 v[44:47], v[158:161], v[176:179], v[44:47]
	v_mfma_f32_16x16x32_bf16 v[36:39], v[150:153], v[184:187], v[36:39]
	v_mfma_f32_16x16x32_bf16 v[28:31], v[158:161], v[184:187], v[28:31]
	s_waitcnt lgkmcnt(0)
	v_mfma_f32_16x16x32_bf16 v[20:23], v[150:153], v[192:195], v[20:23]
	v_mfma_f32_16x16x32_bf16 v[12:15], v[158:161], v[192:195], v[12:15]
	s_barrier
	s_add_u32 s66, s34, 0x40000
	s_addc_u32 s67, s35, 0
	s_add_i32 s65, s68, s13
	s_mov_b32 m0, s65
	v_lshl_add_u64 v[146:147], s[66:67], 0, v[48:49]
	global_load_lds_dwordx4 v[146:147], off
	s_add_i32 m0, s65, 0x2000
	v_lshl_add_u64 v[146:147], s[66:67], 0, v[130:131]
	global_load_lds_dwordx4 v[146:147], off
	s_waitcnt vmcnt(6)
	s_barrier
	v_mfma_f32_16x16x32_bf16 v[50:53], v[196:199], v[162:165], v[50:53]
	v_mfma_f32_16x16x32_bf16 v[40:43], v[204:207], v[162:165], v[40:43]
	v_mfma_f32_16x16x32_bf16 v[32:35], v[196:199], v[170:173], v[32:35]
	v_mfma_f32_16x16x32_bf16 v[24:27], v[204:207], v[170:173], v[24:27]
	v_mfma_f32_16x16x32_bf16 v[16:19], v[196:199], v[180:183], v[16:19]
	v_mfma_f32_16x16x32_bf16 v[8:11], v[204:207], v[180:183], v[8:11]
	v_mfma_f32_16x16x32_bf16 v[4:7], v[196:199], v[188:191], v[4:7]
	v_mfma_f32_16x16x32_bf16 v[0:3], v[204:207], v[188:191], v[0:3]
	v_mfma_f32_16x16x32_bf16 v[50:53], v[200:203], v[166:169], v[50:53]
	v_mfma_f32_16x16x32_bf16 v[40:43], v[208:211], v[166:169], v[40:43]
	v_mfma_f32_16x16x32_bf16 v[32:35], v[200:203], v[176:179], v[32:35]
	v_mfma_f32_16x16x32_bf16 v[24:27], v[208:211], v[176:179], v[24:27]
	v_mfma_f32_16x16x32_bf16 v[16:19], v[200:203], v[184:187], v[16:19]
	v_mfma_f32_16x16x32_bf16 v[8:11], v[208:211], v[184:187], v[8:11]
	v_mfma_f32_16x16x32_bf16 v[4:7], v[200:203], v[192:195], v[4:7]
	v_mfma_f32_16x16x32_bf16 v[0:3], v[208:211], v[192:195], v[0:3]
	s_add_i32 s65, 0, 0x18000
	v_add_u32_e32 v158, s65, v143
	s_barrier
	ds_read_b128 v[146:149], v158
	ds_read_b128 v[150:153], v158 offset:1024
	ds_read_b128 v[154:157], v158 offset:2048
	ds_read_b128 v[158:161], v158 offset:3072
	s_add_u32 s36, s36, 0x40000
	s_addc_u32 s37, s37, 0
	s_mov_b32 m0, s47
	v_lshl_add_u64 v[196:197], s[36:37], 0, v[134:135]
	ds_read_b128 v[162:165], v145 offset:32768
	ds_read_b128 v[166:169], v145 offset:33792
	ds_read_b128 v[170:173], v145 offset:34816
	ds_read_b128 v[176:179], v145 offset:35840
	ds_read_b128 v[180:183], v145 offset:36864
	ds_read_b128 v[184:187], v145 offset:37888
	ds_read_b128 v[188:191], v145 offset:38912
	ds_read_b128 v[192:195], v145 offset:39936
	global_load_lds_dwordx4 v[196:197], off
	s_mov_b32 m0, s48
	v_lshl_add_u64 v[196:197], s[36:37], 0, v[132:133]
	global_load_lds_dwordx4 v[196:197], off
	s_waitcnt lgkmcnt(8)
	s_barrier
; #define PG8_STAGE(bufoff, gbase, voff) do { _Pragma("unroll") for (int _i = 0; _i < 2; ++_i) \
;         __builtin_amdgcn_global_load_lds((const unsigned*)((const char*)(gbase) + (voff)[_i]), (PG8_LAS unsigned*)(lds + (bufoff) + ldsw + _i * 8192), 16, 0, 0); } while (0)
; #define PG8_LDA(dst, b, h) do { _Pragma("unroll") for (int m = 0; m < 4; ++m) _Pragma("unroll") for (int k = 0; k < 2; ++k) dst[m][k] = *(const PG8_LAS bf16x8*)(lds + PG8_SA(b, h) + aoff + m * 2048 + k * 1024); } while (0)
; #define PG8_LDB(dst, b, h) do { _Pragma("unroll") for (int n = 0; n < 2; ++n) _Pragma("unroll") for (int k = 0; k < 2; ++k) dst[n][k] = *(const PG8_LAS bf16x8*)(lds + PG8_SB(b, h) + boff + n * 2048 + k * 1024); } while (0)
; #define PG8_MMA(ai, bj, At, Bt) do { __builtin_amdgcn_s_setprio(1); _Pragma("unroll") for (int m = 0; m < 4; ++m) _Pragma("unroll") for (int n = 0; n < 2; ++n) _Pragma("unroll") for (int k = 0; k < 2; ++k) \
;         acc[ai][bj][m][n] = __builtin_amdgcn_mfma_f32_16x16x32_bf16(Bt[n][k], At[m][k], acc[ai][bj][m][n], 0, 0, 0); __builtin_amdgcn_s_setprio(0); } while (0)
; #define PG8_WAIT_V(n) asm volatile("s_waitcnt vmcnt(" #n ")" ::: "memory")
; #define PG8_WAIT_L(n) asm volatile("s_waitcnt lgkmcnt(" #n ")" ::: "memory")
; #define PG8_BAR __builtin_amdgcn_s_barrier()
; #define PG8_SCHED __builtin_amdgcn_sched_barrier(0)
; template <class Epi, class Sched>
; __device__ __forceinline__ void gemm_phase(PG8_LAS unsigned char* lds, const Gemm g, const Sched& S, const Epi& E) {
;     ...
;             PG8_WAIT_L(8); PG8_BAR; PG8_WAIT_L(0); PG8_MMA(0, 0, At, B0); PG8_BAR; PG8_SCHED;
;             PG8_LDB(B1, 1, 1); PG8_STAGE(PG8_SB(1, 0), b3, voffB);
;             PG8_BAR; PG8_WAIT_L(0); PG8_MMA(0, 1, At, B1); PG8_BAR;
;             PG8_LDA(At, 1, 1); PG8_STAGE(PG8_SA(1, 0), a3, voffA);
;             PG8_BAR; PG8_WAIT_L(0); PG8_MMA(1, 0, At, B0); PG8_BAR; PG8_SCHED;
;             PG8_STAGE(PG8_SB(1, 1), b3 + hstep, voffB);
;             PG8_WAIT_V(6); PG8_BAR; PG8_MMA(1, 1, At, B1); PG8_BAR;
;         }
	s_waitcnt lgkmcnt(7)
	v_mfma_f32_16x16x32_bf16 v[126:129], v[146:149], v[162:165], v[126:129]
	v_mfma_f32_16x16x32_bf16 v[122:125], v[154:157], v[162:165], v[122:125]
	s_waitcnt lgkmcnt(5)
	v_mfma_f32_16x16x32_bf16 v[118:121], v[146:149], v[170:173], v[118:121]
	v_mfma_f32_16x16x32_bf16 v[110:113], v[154:157], v[170:173], v[110:113]
	s_waitcnt lgkmcnt(3)
	v_mfma_f32_16x16x32_bf16 v[102:105], v[146:149], v[180:183], v[102:105]
	v_mfma_f32_16x16x32_bf16 v[94:97], v[154:157], v[180:183], v[94:97]
	s_waitcnt lgkmcnt(1)
	v_mfma_f32_16x16x32_bf16 v[86:89], v[146:149], v[188:191], v[86:89]
	v_mfma_f32_16x16x32_bf16 v[78:81], v[154:157], v[188:191], v[78:81]
	v_mfma_f32_16x16x32_bf16 v[126:129], v[150:153], v[166:169], v[126:129]
	v_mfma_f32_16x16x32_bf16 v[122:125], v[158:161], v[166:169], v[122:125]
	v_mfma_f32_16x16x32_bf16 v[118:121], v[150:153], v[176:179], v[118:121]
	v_mfma_f32_16x16x32_bf16 v[110:113], v[158:161], v[176:179], v[110:113]
	v_mfma_f32_16x16x32_bf16 v[102:105], v[150:153], v[184:187], v[102:105]
	v_mfma_f32_16x16x32_bf16 v[94:97], v[158:161], v[184:187], v[94:97]
	s_waitcnt lgkmcnt(0)
	v_mfma_f32_16x16x32_bf16 v[86:89], v[150:153], v[192:195], v[86:89]
	v_mfma_f32_16x16x32_bf16 v[78:81], v[158:161], v[192:195], v[78:81]
	s_barrier
	s_add_i32 s36, 0, 0x1c000
	s_add_i32 s37, s65, s13
	v_add_u32_e32 v175, s36, v143
	v_lshl_add_u64 v[140:141], v[140:141], 0, s[0:1]
	s_mov_b32 m0, s37
	ds_read_b128 v[196:199], v175
	ds_read_b128 v[200:203], v175 offset:1024
	ds_read_b128 v[204:207], v175 offset:2048
	ds_read_b128 v[208:211], v175 offset:3072
	global_load_lds_dwordx4 v[140:141], off
	s_add_i32 m0, s37, 0x2000
	v_lshl_add_u64 v[140:141], v[212:213], 0, s[0:1]
	global_load_lds_dwordx4 v[140:141], off
	s_barrier
	s_waitcnt lgkmcnt(3)
	v_mfma_f32_16x16x32_bf16 v[114:117], v[196:199], v[162:165], v[114:117]
	s_waitcnt lgkmcnt(1)
	v_mfma_f32_16x16x32_bf16 v[106:109], v[204:207], v[162:165], v[106:109]
	v_mfma_f32_16x16x32_bf16 v[98:101], v[196:199], v[170:173], v[98:101]
	v_mfma_f32_16x16x32_bf16 v[90:93], v[204:207], v[170:173], v[90:93]
	v_mfma_f32_16x16x32_bf16 v[82:85], v[196:199], v[180:183], v[82:85]
	v_mfma_f32_16x16x32_bf16 v[74:77], v[204:207], v[180:183], v[74:77]
	v_mfma_f32_16x16x32_bf16 v[70:73], v[196:199], v[188:191], v[70:73]
	v_mfma_f32_16x16x32_bf16 v[66:69], v[204:207], v[188:191], v[66:69]
	v_mfma_f32_16x16x32_bf16 v[114:117], v[200:203], v[166:169], v[114:117]
	s_waitcnt lgkmcnt(0)
	v_mfma_f32_16x16x32_bf16 v[106:109], v[208:211], v[166:169], v[106:109]
	v_mfma_f32_16x16x32_bf16 v[98:101], v[200:203], v[176:179], v[98:101]
	v_mfma_f32_16x16x32_bf16 v[90:93], v[208:211], v[176:179], v[90:93]
	v_mfma_f32_16x16x32_bf16 v[82:85], v[200:203], v[184:187], v[82:85]
	v_mfma_f32_16x16x32_bf16 v[74:77], v[208:211], v[184:187], v[74:77]
	v_mfma_f32_16x16x32_bf16 v[70:73], v[200:203], v[192:195], v[70:73]
	v_mfma_f32_16x16x32_bf16 v[66:69], v[208:211], v[192:195], v[66:69]
	s_mov_b32 m0, s49
	v_lshl_add_u64 v[140:141], v[214:215], 0, s[0:1]
	s_barrier
	ds_read_b128 v[162:165], v145 offset:49152
	ds_read_b128 v[166:169], v145 offset:50176
	ds_read_b128 v[170:173], v145 offset:51200
	ds_read_b128 v[176:179], v145 offset:52224
	ds_read_b128 v[180:183], v145 offset:53248
	ds_read_b128 v[184:187], v145 offset:54272
	ds_read_b128 v[188:191], v145 offset:55296
	ds_read_b128 v[192:195], v145 offset:56320
	global_load_lds_dwordx4 v[140:141], off
	s_mov_b32 m0, s50
	v_lshl_add_u64 v[140:141], v[216:217], 0, s[0:1]
	global_load_lds_dwordx4 v[140:141], off
	s_barrier
	s_waitcnt lgkmcnt(7)
	v_mfma_f32_16x16x32_bf16 v[62:65], v[146:149], v[162:165], v[62:65]
	v_mfma_f32_16x16x32_bf16 v[58:61], v[154:157], v[162:165], v[58:61]
	s_waitcnt lgkmcnt(5)
	v_mfma_f32_16x16x32_bf16 v[54:57], v[146:149], v[170:173], v[54:57]
	v_mfma_f32_16x16x32_bf16 v[44:47], v[154:157], v[170:173], v[44:47]
	s_waitcnt lgkmcnt(3)
	v_mfma_f32_16x16x32_bf16 v[36:39], v[146:149], v[180:183], v[36:39]
	v_mfma_f32_16x16x32_bf16 v[28:31], v[154:157], v[180:183], v[28:31]
	s_waitcnt lgkmcnt(1)
	v_mfma_f32_16x16x32_bf16 v[20:23], v[146:149], v[188:191], v[20:23]
	v_mfma_f32_16x16x32_bf16 v[12:15], v[154:157], v[188:191], v[12:15]
	v_mfma_f32_16x16x32_bf16 v[62:65], v[150:153], v[166:169], v[62:65]
	v_mfma_f32_16x16x32_bf16 v[58:61], v[158:161], v[166:169], v[58:61]
	v_mfma_f32_16x16x32_bf16 v[54:57], v[150:153], v[176:179], v[54:57]
	v_mfma_f32_16x16x32_bf16 v[44:47], v[158:161], v[176:179], v[44:47]
	v_mfma_f32_16x16x32_bf16 v[36:39], v[150:153], v[184:187], v[36:39]
	v_mfma_f32_16x16x32_bf16 v[28:31], v[158:161], v[184:187], v[28:31]
	s_waitcnt lgkmcnt(0)
	v_mfma_f32_16x16x32_bf16 v[20:23], v[150:153], v[192:195], v[20:23]
	v_mfma_f32_16x16x32_bf16 v[12:15], v[158:161], v[192:195], v[12:15]
	s_barrier
	s_add_u32 s34, s34, 0x40080
	s_addc_u32 s35, s35, 0
	s_add_i32 s36, s36, s13
	s_mov_b32 m0, s36
	v_lshl_add_u64 v[140:141], s[34:35], 0, v[48:49]
	global_load_lds_dwordx4 v[140:141], off
	s_add_i32 m0, s36, 0x2000
	v_lshl_add_u64 v[140:141], s[34:35], 0, v[130:131]
	global_load_lds_dwordx4 v[140:141], off
	s_waitcnt vmcnt(6)
	s_barrier
	v_mfma_f32_16x16x32_bf16 v[50:53], v[196:199], v[162:165], v[50:53]
	v_mfma_f32_16x16x32_bf16 v[40:43], v[204:207], v[162:165], v[40:43]
	v_mfma_f32_16x16x32_bf16 v[32:35], v[196:199], v[170:173], v[32:35]
	v_mfma_f32_16x16x32_bf16 v[24:27], v[204:207], v[170:173], v[24:27]
	v_mfma_f32_16x16x32_bf16 v[16:19], v[196:199], v[180:183], v[16:19]
	v_mfma_f32_16x16x32_bf16 v[8:11], v[204:207], v[180:183], v[8:11]
	v_mfma_f32_16x16x32_bf16 v[4:7], v[196:199], v[188:191], v[4:7]
	v_mfma_f32_16x16x32_bf16 v[0:3], v[204:207], v[188:191], v[0:3]
	v_mfma_f32_16x16x32_bf16 v[50:53], v[200:203], v[166:169], v[50:53]
	v_mfma_f32_16x16x32_bf16 v[40:43], v[208:211], v[166:169], v[40:43]
	v_mfma_f32_16x16x32_bf16 v[32:35], v[200:203], v[176:179], v[32:35]
	v_mfma_f32_16x16x32_bf16 v[24:27], v[208:211], v[176:179], v[24:27]
	v_mfma_f32_16x16x32_bf16 v[16:19], v[200:203], v[184:187], v[16:19]
	v_mfma_f32_16x16x32_bf16 v[8:11], v[208:211], v[184:187], v[8:11]
	v_mfma_f32_16x16x32_bf16 v[4:7], v[200:203], v[192:195], v[4:7]
	v_mfma_f32_16x16x32_bf16 v[0:3], v[208:211], v[192:195], v[0:3]
	s_add_i32 s64, s64, 2
	s_add_u32 s30, s30, 0x100
	s_addc_u32 s31, s31, 0
	s_add_u32 s59, s59, 0x100
	s_addc_u32 s63, s63, 0
	s_cmp_gt_u32 s64, 13
	s_barrier
	s_cbranch_scc0 .LBB0_320

; #define PG8_STAGE(bufoff, gbase, voff) do { _Pragma("unroll") for (int _i = 0; _i < 2; ++_i) \
;         __builtin_amdgcn_global_load_lds((const unsigned*)((const char*)(gbase) + (voff)[_i]), (PG8_LAS unsigned*)(lds + (bufoff) + ldsw + _i * 8192), 16, 0, 0); } while (0)
; #define PG8_LDA(dst, b, h) do { _Pragma("unroll") for (int m = 0; m < 4; ++m) _Pragma("unroll") for (int k = 0; k < 2; ++k) dst[m][k] = *(const PG8_LAS bf16x8*)(lds + PG8_SA(b, h) + aoff + m * 2048 + k * 1024); } while (0)
; #define PG8_LDB(dst, b, h) do { _Pragma("unroll") for (int n = 0; n < 2; ++n) _Pragma("unroll") for (int k = 0; k < 2; ++k) dst[n][k] = *(const PG8_LAS bf16x8*)(lds + PG8_SB(b, h) + boff + n * 2048 + k * 1024); } while (0)
; #define PG8_WAIT_L(n) asm volatile("s_waitcnt lgkmcnt(" #n ")" ::: "memory")
; #define PG8_BAR __builtin_amdgcn_s_barrier()
; #define PG8_SCHED __builtin_amdgcn_sched_barrier(0)
; template <class Epi, class Sched>
; __device__ __forceinline__ void gemm_phase(PG8_LAS unsigned char* lds, const Gemm g, const Sched& S, const Epi& E) {
;     ...
;         const bool has_next = S.next(ui + 1, nxt);
;         const char* nA = has_next ? (const char*)g.A + (size_t)nxt.pm * tstepA + (size_t)nxt.kc * cstep : cA; const char* nB = has_next ? (const char*)g.Bt + (size_t)nxt.pn * tstep + (size_t)nxt.kc * cstep : cB;
;         for (int t = 0; t < nt; t += 2) {
;             const bool last = (t == nt - 2);
;             const char* a1 = cA + (size_t)(t + 1) * kstep;
;             const char* a2 = last ? nA : cA + (size_t)(t + 2) * kstep; const char* b2 = last ? nB : cB + (size_t)(t + 2) * kstep;
;             const char* a3 = a2 + kstep; const char* b3 = b2 + kstep;
;             if (last && has_next) S.a_ready(nxt);
;             PG8_LDB(B0, 0, 0); PG8_SCHED; PG8_LDA(At, 0, 0); PG8_STAGE(PG8_SA(1, 1), a1 + hstep, voffA);
;             PG8_WAIT_L(8); PG8_BAR; PG8_WAIT_L(0); PG8_MMA(0, 0, At, B0); PG8_BAR; PG8_SCHED;
;             PG8_LDB(B1, 0, 1); PG8_STAGE(PG8_SB(0, 0), b2, voffB);
;             PG8_BAR; PG8_WAIT_L(0); PG8_MMA(0, 1, At, B1); PG8_BAR;
;             PG8_LDA(At, 0, 1); PG8_STAGE(PG8_SA(0, 0), a2, voffA);
;             PG8_BAR; PG8_WAIT_L(0); PG8_MMA(1, 0, At, B0); PG8_BAR; PG8_SCHED;
.LBB0_334:
	v_mov_b64_e32 v[0:1], 0x440
	s_ashr_i32 s23, s22, 31
	v_cmp_lt_i64_e32 vcc, s[16:17], v[0:1]
	s_lshl_b64 s[16:17], s[22:23], 19
	s_add_u32 s24, s28, s16
	s_addc_u32 s25, s29, s17
	s_and_b64 s[16:17], vcc, exec
	s_cselect_b32 s23, s25, s7
	s_cselect_b32 s50, s24, s6
	s_ashr_i32 s21, s20, 31
	s_lshl_b64 s[16:17], s[20:21], 19
	s_add_u32 s26, s30, s16
	s_addc_u32 s27, s31, s17
	s_and_b64 s[16:17], vcc, exec
	s_cselect_b32 s21, s27, s13
	s_cselect_b32 s51, s26, s12
	s_add_u32 s6, s6, 0x40080
	s_addc_u32 s7, s7, 0
	s_add_u32 s54, s12, 0x100
	s_addc_u32 s55, s13, 0
	s_mov_b32 s56, -2
	s_add_u32 s12, s6, 0xfffc0080
	s_addc_u32 s13, s7, -1
	s_add_i32 s57, 0, 0x10000
	v_add_u32_e32 v48, s57, v166
	ds_read_b128 v[144:147], v48
	ds_read_b128 v[148:151], v48 offset:1024
	ds_read_b128 v[152:155], v48 offset:2048
	ds_read_b128 v[156:159], v48 offset:3072
	s_cmp_eq_u32 s56, 12
	s_cselect_b32 s17, s23, s13
	s_cselect_b32 s16, s50, s12
	s_cselect_b32 s13, s21, s55
	s_cselect_b32 s12, s51, s54
	v_lshl_add_u64 v[164:165], s[6:7], 0, v[140:141]
	s_add_i32 m0, s3, 0xc000
	ds_read_b128 v[160:163], v167
	ds_read_b128 v[168:171], v167 offset:1024
	ds_read_b128 v[176:179], v167 offset:2048
	ds_read_b128 v[180:183], v167 offset:3072
	ds_read_b128 v[184:187], v167 offset:4096
	ds_read_b128 v[188:191], v167 offset:5120
	ds_read_b128 v[192:195], v167 offset:6144
	ds_read_b128 v[196:199], v167 offset:7168
	global_load_lds_dwordx4 v[164:165], off
	s_add_i32 m0, s3, 0xe000
	v_lshl_add_u64 v[164:165], s[6:7], 0, v[142:143]
	global_load_lds_dwordx4 v[164:165], off
	s_waitcnt lgkmcnt(8)
	s_barrier
	s_waitcnt lgkmcnt(7)
	v_mfma_f32_16x16x32_bf16 v[126:129], v[144:147], v[160:163], 0
	v_mfma_f32_16x16x32_bf16 v[122:125], v[152:155], v[160:163], 0
	s_waitcnt lgkmcnt(5)
	v_mfma_f32_16x16x32_bf16 v[110:113], v[144:147], v[176:179], 0
	v_mfma_f32_16x16x32_bf16 v[106:109], v[152:155], v[176:179], 0
	s_waitcnt lgkmcnt(3)
	v_mfma_f32_16x16x32_bf16 v[94:97], v[144:147], v[184:187], 0
	v_mfma_f32_16x16x32_bf16 v[90:93], v[152:155], v[184:187], 0
	s_waitcnt lgkmcnt(1)
	v_mfma_f32_16x16x32_bf16 v[78:81], v[144:147], v[192:195], 0
	v_mfma_f32_16x16x32_bf16 v[74:77], v[152:155], v[192:195], 0
	v_mfma_f32_16x16x32_bf16 v[126:129], v[148:151], v[168:171], v[126:129]
	v_mfma_f32_16x16x32_bf16 v[122:125], v[156:159], v[168:171], v[122:125]
	v_mfma_f32_16x16x32_bf16 v[110:113], v[148:151], v[180:183], v[110:113]
	v_mfma_f32_16x16x32_bf16 v[106:109], v[156:159], v[180:183], v[106:109]
	v_mfma_f32_16x16x32_bf16 v[94:97], v[148:151], v[188:191], v[94:97]
	v_mfma_f32_16x16x32_bf16 v[90:93], v[156:159], v[188:191], v[90:93]
	s_waitcnt lgkmcnt(0)
	v_mfma_f32_16x16x32_bf16 v[78:81], v[148:151], v[196:199], v[78:81]
	v_mfma_f32_16x16x32_bf16 v[74:77], v[156:159], v[196:199], v[74:77]
	s_barrier
	s_add_i32 s59, 0, 0x14000
	s_add_i32 s57, s57, s34
	v_add_u32_e32 v48, s59, v166
	v_lshl_add_u64 v[164:165], s[12:13], 0, v[134:135]
	s_mov_b32 m0, s57
	ds_read_b128 v[200:203], v48
	ds_read_b128 v[204:207], v48 offset:1024
	ds_read_b128 v[208:211], v48 offset:2048
	ds_read_b128 v[212:215], v48 offset:3072
	global_load_lds_dwordx4 v[164:165], off
	s_add_i32 m0, s57, 0x2000
	v_lshl_add_u64 v[172:173], s[12:13], 0, v[130:131]
	global_load_lds_dwordx4 v[172:173], off
	s_barrier
	s_waitcnt lgkmcnt(3)
	v_mfma_f32_16x16x32_bf16 v[118:121], v[200:203], v[160:163], 0
	s_waitcnt lgkmcnt(1)
	v_mfma_f32_16x16x32_bf16 v[114:117], v[208:211], v[160:163], 0
	v_mfma_f32_16x16x32_bf16 v[102:105], v[200:203], v[176:179], 0
	v_mfma_f32_16x16x32_bf16 v[98:101], v[208:211], v[176:179], 0
	v_mfma_f32_16x16x32_bf16 v[86:89], v[200:203], v[184:187], 0
	v_mfma_f32_16x16x32_bf16 v[82:85], v[208:211], v[184:187], 0
	v_mfma_f32_16x16x32_bf16 v[70:73], v[200:203], v[192:195], 0
	v_mfma_f32_16x16x32_bf16 v[66:69], v[208:211], v[192:195], 0
	v_mfma_f32_16x16x32_bf16 v[118:121], v[204:207], v[168:171], v[118:121]
	s_waitcnt lgkmcnt(0)
	v_mfma_f32_16x16x32_bf16 v[114:117], v[212:215], v[168:171], v[114:117]
	v_mfma_f32_16x16x32_bf16 v[102:105], v[204:207], v[180:183], v[102:105]
	v_mfma_f32_16x16x32_bf16 v[98:101], v[212:215], v[180:183], v[98:101]
	v_mfma_f32_16x16x32_bf16 v[86:89], v[204:207], v[188:191], v[86:89]
	v_mfma_f32_16x16x32_bf16 v[82:85], v[212:215], v[188:191], v[82:85]
	v_mfma_f32_16x16x32_bf16 v[70:73], v[204:207], v[196:199], v[70:73]
	v_mfma_f32_16x16x32_bf16 v[66:69], v[212:215], v[196:199], v[66:69]
	s_mov_b32 m0, s3
	v_lshl_add_u64 v[216:217], s[16:17], 0, v[136:137]
	s_barrier
	ds_read_b128 v[160:163], v167 offset:16384
	ds_read_b128 v[168:171], v167 offset:17408
	ds_read_b128 v[176:179], v167 offset:18432
	ds_read_b128 v[180:183], v167 offset:19456
	ds_read_b128 v[184:187], v167 offset:20480
	ds_read_b128 v[188:191], v167 offset:21504
	ds_read_b128 v[192:195], v167 offset:22528
	ds_read_b128 v[196:199], v167 offset:23552
	global_load_lds_dwordx4 v[216:217], off
	s_mov_b32 m0, s36
	v_lshl_add_u64 v[218:219], s[16:17], 0, v[132:133]
	global_load_lds_dwordx4 v[218:219], off
	s_barrier
	s_waitcnt lgkmcnt(7)
	v_mfma_f32_16x16x32_bf16 v[62:65], v[144:147], v[160:163], 0
	v_mfma_f32_16x16x32_bf16 v[58:61], v[152:155], v[160:163], 0
	s_waitcnt lgkmcnt(5)
	v_mfma_f32_16x16x32_bf16 v[44:47], v[144:147], v[176:179], 0
	v_mfma_f32_16x16x32_bf16 v[40:43], v[152:155], v[176:179], 0
	s_waitcnt lgkmcnt(3)
	v_mfma_f32_16x16x32_bf16 v[28:31], v[144:147], v[184:187], 0
	v_mfma_f32_16x16x32_bf16 v[24:27], v[152:155], v[184:187], 0
	s_waitcnt lgkmcnt(1)
	v_mfma_f32_16x16x32_bf16 v[12:15], v[144:147], v[192:195], 0
	v_mfma_f32_16x16x32_bf16 v[8:11], v[152:155], v[192:195], 0
	v_mfma_f32_16x16x32_bf16 v[62:65], v[148:151], v[168:171], v[62:65]
	v_mfma_f32_16x16x32_bf16 v[58:61], v[156:159], v[168:171], v[58:61]
	v_mfma_f32_16x16x32_bf16 v[44:47], v[148:151], v[180:183], v[44:47]
	v_mfma_f32_16x16x32_bf16 v[40:43], v[156:159], v[180:183], v[40:43]
	v_mfma_f32_16x16x32_bf16 v[28:31], v[148:151], v[188:191], v[28:31]
	v_mfma_f32_16x16x32_bf16 v[24:27], v[156:159], v[188:191], v[24:27]
	s_waitcnt lgkmcnt(0)
	v_mfma_f32_16x16x32_bf16 v[12:15], v[148:151], v[196:199], v[12:15]
	v_mfma_f32_16x16x32_bf16 v[8:11], v[156:159], v[196:199], v[8:11]
	s_barrier
; #define PG8_STAGE(bufoff, gbase, voff) do { _Pragma("unroll") for (int _i = 0; _i < 2; ++_i) \
;         __builtin_amdgcn_global_load_lds((const unsigned*)((const char*)(gbase) + (voff)[_i]), (PG8_LAS unsigned*)(lds + (bufoff) + ldsw + _i * 8192), 16, 0, 0); } while (0)
; #define PG8_LDA(dst, b, h) do { _Pragma("unroll") for (int m = 0; m < 4; ++m) _Pragma("unroll") for (int k = 0; k < 2; ++k) dst[m][k] = *(const PG8_LAS bf16x8*)(lds + PG8_SA(b, h) + aoff + m * 2048 + k * 1024); } while (0)
; #define PG8_LDB(dst, b, h) do { _Pragma("unroll") for (int n = 0; n < 2; ++n) _Pragma("unroll") for (int k = 0; k < 2; ++k) dst[n][k] = *(const PG8_LAS bf16x8*)(lds + PG8_SB(b, h) + boff + n * 2048 + k * 1024); } while (0)
; #define PG8_MMA(ai, bj, At, Bt) do { __builtin_amdgcn_s_setprio(1); _Pragma("unroll") for (int m = 0; m < 4; ++m) _Pragma("unroll") for (int n = 0; n < 2; ++n) _Pragma("unroll") for (int k = 0; k < 2; ++k) \
;         acc[ai][bj][m][n] = __builtin_amdgcn_mfma_f32_16x16x32_bf16(Bt[n][k], At[m][k], acc[ai][bj][m][n], 0, 0, 0); __builtin_amdgcn_s_setprio(0); } while (0)
; #define PG8_WAIT_V(n) asm volatile("s_waitcnt vmcnt(" #n ")" ::: "memory")
; #define PG8_WAIT_L(n) asm volatile("s_waitcnt lgkmcnt(" #n ")" ::: "memory")
; #define PG8_BAR __builtin_amdgcn_s_barrier()
; #define PG8_SCHED __builtin_amdgcn_sched_barrier(0)
; template <class Epi, class Sched>
; __device__ __forceinline__ void gemm_phase(PG8_LAS unsigned char* lds, const Gemm g, const Sched& S, const Epi& E) {
;     ...
;             PG8_STAGE(PG8_SB(0, 1), b2 + hstep, voffB);
;             PG8_WAIT_V(6); PG8_BAR; PG8_MMA(1, 1, At, B1); PG8_BAR;
;             PG8_LDB(B0, 1, 0); PG8_SCHED; PG8_LDA(At, 1, 0); PG8_STAGE(PG8_SA(0, 1), a2 + hstep, voffA);
;             PG8_WAIT_L(8); PG8_BAR; PG8_WAIT_L(0); PG8_MMA(0, 0, At, B0); PG8_BAR; PG8_SCHED;
;             PG8_LDB(B1, 1, 1); PG8_STAGE(PG8_SB(1, 0), b3, voffB);
;             PG8_BAR; PG8_WAIT_L(0); PG8_MMA(0, 1, At, B1); PG8_BAR;
;             PG8_LDA(At, 1, 1); PG8_STAGE(PG8_SA(1, 0), a3, voffA);
	s_add_u32 s64, s12, 0x40000
	s_addc_u32 s65, s13, 0
	s_add_i32 s57, s59, s34
	s_mov_b32 m0, s57
	v_lshl_add_u64 v[144:145], s[64:65], 0, v[134:135]
	global_load_lds_dwordx4 v[144:145], off
	s_add_i32 m0, s57, 0x2000
	v_lshl_add_u64 v[144:145], s[64:65], 0, v[130:131]
	global_load_lds_dwordx4 v[144:145], off
	s_waitcnt vmcnt(6)
	s_barrier
	v_mfma_f32_16x16x32_bf16 v[54:57], v[200:203], v[160:163], 0
	v_mfma_f32_16x16x32_bf16 v[50:53], v[208:211], v[160:163], 0
	v_mfma_f32_16x16x32_bf16 v[36:39], v[200:203], v[176:179], 0
	v_mfma_f32_16x16x32_bf16 v[32:35], v[208:211], v[176:179], 0
	v_mfma_f32_16x16x32_bf16 v[20:23], v[200:203], v[184:187], 0
	v_mfma_f32_16x16x32_bf16 v[16:19], v[208:211], v[184:187], 0
	v_mfma_f32_16x16x32_bf16 v[4:7], v[200:203], v[192:195], 0
	v_mfma_f32_16x16x32_bf16 v[0:3], v[208:211], v[192:195], 0
	v_mfma_f32_16x16x32_bf16 v[54:57], v[204:207], v[168:171], v[54:57]
	v_mfma_f32_16x16x32_bf16 v[50:53], v[212:215], v[168:171], v[50:53]
	v_mfma_f32_16x16x32_bf16 v[36:39], v[204:207], v[180:183], v[36:39]
	v_mfma_f32_16x16x32_bf16 v[32:35], v[212:215], v[180:183], v[32:35]
	v_mfma_f32_16x16x32_bf16 v[20:23], v[204:207], v[188:191], v[20:23]
	v_mfma_f32_16x16x32_bf16 v[16:19], v[212:215], v[188:191], v[16:19]
	v_mfma_f32_16x16x32_bf16 v[4:7], v[204:207], v[196:199], v[4:7]
	v_mfma_f32_16x16x32_bf16 v[0:3], v[212:215], v[196:199], v[0:3]
	s_add_i32 s57, 0, 0x18000
	v_add_u32_e32 v48, s57, v166
	s_barrier
	ds_read_b128 v[144:147], v48
	ds_read_b128 v[148:151], v48 offset:1024
	ds_read_b128 v[152:155], v48 offset:2048
	ds_read_b128 v[156:159], v48 offset:3072
	s_add_u32 s16, s16, 0x40000
	s_addc_u32 s17, s17, 0
	s_mov_b32 m0, s37
	v_lshl_add_u64 v[200:201], s[16:17], 0, v[136:137]
	ds_read_b128 v[160:163], v167 offset:32768
	ds_read_b128 v[168:171], v167 offset:33792
	ds_read_b128 v[176:179], v167 offset:34816
	ds_read_b128 v[180:183], v167 offset:35840
	ds_read_b128 v[184:187], v167 offset:36864
	ds_read_b128 v[188:191], v167 offset:37888
	ds_read_b128 v[192:195], v167 offset:38912
	ds_read_b128 v[196:199], v167 offset:39936
	global_load_lds_dwordx4 v[200:201], off
	s_mov_b32 m0, s38
	v_lshl_add_u64 v[200:201], s[16:17], 0, v[132:133]
	global_load_lds_dwordx4 v[200:201], off
	s_waitcnt lgkmcnt(8)
	s_barrier
	s_waitcnt lgkmcnt(7)
	v_mfma_f32_16x16x32_bf16 v[126:129], v[144:147], v[160:163], v[126:129]
	v_mfma_f32_16x16x32_bf16 v[122:125], v[152:155], v[160:163], v[122:125]
	s_waitcnt lgkmcnt(5)
	v_mfma_f32_16x16x32_bf16 v[110:113], v[144:147], v[176:179], v[110:113]
	v_mfma_f32_16x16x32_bf16 v[106:109], v[152:155], v[176:179], v[106:109]
	s_waitcnt lgkmcnt(3)
	v_mfma_f32_16x16x32_bf16 v[94:97], v[144:147], v[184:187], v[94:97]
	v_mfma_f32_16x16x32_bf16 v[90:93], v[152:155], v[184:187], v[90:93]
	s_waitcnt lgkmcnt(1)
	v_mfma_f32_16x16x32_bf16 v[78:81], v[144:147], v[192:195], v[78:81]
	v_mfma_f32_16x16x32_bf16 v[74:77], v[152:155], v[192:195], v[74:77]
	v_mfma_f32_16x16x32_bf16 v[126:129], v[148:151], v[168:171], v[126:129]
	v_mfma_f32_16x16x32_bf16 v[122:125], v[156:159], v[168:171], v[122:125]
	v_mfma_f32_16x16x32_bf16 v[110:113], v[148:151], v[180:183], v[110:113]
	v_mfma_f32_16x16x32_bf16 v[106:109], v[156:159], v[180:183], v[106:109]
	v_mfma_f32_16x16x32_bf16 v[94:97], v[148:151], v[188:191], v[94:97]
	v_mfma_f32_16x16x32_bf16 v[90:93], v[156:159], v[188:191], v[90:93]
	s_waitcnt lgkmcnt(0)
	v_mfma_f32_16x16x32_bf16 v[78:81], v[148:151], v[196:199], v[78:81]
	v_mfma_f32_16x16x32_bf16 v[74:77], v[156:159], v[196:199], v[74:77]
	s_barrier
	s_add_i32 s16, 0, 0x1c000
	s_add_i32 s17, s57, s34
	v_add_u32_e32 v48, s16, v166
	v_lshl_add_u64 v[164:165], v[164:165], 0, s[0:1]
	s_mov_b32 m0, s17
	ds_read_b128 v[200:203], v48
	ds_read_b128 v[204:207], v48 offset:1024
	ds_read_b128 v[208:211], v48 offset:2048
	ds_read_b128 v[212:215], v48 offset:3072
	global_load_lds_dwordx4 v[164:165], off
	s_add_i32 m0, s17, 0x2000
	v_lshl_add_u64 v[164:165], v[172:173], 0, s[0:1]
	global_load_lds_dwordx4 v[164:165], off
	s_barrier
	s_waitcnt lgkmcnt(3)
	v_mfma_f32_16x16x32_bf16 v[118:121], v[200:203], v[160:163], v[118:121]
	s_waitcnt lgkmcnt(1)
	v_mfma_f32_16x16x32_bf16 v[114:117], v[208:211], v[160:163], v[114:117]
	v_mfma_f32_16x16x32_bf16 v[102:105], v[200:203], v[176:179], v[102:105]
	v_mfma_f32_16x16x32_bf16 v[98:101], v[208:211], v[176:179], v[98:101]
	v_mfma_f32_16x16x32_bf16 v[86:89], v[200:203], v[184:187], v[86:89]
	v_mfma_f32_16x16x32_bf16 v[82:85], v[208:211], v[184:187], v[82:85]
	v_mfma_f32_16x16x32_bf16 v[70:73], v[200:203], v[192:195], v[70:73]
	v_mfma_f32_16x16x32_bf16 v[66:69], v[208:211], v[192:195], v[66:69]
	v_mfma_f32_16x16x32_bf16 v[118:121], v[204:207], v[168:171], v[118:121]
	s_waitcnt lgkmcnt(0)
	v_mfma_f32_16x16x32_bf16 v[114:117], v[212:215], v[168:171], v[114:117]
	v_mfma_f32_16x16x32_bf16 v[102:105], v[204:207], v[180:183], v[102:105]
	v_mfma_f32_16x16x32_bf16 v[98:101], v[212:215], v[180:183], v[98:101]
	v_mfma_f32_16x16x32_bf16 v[86:89], v[204:207], v[188:191], v[86:89]
	v_mfma_f32_16x16x32_bf16 v[82:85], v[212:215], v[188:191], v[82:85]
	v_mfma_f32_16x16x32_bf16 v[70:73], v[204:207], v[196:199], v[70:73]
	v_mfma_f32_16x16x32_bf16 v[66:69], v[212:215], v[196:199], v[66:69]
	s_mov_b32 m0, s39
	v_lshl_add_u64 v[164:165], v[216:217], 0, s[0:1]
	s_barrier
	ds_read_b128 v[160:163], v167 offset:49152
	ds_read_b128 v[168:171], v167 offset:50176
	ds_read_b128 v[176:179], v167 offset:51200
	ds_read_b128 v[180:183], v167 offset:52224
	ds_read_b128 v[184:187], v167 offset:53248
	ds_read_b128 v[188:191], v167 offset:54272
	ds_read_b128 v[192:195], v167 offset:55296
	ds_read_b128 v[196:199], v167 offset:56320
	global_load_lds_dwordx4 v[164:165], off
	s_mov_b32 m0, s42
	v_lshl_add_u64 v[164:165], v[218:219], 0, s[0:1]
	global_load_lds_dwordx4 v[164:165], off
	s_barrier
; #define PG8_STAGE(bufoff, gbase, voff) do { _Pragma("unroll") for (int _i = 0; _i < 2; ++_i) \
;         __builtin_amdgcn_global_load_lds((const unsigned*)((const char*)(gbase) + (voff)[_i]), (PG8_LAS unsigned*)(lds + (bufoff) + ldsw + _i * 8192), 16, 0, 0); } while (0)
; #define PG8_LDA(dst, b, h) do { _Pragma("unroll") for (int m = 0; m < 4; ++m) _Pragma("unroll") for (int k = 0; k < 2; ++k) dst[m][k] = *(const PG8_LAS bf16x8*)(lds + PG8_SA(b, h) + aoff + m * 2048 + k * 1024); } while (0)
; #define PG8_LDB(dst, b, h) do { _Pragma("unroll") for (int n = 0; n < 2; ++n) _Pragma("unroll") for (int k = 0; k < 2; ++k) dst[n][k] = *(const PG8_LAS bf16x8*)(lds + PG8_SB(b, h) + boff + n * 2048 + k * 1024); } while (0)
; #define PG8_WAIT_V(n) asm volatile("s_waitcnt vmcnt(" #n ")" ::: "memory")
; #define PG8_WAIT_L(n) asm volatile("s_waitcnt lgkmcnt(" #n ")" ::: "memory")
; #define PG8_BAR __builtin_amdgcn_s_barrier()
; #define PG8_SCHED __builtin_amdgcn_sched_barrier(0)
; template <class Epi, class Sched>
; __device__ __forceinline__ void gemm_phase(PG8_LAS unsigned char* lds, const Gemm g, const Sched& S, const Epi& E) {
;     ...
;             PG8_LDB(B0, 0, 0); PG8_SCHED; PG8_LDA(At, 0, 0); PG8_STAGE(PG8_SA(1, 1), a1 + hstep, voffA);
;             PG8_WAIT_L(8); PG8_BAR; PG8_WAIT_L(0); PG8_MMA(0, 0, At, B0); PG8_BAR; PG8_SCHED;
;             PG8_LDB(B1, 0, 1); PG8_STAGE(PG8_SB(0, 0), b2, voffB);
;             PG8_BAR; PG8_WAIT_L(0); PG8_MMA(0, 1, At, B1); PG8_BAR;
;             PG8_LDA(At, 0, 1); PG8_STAGE(PG8_SA(0, 0), a2, voffA);
;             PG8_BAR; PG8_WAIT_L(0); PG8_MMA(1, 0, At, B0); PG8_BAR; PG8_SCHED;
;             PG8_STAGE(PG8_SB(0, 1), b2 + hstep, voffB);
;             PG8_WAIT_V(6); PG8_BAR; PG8_MMA(1, 1, At, B1); PG8_BAR;
;             PG8_LDB(B0, 1, 0); PG8_SCHED; PG8_LDA(At, 1, 0); PG8_STAGE(PG8_SA(0, 1), a2 + hstep, voffA);
;             PG8_WAIT_L(8); PG8_BAR; PG8_WAIT_L(0); PG8_MMA(0, 0, At, B0); PG8_BAR; PG8_SCHED;
;             PG8_LDB(B1, 1, 1); PG8_STAGE(PG8_SB(1, 0), b3, voffB);
;             PG8_BAR; PG8_WAIT_L(0); PG8_MMA(0, 1, At, B1); PG8_BAR;
;             PG8_LDA(At, 1, 1); PG8_STAGE(PG8_SA(1, 0), a3, voffA);
;             PG8_BAR; PG8_WAIT_L(0); PG8_MMA(1, 0, At, B0); PG8_BAR; PG8_SCHED;
;             PG8_STAGE(PG8_SB(1, 1), b3 + hstep, voffB);
;             PG8_WAIT_V(6); PG8_BAR; PG8_MMA(1, 1, At, B1); PG8_BAR;
	s_waitcnt lgkmcnt(7)
	v_mfma_f32_16x16x32_bf16 v[62:65], v[144:147], v[160:163], v[62:65]
	v_mfma_f32_16x16x32_bf16 v[58:61], v[152:155], v[160:163], v[58:61]
	s_waitcnt lgkmcnt(5)
	v_mfma_f32_16x16x32_bf16 v[44:47], v[144:147], v[176:179], v[44:47]
	v_mfma_f32_16x16x32_bf16 v[40:43], v[152:155], v[176:179], v[40:43]
	s_waitcnt lgkmcnt(3)
	v_mfma_f32_16x16x32_bf16 v[28:31], v[144:147], v[184:187], v[28:31]
	v_mfma_f32_16x16x32_bf16 v[24:27], v[152:155], v[184:187], v[24:27]
	s_waitcnt lgkmcnt(1)
	v_mfma_f32_16x16x32_bf16 v[12:15], v[144:147], v[192:195], v[12:15]
	v_mfma_f32_16x16x32_bf16 v[8:11], v[152:155], v[192:195], v[8:11]
	v_mfma_f32_16x16x32_bf16 v[62:65], v[148:151], v[168:171], v[62:65]
	v_mfma_f32_16x16x32_bf16 v[58:61], v[156:159], v[168:171], v[58:61]
	v_mfma_f32_16x16x32_bf16 v[44:47], v[148:151], v[180:183], v[44:47]
	v_mfma_f32_16x16x32_bf16 v[40:43], v[156:159], v[180:183], v[40:43]
	v_mfma_f32_16x16x32_bf16 v[28:31], v[148:151], v[188:191], v[28:31]
	v_mfma_f32_16x16x32_bf16 v[24:27], v[156:159], v[188:191], v[24:27]
	s_waitcnt lgkmcnt(0)
	v_mfma_f32_16x16x32_bf16 v[12:15], v[148:151], v[196:199], v[12:15]
	v_mfma_f32_16x16x32_bf16 v[8:11], v[156:159], v[196:199], v[8:11]
	s_barrier
	s_add_u32 s12, s12, 0x40080
	s_addc_u32 s13, s13, 0
	s_add_i32 s16, s16, s34
	s_mov_b32 m0, s16
	v_lshl_add_u64 v[144:145], s[12:13], 0, v[134:135]
	global_load_lds_dwordx4 v[144:145], off
	s_add_i32 m0, s16, 0x2000
	v_lshl_add_u64 v[144:145], s[12:13], 0, v[130:131]
	global_load_lds_dwordx4 v[144:145], off
	s_waitcnt vmcnt(6)
	s_barrier
	v_mfma_f32_16x16x32_bf16 v[54:57], v[200:203], v[160:163], v[54:57]
	v_mfma_f32_16x16x32_bf16 v[50:53], v[208:211], v[160:163], v[50:53]
	v_mfma_f32_16x16x32_bf16 v[36:39], v[200:203], v[176:179], v[36:39]
	v_mfma_f32_16x16x32_bf16 v[32:35], v[208:211], v[176:179], v[32:35]
	v_mfma_f32_16x16x32_bf16 v[20:23], v[200:203], v[184:187], v[20:23]
	v_mfma_f32_16x16x32_bf16 v[16:19], v[208:211], v[184:187], v[16:19]
	v_mfma_f32_16x16x32_bf16 v[4:7], v[200:203], v[192:195], v[4:7]
	v_mfma_f32_16x16x32_bf16 v[0:3], v[208:211], v[192:195], v[0:3]
	v_mfma_f32_16x16x32_bf16 v[54:57], v[204:207], v[168:171], v[54:57]
	v_mfma_f32_16x16x32_bf16 v[50:53], v[212:215], v[168:171], v[50:53]
	v_mfma_f32_16x16x32_bf16 v[36:39], v[204:207], v[180:183], v[36:39]
	v_mfma_f32_16x16x32_bf16 v[32:35], v[212:215], v[180:183], v[32:35]
	v_mfma_f32_16x16x32_bf16 v[20:23], v[204:207], v[188:191], v[20:23]
	v_mfma_f32_16x16x32_bf16 v[16:19], v[212:215], v[188:191], v[16:19]
	v_mfma_f32_16x16x32_bf16 v[4:7], v[204:207], v[196:199], v[4:7]
	v_mfma_f32_16x16x32_bf16 v[0:3], v[212:215], v[196:199], v[0:3]
	s_add_i32 s56, s56, 2
	s_add_u32 s6, s6, 0x100
	s_addc_u32 s7, s7, 0
	s_add_u32 s54, s54, 0x100
	s_addc_u32 s55, s55, 0
	s_cmp_gt_u32 s56, 13
	s_barrier
	s_cbranch_scc1 .Lkpeel_exit_335
.LBB0_335:
	s_add_u32 s12, s6, 0xfffc0080
	s_addc_u32 s13, s7, -1
	s_add_i32 s57, 0, 0x10000
	v_add_u32_e32 v48, s57, v166
	ds_read_b128 v[144:147], v48
	ds_read_b128 v[148:151], v48 offset:1024
	ds_read_b128 v[152:155], v48 offset:2048
	ds_read_b128 v[156:159], v48 offset:3072
	s_cmp_eq_u32 s56, 12
	s_cselect_b32 s17, s23, s13
	s_cselect_b32 s16, s50, s12
	s_cselect_b32 s13, s21, s55
	s_cselect_b32 s12, s51, s54
	v_lshl_add_u64 v[164:165], s[6:7], 0, v[140:141]
	s_add_i32 m0, s3, 0xc000
	ds_read_b128 v[160:163], v167
	ds_read_b128 v[168:171], v167 offset:1024
	ds_read_b128 v[176:179], v167 offset:2048
	ds_read_b128 v[180:183], v167 offset:3072
	ds_read_b128 v[184:187], v167 offset:4096
	ds_read_b128 v[188:191], v167 offset:5120
	ds_read_b128 v[192:195], v167 offset:6144
	ds_read_b128 v[196:199], v167 offset:7168
	global_load_lds_dwordx4 v[164:165], off
	s_add_i32 m0, s3, 0xe000
	v_lshl_add_u64 v[164:165], s[6:7], 0, v[142:143]
	global_load_lds_dwordx4 v[164:165], off
	s_waitcnt lgkmcnt(8)
	s_barrier
	s_waitcnt lgkmcnt(7)
	v_mfma_f32_16x16x32_bf16 v[126:129], v[144:147], v[160:163], v[126:129]
	v_mfma_f32_16x16x32_bf16 v[122:125], v[152:155], v[160:163], v[122:125]
	s_waitcnt lgkmcnt(5)
	v_mfma_f32_16x16x32_bf16 v[110:113], v[144:147], v[176:179], v[110:113]
	v_mfma_f32_16x16x32_bf16 v[106:109], v[152:155], v[176:179], v[106:109]
	s_waitcnt lgkmcnt(3)
	v_mfma_f32_16x16x32_bf16 v[94:97], v[144:147], v[184:187], v[94:97]
	v_mfma_f32_16x16x32_bf16 v[90:93], v[152:155], v[184:187], v[90:93]
	s_waitcnt lgkmcnt(1)
	v_mfma_f32_16x16x32_bf16 v[78:81], v[144:147], v[192:195], v[78:81]
	v_mfma_f32_16x16x32_bf16 v[74:77], v[152:155], v[192:195], v[74:77]
	v_mfma_f32_16x16x32_bf16 v[126:129], v[148:151], v[168:171], v[126:129]
	v_mfma_f32_16x16x32_bf16 v[122:125], v[156:159], v[168:171], v[122:125]
	v_mfma_f32_16x16x32_bf16 v[110:113], v[148:151], v[180:183], v[110:113]
	v_mfma_f32_16x16x32_bf16 v[106:109], v[156:159], v[180:183], v[106:109]
	v_mfma_f32_16x16x32_bf16 v[94:97], v[148:151], v[188:191], v[94:97]
	v_mfma_f32_16x16x32_bf16 v[90:93], v[156:159], v[188:191], v[90:93]
	s_waitcnt lgkmcnt(0)
	v_mfma_f32_16x16x32_bf16 v[78:81], v[148:151], v[196:199], v[78:81]
	v_mfma_f32_16x16x32_bf16 v[74:77], v[156:159], v[196:199], v[74:77]
	s_barrier
	s_add_i32 s59, 0, 0x14000
	s_add_i32 s57, s57, s34
	v_add_u32_e32 v48, s59, v166
	v_lshl_add_u64 v[164:165], s[12:13], 0, v[134:135]
	s_mov_b32 m0, s57
	ds_read_b128 v[200:203], v48
	ds_read_b128 v[204:207], v48 offset:1024
	ds_read_b128 v[208:211], v48 offset:2048
	ds_read_b128 v[212:215], v48 offset:3072
	global_load_lds_dwordx4 v[164:165], off
	s_add_i32 m0, s57, 0x2000
	v_lshl_add_u64 v[172:173], s[12:13], 0, v[130:131]
	global_load_lds_dwordx4 v[172:173], off
	s_barrier
; #define PG8_STAGE(bufoff, gbase, voff) do { _Pragma("unroll") for (int _i = 0; _i < 2; ++_i) \
;         __builtin_amdgcn_global_load_lds((const unsigned*)((const char*)(gbase) + (voff)[_i]), (PG8_LAS unsigned*)(lds + (bufoff) + ldsw + _i * 8192), 16, 0, 0); } while (0)
; #define PG8_LDA(dst, b, h) do { _Pragma("unroll") for (int m = 0; m < 4; ++m) _Pragma("unroll") for (int k = 0; k < 2; ++k) dst[m][k] = *(const PG8_LAS bf16x8*)(lds + PG8_SA(b, h) + aoff + m * 2048 + k * 1024); } while (0)
; #define PG8_LDB(dst, b, h) do { _Pragma("unroll") for (int n = 0; n < 2; ++n) _Pragma("unroll") for (int k = 0; k < 2; ++k) dst[n][k] = *(const PG8_LAS bf16x8*)(lds + PG8_SB(b, h) + boff + n * 2048 + k * 1024); } while (0)
; #define PG8_MMA(ai, bj, At, Bt) do { __builtin_amdgcn_s_setprio(1); _Pragma("unroll") for (int m = 0; m < 4; ++m) _Pragma("unroll") for (int n = 0; n < 2; ++n) _Pragma("unroll") for (int k = 0; k < 2; ++k) \
;         acc[ai][bj][m][n] = __builtin_amdgcn_mfma_f32_16x16x32_bf16(Bt[n][k], At[m][k], acc[ai][bj][m][n], 0, 0, 0); __builtin_amdgcn_s_setprio(0); } while (0)
; #define PG8_WAIT_V(n) asm volatile("s_waitcnt vmcnt(" #n ")" ::: "memory")
; #define PG8_WAIT_L(n) asm volatile("s_waitcnt lgkmcnt(" #n ")" ::: "memory")
; #define PG8_BAR __builtin_amdgcn_s_barrier()
; #define PG8_SCHED __builtin_amdgcn_sched_barrier(0)
; template <class Epi, class Sched>
; __device__ __forceinline__ void gemm_phase(PG8_LAS unsigned char* lds, const Gemm g, const Sched& S, const Epi& E) {
;     ...
;             PG8_BAR; PG8_WAIT_L(0); PG8_MMA(0, 1, At, B1); PG8_BAR;
;             PG8_LDA(At, 0, 1); PG8_STAGE(PG8_SA(0, 0), a2, voffA);
;             PG8_BAR; PG8_WAIT_L(0); PG8_MMA(1, 0, At, B0); PG8_BAR; PG8_SCHED;
;             PG8_STAGE(PG8_SB(0, 1), b2 + hstep, voffB);
;             PG8_WAIT_V(6); PG8_BAR; PG8_MMA(1, 1, At, B1); PG8_BAR;
;             PG8_LDB(B0, 1, 0); PG8_SCHED; PG8_LDA(At, 1, 0); PG8_STAGE(PG8_SA(0, 1), a2 + hstep, voffA);
;             PG8_WAIT_L(8); PG8_BAR; PG8_WAIT_L(0); PG8_MMA(0, 0, At, B0); PG8_BAR; PG8_SCHED;
	s_waitcnt lgkmcnt(3)
	v_mfma_f32_16x16x32_bf16 v[118:121], v[200:203], v[160:163], v[118:121]
	s_waitcnt lgkmcnt(1)
	v_mfma_f32_16x16x32_bf16 v[114:117], v[208:211], v[160:163], v[114:117]
	v_mfma_f32_16x16x32_bf16 v[102:105], v[200:203], v[176:179], v[102:105]
	v_mfma_f32_16x16x32_bf16 v[98:101], v[208:211], v[176:179], v[98:101]
	v_mfma_f32_16x16x32_bf16 v[86:89], v[200:203], v[184:187], v[86:89]
	v_mfma_f32_16x16x32_bf16 v[82:85], v[208:211], v[184:187], v[82:85]
	v_mfma_f32_16x16x32_bf16 v[70:73], v[200:203], v[192:195], v[70:73]
	v_mfma_f32_16x16x32_bf16 v[66:69], v[208:211], v[192:195], v[66:69]
	v_mfma_f32_16x16x32_bf16 v[118:121], v[204:207], v[168:171], v[118:121]
	s_waitcnt lgkmcnt(0)
	v_mfma_f32_16x16x32_bf16 v[114:117], v[212:215], v[168:171], v[114:117]
	v_mfma_f32_16x16x32_bf16 v[102:105], v[204:207], v[180:183], v[102:105]
	v_mfma_f32_16x16x32_bf16 v[98:101], v[212:215], v[180:183], v[98:101]
	v_mfma_f32_16x16x32_bf16 v[86:89], v[204:207], v[188:191], v[86:89]
	v_mfma_f32_16x16x32_bf16 v[82:85], v[212:215], v[188:191], v[82:85]
	v_mfma_f32_16x16x32_bf16 v[70:73], v[204:207], v[196:199], v[70:73]
	v_mfma_f32_16x16x32_bf16 v[66:69], v[212:215], v[196:199], v[66:69]
	s_mov_b32 m0, s3
	v_lshl_add_u64 v[216:217], s[16:17], 0, v[136:137]
	s_barrier
	ds_read_b128 v[160:163], v167 offset:16384
	ds_read_b128 v[168:171], v167 offset:17408
	ds_read_b128 v[176:179], v167 offset:18432
	ds_read_b128 v[180:183], v167 offset:19456
	ds_read_b128 v[184:187], v167 offset:20480
	ds_read_b128 v[188:191], v167 offset:21504
	ds_read_b128 v[192:195], v167 offset:22528
	ds_read_b128 v[196:199], v167 offset:23552
	global_load_lds_dwordx4 v[216:217], off
	s_mov_b32 m0, s36
	v_lshl_add_u64 v[218:219], s[16:17], 0, v[132:133]
	global_load_lds_dwordx4 v[218:219], off
	s_barrier
	s_waitcnt lgkmcnt(7)
	v_mfma_f32_16x16x32_bf16 v[62:65], v[144:147], v[160:163], v[62:65]
	v_mfma_f32_16x16x32_bf16 v[58:61], v[152:155], v[160:163], v[58:61]
	s_waitcnt lgkmcnt(5)
	v_mfma_f32_16x16x32_bf16 v[44:47], v[144:147], v[176:179], v[44:47]
	v_mfma_f32_16x16x32_bf16 v[40:43], v[152:155], v[176:179], v[40:43]
	s_waitcnt lgkmcnt(3)
	v_mfma_f32_16x16x32_bf16 v[28:31], v[144:147], v[184:187], v[28:31]
	v_mfma_f32_16x16x32_bf16 v[24:27], v[152:155], v[184:187], v[24:27]
	s_waitcnt lgkmcnt(1)
	v_mfma_f32_16x16x32_bf16 v[12:15], v[144:147], v[192:195], v[12:15]
	v_mfma_f32_16x16x32_bf16 v[8:11], v[152:155], v[192:195], v[8:11]
	v_mfma_f32_16x16x32_bf16 v[62:65], v[148:151], v[168:171], v[62:65]
	v_mfma_f32_16x16x32_bf16 v[58:61], v[156:159], v[168:171], v[58:61]
	v_mfma_f32_16x16x32_bf16 v[44:47], v[148:151], v[180:183], v[44:47]
	v_mfma_f32_16x16x32_bf16 v[40:43], v[156:159], v[180:183], v[40:43]
	v_mfma_f32_16x16x32_bf16 v[28:31], v[148:151], v[188:191], v[28:31]
	v_mfma_f32_16x16x32_bf16 v[24:27], v[156:159], v[188:191], v[24:27]
	s_waitcnt lgkmcnt(0)
	v_mfma_f32_16x16x32_bf16 v[12:15], v[148:151], v[196:199], v[12:15]
	v_mfma_f32_16x16x32_bf16 v[8:11], v[156:159], v[196:199], v[8:11]
	s_barrier
	s_add_u32 s64, s12, 0x40000
	s_addc_u32 s65, s13, 0
	s_add_i32 s57, s59, s34
	s_mov_b32 m0, s57
	v_lshl_add_u64 v[144:145], s[64:65], 0, v[134:135]
	global_load_lds_dwordx4 v[144:145], off
	s_add_i32 m0, s57, 0x2000
	v_lshl_add_u64 v[144:145], s[64:65], 0, v[130:131]
	global_load_lds_dwordx4 v[144:145], off
	s_waitcnt vmcnt(6)
	s_barrier
	v_mfma_f32_16x16x32_bf16 v[54:57], v[200:203], v[160:163], v[54:57]
	v_mfma_f32_16x16x32_bf16 v[50:53], v[208:211], v[160:163], v[50:53]
	v_mfma_f32_16x16x32_bf16 v[36:39], v[200:203], v[176:179], v[36:39]
	v_mfma_f32_16x16x32_bf16 v[32:35], v[208:211], v[176:179], v[32:35]
	v_mfma_f32_16x16x32_bf16 v[20:23], v[200:203], v[184:187], v[20:23]
	v_mfma_f32_16x16x32_bf16 v[16:19], v[208:211], v[184:187], v[16:19]
	v_mfma_f32_16x16x32_bf16 v[4:7], v[200:203], v[192:195], v[4:7]
	v_mfma_f32_16x16x32_bf16 v[0:3], v[208:211], v[192:195], v[0:3]
	v_mfma_f32_16x16x32_bf16 v[54:57], v[204:207], v[168:171], v[54:57]
	v_mfma_f32_16x16x32_bf16 v[50:53], v[212:215], v[168:171], v[50:53]
	v_mfma_f32_16x16x32_bf16 v[36:39], v[204:207], v[180:183], v[36:39]
	v_mfma_f32_16x16x32_bf16 v[32:35], v[212:215], v[180:183], v[32:35]
	v_mfma_f32_16x16x32_bf16 v[20:23], v[204:207], v[188:191], v[20:23]
	v_mfma_f32_16x16x32_bf16 v[16:19], v[212:215], v[188:191], v[16:19]
	v_mfma_f32_16x16x32_bf16 v[4:7], v[204:207], v[196:199], v[4:7]
	v_mfma_f32_16x16x32_bf16 v[0:3], v[212:215], v[196:199], v[0:3]
	s_add_i32 s57, 0, 0x18000
	v_add_u32_e32 v48, s57, v166
	s_barrier
	ds_read_b128 v[144:147], v48
	ds_read_b128 v[148:151], v48 offset:1024
	ds_read_b128 v[152:155], v48 offset:2048
	ds_read_b128 v[156:159], v48 offset:3072
	s_add_u32 s16, s16, 0x40000
	s_addc_u32 s17, s17, 0
	s_mov_b32 m0, s37
	v_lshl_add_u64 v[200:201], s[16:17], 0, v[136:137]
	ds_read_b128 v[160:163], v167 offset:32768
	ds_read_b128 v[168:171], v167 offset:33792
	ds_read_b128 v[176:179], v167 offset:34816
	ds_read_b128 v[180:183], v167 offset:35840
	ds_read_b128 v[184:187], v167 offset:36864
	ds_read_b128 v[188:191], v167 offset:37888
	ds_read_b128 v[192:195], v167 offset:38912
	ds_read_b128 v[196:199], v167 offset:39936
	global_load_lds_dwordx4 v[200:201], off
	s_mov_b32 m0, s38
	v_lshl_add_u64 v[200:201], s[16:17], 0, v[132:133]
	global_load_lds_dwordx4 v[200:201], off
	s_waitcnt lgkmcnt(8)
	s_barrier
; #define PG8_STAGE(bufoff, gbase, voff) do { _Pragma("unroll") for (int _i = 0; _i < 2; ++_i) \
;         __builtin_amdgcn_global_load_lds((const unsigned*)((const char*)(gbase) + (voff)[_i]), (PG8_LAS unsigned*)(lds + (bufoff) + ldsw + _i * 8192), 16, 0, 0); } while (0)
; #define PG8_LDA(dst, b, h) do { _Pragma("unroll") for (int m = 0; m < 4; ++m) _Pragma("unroll") for (int k = 0; k < 2; ++k) dst[m][k] = *(const PG8_LAS bf16x8*)(lds + PG8_SA(b, h) + aoff + m * 2048 + k * 1024); } while (0)
; #define PG8_LDB(dst, b, h) do { _Pragma("unroll") for (int n = 0; n < 2; ++n) _Pragma("unroll") for (int k = 0; k < 2; ++k) dst[n][k] = *(const PG8_LAS bf16x8*)(lds + PG8_SB(b, h) + boff + n * 2048 + k * 1024); } while (0)
; #define PG8_MMA(ai, bj, At, Bt) do { __builtin_amdgcn_s_setprio(1); _Pragma("unroll") for (int m = 0; m < 4; ++m) _Pragma("unroll") for (int n = 0; n < 2; ++n) _Pragma("unroll") for (int k = 0; k < 2; ++k) \
;         acc[ai][bj][m][n] = __builtin_amdgcn_mfma_f32_16x16x32_bf16(Bt[n][k], At[m][k], acc[ai][bj][m][n], 0, 0, 0); __builtin_amdgcn_s_setprio(0); } while (0)
; #define PG8_WAIT_V(n) asm volatile("s_waitcnt vmcnt(" #n ")" ::: "memory")
; #define PG8_WAIT_L(n) asm volatile("s_waitcnt lgkmcnt(" #n ")" ::: "memory")
; #define PG8_BAR __builtin_amdgcn_s_barrier()
; #define PG8_SCHED __builtin_amdgcn_sched_barrier(0)
; template <class Epi, class Sched>
; __device__ __forceinline__ void gemm_phase(PG8_LAS unsigned char* lds, const Gemm g, const Sched& S, const Epi& E) {
;     ...
;             PG8_WAIT_L(8); PG8_BAR; PG8_WAIT_L(0); PG8_MMA(0, 0, At, B0); PG8_BAR; PG8_SCHED;
;             PG8_LDB(B1, 1, 1); PG8_STAGE(PG8_SB(1, 0), b3, voffB);
;             PG8_BAR; PG8_WAIT_L(0); PG8_MMA(0, 1, At, B1); PG8_BAR;
;             PG8_LDA(At, 1, 1); PG8_STAGE(PG8_SA(1, 0), a3, voffA);
;             PG8_BAR; PG8_WAIT_L(0); PG8_MMA(1, 0, At, B0); PG8_BAR; PG8_SCHED;
;             PG8_STAGE(PG8_SB(1, 1), b3 + hstep, voffB);
;             PG8_WAIT_V(6); PG8_BAR; PG8_MMA(1, 1, At, B1); PG8_BAR;
;         }
	s_waitcnt lgkmcnt(7)
	v_mfma_f32_16x16x32_bf16 v[126:129], v[144:147], v[160:163], v[126:129]
	v_mfma_f32_16x16x32_bf16 v[122:125], v[152:155], v[160:163], v[122:125]
	s_waitcnt lgkmcnt(5)
	v_mfma_f32_16x16x32_bf16 v[110:113], v[144:147], v[176:179], v[110:113]
	v_mfma_f32_16x16x32_bf16 v[106:109], v[152:155], v[176:179], v[106:109]
	s_waitcnt lgkmcnt(3)
	v_mfma_f32_16x16x32_bf16 v[94:97], v[144:147], v[184:187], v[94:97]
	v_mfma_f32_16x16x32_bf16 v[90:93], v[152:155], v[184:187], v[90:93]
	s_waitcnt lgkmcnt(1)
	v_mfma_f32_16x16x32_bf16 v[78:81], v[144:147], v[192:195], v[78:81]
	v_mfma_f32_16x16x32_bf16 v[74:77], v[152:155], v[192:195], v[74:77]
	v_mfma_f32_16x16x32_bf16 v[126:129], v[148:151], v[168:171], v[126:129]
	v_mfma_f32_16x16x32_bf16 v[122:125], v[156:159], v[168:171], v[122:125]
	v_mfma_f32_16x16x32_bf16 v[110:113], v[148:151], v[180:183], v[110:113]
	v_mfma_f32_16x16x32_bf16 v[106:109], v[156:159], v[180:183], v[106:109]
	v_mfma_f32_16x16x32_bf16 v[94:97], v[148:151], v[188:191], v[94:97]
	v_mfma_f32_16x16x32_bf16 v[90:93], v[156:159], v[188:191], v[90:93]
	s_waitcnt lgkmcnt(0)
	v_mfma_f32_16x16x32_bf16 v[78:81], v[148:151], v[196:199], v[78:81]
	v_mfma_f32_16x16x32_bf16 v[74:77], v[156:159], v[196:199], v[74:77]
	s_barrier
	s_add_i32 s16, 0, 0x1c000
	s_add_i32 s17, s57, s34
	v_add_u32_e32 v48, s16, v166
	v_lshl_add_u64 v[164:165], v[164:165], 0, s[0:1]
	s_mov_b32 m0, s17
	ds_read_b128 v[200:203], v48
	ds_read_b128 v[204:207], v48 offset:1024
	ds_read_b128 v[208:211], v48 offset:2048
	ds_read_b128 v[212:215], v48 offset:3072
	global_load_lds_dwordx4 v[164:165], off
	s_add_i32 m0, s17, 0x2000
	v_lshl_add_u64 v[164:165], v[172:173], 0, s[0:1]
	global_load_lds_dwordx4 v[164:165], off
	s_barrier
	s_waitcnt lgkmcnt(3)
	v_mfma_f32_16x16x32_bf16 v[118:121], v[200:203], v[160:163], v[118:121]
	s_waitcnt lgkmcnt(1)
	v_mfma_f32_16x16x32_bf16 v[114:117], v[208:211], v[160:163], v[114:117]
	v_mfma_f32_16x16x32_bf16 v[102:105], v[200:203], v[176:179], v[102:105]
	v_mfma_f32_16x16x32_bf16 v[98:101], v[208:211], v[176:179], v[98:101]
	v_mfma_f32_16x16x32_bf16 v[86:89], v[200:203], v[184:187], v[86:89]
	v_mfma_f32_16x16x32_bf16 v[82:85], v[208:211], v[184:187], v[82:85]
	v_mfma_f32_16x16x32_bf16 v[70:73], v[200:203], v[192:195], v[70:73]
	v_mfma_f32_16x16x32_bf16 v[66:69], v[208:211], v[192:195], v[66:69]
	v_mfma_f32_16x16x32_bf16 v[118:121], v[204:207], v[168:171], v[118:121]
	s_waitcnt lgkmcnt(0)
	v_mfma_f32_16x16x32_bf16 v[114:117], v[212:215], v[168:171], v[114:117]
	v_mfma_f32_16x16x32_bf16 v[102:105], v[204:207], v[180:183], v[102:105]
	v_mfma_f32_16x16x32_bf16 v[98:101], v[212:215], v[180:183], v[98:101]
	v_mfma_f32_16x16x32_bf16 v[86:89], v[204:207], v[188:191], v[86:89]
	v_mfma_f32_16x16x32_bf16 v[82:85], v[212:215], v[188:191], v[82:85]
	v_mfma_f32_16x16x32_bf16 v[70:73], v[204:207], v[196:199], v[70:73]
	v_mfma_f32_16x16x32_bf16 v[66:69], v[212:215], v[196:199], v[66:69]
	s_mov_b32 m0, s39
	v_lshl_add_u64 v[164:165], v[216:217], 0, s[0:1]
	s_barrier
	ds_read_b128 v[160:163], v167 offset:49152
	ds_read_b128 v[168:171], v167 offset:50176
	ds_read_b128 v[176:179], v167 offset:51200
	ds_read_b128 v[180:183], v167 offset:52224
	ds_read_b128 v[184:187], v167 offset:53248
	ds_read_b128 v[188:191], v167 offset:54272
	ds_read_b128 v[192:195], v167 offset:55296
	ds_read_b128 v[196:199], v167 offset:56320
	global_load_lds_dwordx4 v[164:165], off
	s_mov_b32 m0, s42
	v_lshl_add_u64 v[164:165], v[218:219], 0, s[0:1]
	global_load_lds_dwordx4 v[164:165], off
	s_barrier
	s_waitcnt lgkmcnt(7)
	v_mfma_f32_16x16x32_bf16 v[62:65], v[144:147], v[160:163], v[62:65]
	v_mfma_f32_16x16x32_bf16 v[58:61], v[152:155], v[160:163], v[58:61]
	s_waitcnt lgkmcnt(5)
	v_mfma_f32_16x16x32_bf16 v[44:47], v[144:147], v[176:179], v[44:47]
	v_mfma_f32_16x16x32_bf16 v[40:43], v[152:155], v[176:179], v[40:43]
	s_waitcnt lgkmcnt(3)
	v_mfma_f32_16x16x32_bf16 v[28:31], v[144:147], v[184:187], v[28:31]
	v_mfma_f32_16x16x32_bf16 v[24:27], v[152:155], v[184:187], v[24:27]
	s_waitcnt lgkmcnt(1)
	v_mfma_f32_16x16x32_bf16 v[12:15], v[144:147], v[192:195], v[12:15]
	v_mfma_f32_16x16x32_bf16 v[8:11], v[152:155], v[192:195], v[8:11]
	v_mfma_f32_16x16x32_bf16 v[62:65], v[148:151], v[168:171], v[62:65]
	v_mfma_f32_16x16x32_bf16 v[58:61], v[156:159], v[168:171], v[58:61]
	v_mfma_f32_16x16x32_bf16 v[44:47], v[148:151], v[180:183], v[44:47]
	v_mfma_f32_16x16x32_bf16 v[40:43], v[156:159], v[180:183], v[40:43]
	v_mfma_f32_16x16x32_bf16 v[28:31], v[148:151], v[188:191], v[28:31]
	v_mfma_f32_16x16x32_bf16 v[24:27], v[156:159], v[188:191], v[24:27]
	s_waitcnt lgkmcnt(0)
	v_mfma_f32_16x16x32_bf16 v[12:15], v[148:151], v[196:199], v[12:15]
	v_mfma_f32_16x16x32_bf16 v[8:11], v[156:159], v[196:199], v[8:11]
	s_barrier
	s_add_u32 s12, s12, 0x40080
	s_addc_u32 s13, s13, 0
	s_add_i32 s16, s16, s34
	s_mov_b32 m0, s16
	v_lshl_add_u64 v[144:145], s[12:13], 0, v[134:135]
	global_load_lds_dwordx4 v[144:145], off
	s_add_i32 m0, s16, 0x2000
	v_lshl_add_u64 v[144:145], s[12:13], 0, v[130:131]
	global_load_lds_dwordx4 v[144:145], off
	s_waitcnt vmcnt(6)
	s_barrier
	v_mfma_f32_16x16x32_bf16 v[54:57], v[200:203], v[160:163], v[54:57]
	v_mfma_f32_16x16x32_bf16 v[50:53], v[208:211], v[160:163], v[50:53]
	v_mfma_f32_16x16x32_bf16 v[36:39], v[200:203], v[176:179], v[36:39]
	v_mfma_f32_16x16x32_bf16 v[32:35], v[208:211], v[176:179], v[32:35]
	v_mfma_f32_16x16x32_bf16 v[20:23], v[200:203], v[184:187], v[20:23]
	v_mfma_f32_16x16x32_bf16 v[16:19], v[208:211], v[184:187], v[16:19]
	v_mfma_f32_16x16x32_bf16 v[4:7], v[200:203], v[192:195], v[4:7]
	v_mfma_f32_16x16x32_bf16 v[0:3], v[208:211], v[192:195], v[0:3]
	v_mfma_f32_16x16x32_bf16 v[54:57], v[204:207], v[168:171], v[54:57]
	v_mfma_f32_16x16x32_bf16 v[50:53], v[212:215], v[168:171], v[50:53]
	v_mfma_f32_16x16x32_bf16 v[36:39], v[204:207], v[180:183], v[36:39]
	v_mfma_f32_16x16x32_bf16 v[32:35], v[212:215], v[180:183], v[32:35]
	v_mfma_f32_16x16x32_bf16 v[20:23], v[204:207], v[188:191], v[20:23]
	v_mfma_f32_16x16x32_bf16 v[16:19], v[212:215], v[188:191], v[16:19]
	v_mfma_f32_16x16x32_bf16 v[4:7], v[204:207], v[196:199], v[4:7]
	v_mfma_f32_16x16x32_bf16 v[0:3], v[212:215], v[196:199], v[0:3]
	s_add_i32 s56, s56, 2
	s_add_u32 s6, s6, 0x100
	s_addc_u32 s7, s7, 0
	s_add_u32 s54, s54, 0x100
	s_addc_u32 s55, s55, 0
	s_cmp_gt_u32 s56, 13
	s_barrier
	s_cbranch_scc0 .LBB0_335

; #define PG8_STAGE(bufoff, gbase, voff) do { _Pragma("unroll") for (int _i = 0; _i < 2; ++_i) \
;         __builtin_amdgcn_global_load_lds((const unsigned*)((const char*)(gbase) + (voff)[_i]), (PG8_LAS unsigned*)(lds + (bufoff) + ldsw + _i * 8192), 16, 0, 0); } while (0)
; #define PG8_LDA(dst, b, h) do { _Pragma("unroll") for (int m = 0; m < 4; ++m) _Pragma("unroll") for (int k = 0; k < 2; ++k) dst[m][k] = *(const PG8_LAS bf16x8*)(lds + PG8_SA(b, h) + aoff + m * 2048 + k * 1024); } while (0)
; #define PG8_LDB(dst, b, h) do { _Pragma("unroll") for (int n = 0; n < 2; ++n) _Pragma("unroll") for (int k = 0; k < 2; ++k) dst[n][k] = *(const PG8_LAS bf16x8*)(lds + PG8_SB(b, h) + boff + n * 2048 + k * 1024); } while (0)
; #define PG8_WAIT_L(n) asm volatile("s_waitcnt lgkmcnt(" #n ")" ::: "memory")
; #define PG8_BAR __builtin_amdgcn_s_barrier()
; #define PG8_SCHED __builtin_amdgcn_sched_barrier(0)
; template <class Epi, class Sched>
; __device__ __forceinline__ void gemm_phase(PG8_LAS unsigned char* lds, const Gemm g, const Sched& S, const Epi& E) {
;     ...
;         const bool has_next = S.next(ui + 1, nxt);
;         const char* nA = has_next ? (const char*)g.A + (size_t)nxt.pm * tstepA + (size_t)nxt.kc * cstep : cA; const char* nB = has_next ? (const char*)g.Bt + (size_t)nxt.pn * tstep + (size_t)nxt.kc * cstep : cB;
;         for (int t = 0; t < nt; t += 2) {
;             const bool last = (t == nt - 2);
;             const char* a1 = cA + (size_t)(t + 1) * kstep;
;             const char* a2 = last ? nA : cA + (size_t)(t + 2) * kstep; const char* b2 = last ? nB : cB + (size_t)(t + 2) * kstep;
;             const char* a3 = a2 + kstep; const char* b3 = b2 + kstep;
;             if (last && has_next) S.a_ready(nxt);
;             PG8_LDB(B0, 0, 0); PG8_SCHED; PG8_LDA(At, 0, 0); PG8_STAGE(PG8_SA(1, 1), a1 + hstep, voffA);
;             PG8_WAIT_L(8); PG8_BAR; PG8_WAIT_L(0); PG8_MMA(0, 0, At, B0); PG8_BAR; PG8_SCHED;
;             PG8_LDB(B1, 0, 1); PG8_STAGE(PG8_SB(0, 0), b2, voffB);
;             PG8_BAR; PG8_WAIT_L(0); PG8_MMA(0, 1, At, B1); PG8_BAR;
;             PG8_LDA(At, 0, 1); PG8_STAGE(PG8_SA(0, 0), a2, voffA);
;             PG8_BAR; PG8_WAIT_L(0); PG8_MMA(1, 0, At, B0); PG8_BAR; PG8_SCHED;
.LBB0_387:
	s_ashr_i32 s39, s38, 31
	s_lshl_b64 s[16:17], s[38:39], 19
	v_readlane_b32 s3, v254, 53
	s_add_u32 s94, s3, s16
	v_readlane_b32 s3, v254, 54
	s_addc_u32 s95, s3, s17
	s_and_b64 s[16:17], s[62:63], exec
	s_cselect_b32 s3, s95, s13
	s_cselect_b32 s26, s94, s12
	s_add_u32 s6, s6, 0x40080
	s_addc_u32 s7, s7, 0
	s_add_u32 s27, s12, 0x100
	s_addc_u32 s29, s13, 0
	s_mov_b32 s30, -2
	s_add_u32 s12, s6, 0xfffc0080
	s_addc_u32 s13, s7, -1
	s_add_i32 s22, 0, 0x10000
	v_add_u32_e32 v48, s22, v250
	ds_read_b128 v[130:133], v48
	ds_read_b128 v[134:137], v48 offset:1024
	ds_read_b128 v[138:141], v48 offset:2048
	ds_read_b128 v[142:145], v48 offset:3072
	s_cmp_eq_u32 s30, 12
	s_cselect_b32 s17, s9, s13
	s_cselect_b32 s16, s8, s12
	s_cselect_b32 s13, s3, s29
	s_cselect_b32 s12, s26, s27
	v_lshl_add_u64 v[192:193], s[6:7], 0, v[184:185]
	s_add_i32 m0, s37, 0xc000
	ds_read_b128 v[146:149], v242
	ds_read_b128 v[150:153], v242 offset:1024
	ds_read_b128 v[154:157], v242 offset:2048
	ds_read_b128 v[158:161], v242 offset:3072
	ds_read_b128 v[162:165], v242 offset:4096
	ds_read_b128 v[166:169], v242 offset:5120
	ds_read_b128 v[170:173], v242 offset:6144
	ds_read_b128 v[188:191], v242 offset:7168
	global_load_lds_dwordx4 v[192:193], off
	s_add_i32 m0, s37, 0xe000
	v_lshl_add_u64 v[192:193], s[6:7], 0, v[186:187]
	global_load_lds_dwordx4 v[192:193], off
	s_waitcnt lgkmcnt(8)
	s_barrier
	s_waitcnt lgkmcnt(7)
	v_mfma_f32_16x16x32_bf16 v[126:129], v[130:133], v[146:149], 0
	v_mfma_f32_16x16x32_bf16 v[62:65], v[138:141], v[146:149], 0
	s_waitcnt lgkmcnt(5)
	v_mfma_f32_16x16x32_bf16 v[118:121], v[130:133], v[154:157], 0
	v_mfma_f32_16x16x32_bf16 v[54:57], v[138:141], v[154:157], 0
	s_waitcnt lgkmcnt(3)
	v_mfma_f32_16x16x32_bf16 v[110:113], v[130:133], v[162:165], 0
	v_mfma_f32_16x16x32_bf16 v[44:47], v[138:141], v[162:165], 0
	s_waitcnt lgkmcnt(1)
	v_mfma_f32_16x16x32_bf16 v[102:105], v[130:133], v[170:173], 0
	v_mfma_f32_16x16x32_bf16 v[36:39], v[138:141], v[170:173], 0
	v_mfma_f32_16x16x32_bf16 v[126:129], v[134:137], v[150:153], v[126:129]
	v_mfma_f32_16x16x32_bf16 v[62:65], v[142:145], v[150:153], v[62:65]
	v_mfma_f32_16x16x32_bf16 v[118:121], v[134:137], v[158:161], v[118:121]
	v_mfma_f32_16x16x32_bf16 v[54:57], v[142:145], v[158:161], v[54:57]
	v_mfma_f32_16x16x32_bf16 v[110:113], v[134:137], v[166:169], v[110:113]
	v_mfma_f32_16x16x32_bf16 v[44:47], v[142:145], v[166:169], v[44:47]
	s_waitcnt lgkmcnt(0)
	v_mfma_f32_16x16x32_bf16 v[102:105], v[134:137], v[188:191], v[102:105]
	v_mfma_f32_16x16x32_bf16 v[36:39], v[142:145], v[188:191], v[36:39]
	s_barrier
	s_add_i32 s31, 0, 0x14000
	s_add_i32 s22, s22, s36
	v_add_u32_e32 v48, s31, v250
	v_lshl_add_u64 v[208:209], s[12:13], 0, v[178:179]
	s_mov_b32 m0, s22
	ds_read_b128 v[192:195], v48
	ds_read_b128 v[196:199], v48 offset:1024
	ds_read_b128 v[200:203], v48 offset:2048
	ds_read_b128 v[204:207], v48 offset:3072
	global_load_lds_dwordx4 v[208:209], off
	s_add_i32 m0, s22, 0x2000
	v_lshl_add_u64 v[210:211], s[12:13], 0, v[182:183]
	global_load_lds_dwordx4 v[210:211], off
	s_barrier
	s_waitcnt lgkmcnt(3)
	v_mfma_f32_16x16x32_bf16 v[122:125], v[192:195], v[146:149], 0
	s_waitcnt lgkmcnt(1)
	v_mfma_f32_16x16x32_bf16 v[58:61], v[200:203], v[146:149], 0
	v_mfma_f32_16x16x32_bf16 v[114:117], v[192:195], v[154:157], 0
	v_mfma_f32_16x16x32_bf16 v[50:53], v[200:203], v[154:157], 0
	v_mfma_f32_16x16x32_bf16 v[106:109], v[192:195], v[162:165], 0
	v_mfma_f32_16x16x32_bf16 v[40:43], v[200:203], v[162:165], 0
	v_mfma_f32_16x16x32_bf16 v[98:101], v[192:195], v[170:173], 0
	v_mfma_f32_16x16x32_bf16 v[32:35], v[200:203], v[170:173], 0
	v_mfma_f32_16x16x32_bf16 v[122:125], v[196:199], v[150:153], v[122:125]
	s_waitcnt lgkmcnt(0)
	v_mfma_f32_16x16x32_bf16 v[58:61], v[204:207], v[150:153], v[58:61]
	v_mfma_f32_16x16x32_bf16 v[114:117], v[196:199], v[158:161], v[114:117]
	v_mfma_f32_16x16x32_bf16 v[50:53], v[204:207], v[158:161], v[50:53]
	v_mfma_f32_16x16x32_bf16 v[106:109], v[196:199], v[166:169], v[106:109]
	v_mfma_f32_16x16x32_bf16 v[40:43], v[204:207], v[166:169], v[40:43]
	v_mfma_f32_16x16x32_bf16 v[98:101], v[196:199], v[188:191], v[98:101]
	v_mfma_f32_16x16x32_bf16 v[32:35], v[204:207], v[188:191], v[32:35]
	s_mov_b32 m0, s37
	v_lshl_add_u64 v[212:213], s[16:17], 0, v[176:177]
	s_barrier
	ds_read_b128 v[146:149], v242 offset:16384
	ds_read_b128 v[150:153], v242 offset:17408
	ds_read_b128 v[154:157], v242 offset:18432
	ds_read_b128 v[158:161], v242 offset:19456
	ds_read_b128 v[162:165], v242 offset:20480
	ds_read_b128 v[166:169], v242 offset:21504
	ds_read_b128 v[170:173], v242 offset:22528
	ds_read_b128 v[188:191], v242 offset:23552
	global_load_lds_dwordx4 v[212:213], off
	s_mov_b32 m0, s10
	v_lshl_add_u64 v[214:215], s[16:17], 0, v[180:181]
	global_load_lds_dwordx4 v[214:215], off
	s_barrier
	s_waitcnt lgkmcnt(7)
	v_mfma_f32_16x16x32_bf16 v[94:97], v[130:133], v[146:149], 0
	v_mfma_f32_16x16x32_bf16 v[28:31], v[138:141], v[146:149], 0
	s_waitcnt lgkmcnt(5)
	v_mfma_f32_16x16x32_bf16 v[86:89], v[130:133], v[154:157], 0
	v_mfma_f32_16x16x32_bf16 v[20:23], v[138:141], v[154:157], 0
	s_waitcnt lgkmcnt(3)
	v_mfma_f32_16x16x32_bf16 v[78:81], v[130:133], v[162:165], 0
	v_mfma_f32_16x16x32_bf16 v[12:15], v[138:141], v[162:165], 0
	s_waitcnt lgkmcnt(1)
	v_mfma_f32_16x16x32_bf16 v[70:73], v[130:133], v[170:173], 0
	v_mfma_f32_16x16x32_bf16 v[4:7], v[138:141], v[170:173], 0
	v_mfma_f32_16x16x32_bf16 v[94:97], v[134:137], v[150:153], v[94:97]
	v_mfma_f32_16x16x32_bf16 v[28:31], v[142:145], v[150:153], v[28:31]
	v_mfma_f32_16x16x32_bf16 v[86:89], v[134:137], v[158:161], v[86:89]
	v_mfma_f32_16x16x32_bf16 v[20:23], v[142:145], v[158:161], v[20:23]
	v_mfma_f32_16x16x32_bf16 v[78:81], v[134:137], v[166:169], v[78:81]
	v_mfma_f32_16x16x32_bf16 v[12:15], v[142:145], v[166:169], v[12:15]
	s_waitcnt lgkmcnt(0)
	v_mfma_f32_16x16x32_bf16 v[70:73], v[134:137], v[188:191], v[70:73]
	v_mfma_f32_16x16x32_bf16 v[4:7], v[142:145], v[188:191], v[4:7]
	s_barrier
; #define PG8_STAGE(bufoff, gbase, voff) do { _Pragma("unroll") for (int _i = 0; _i < 2; ++_i) \
;         __builtin_amdgcn_global_load_lds((const unsigned*)((const char*)(gbase) + (voff)[_i]), (PG8_LAS unsigned*)(lds + (bufoff) + ldsw + _i * 8192), 16, 0, 0); } while (0)
; #define PG8_LDA(dst, b, h) do { _Pragma("unroll") for (int m = 0; m < 4; ++m) _Pragma("unroll") for (int k = 0; k < 2; ++k) dst[m][k] = *(const PG8_LAS bf16x8*)(lds + PG8_SA(b, h) + aoff + m * 2048 + k * 1024); } while (0)
; #define PG8_LDB(dst, b, h) do { _Pragma("unroll") for (int n = 0; n < 2; ++n) _Pragma("unroll") for (int k = 0; k < 2; ++k) dst[n][k] = *(const PG8_LAS bf16x8*)(lds + PG8_SB(b, h) + boff + n * 2048 + k * 1024); } while (0)
; #define PG8_MMA(ai, bj, At, Bt) do { __builtin_amdgcn_s_setprio(1); _Pragma("unroll") for (int m = 0; m < 4; ++m) _Pragma("unroll") for (int n = 0; n < 2; ++n) _Pragma("unroll") for (int k = 0; k < 2; ++k) \
;         acc[ai][bj][m][n] = __builtin_amdgcn_mfma_f32_16x16x32_bf16(Bt[n][k], At[m][k], acc[ai][bj][m][n], 0, 0, 0); __builtin_amdgcn_s_setprio(0); } while (0)
; #define PG8_WAIT_V(n) asm volatile("s_waitcnt vmcnt(" #n ")" ::: "memory")
; #define PG8_WAIT_L(n) asm volatile("s_waitcnt lgkmcnt(" #n ")" ::: "memory")
; #define PG8_BAR __builtin_amdgcn_s_barrier()
; #define PG8_SCHED __builtin_amdgcn_sched_barrier(0)
; template <class Epi, class Sched>
; __device__ __forceinline__ void gemm_phase(PG8_LAS unsigned char* lds, const Gemm g, const Sched& S, const Epi& E) {
;     ...
;             PG8_STAGE(PG8_SB(0, 1), b2 + hstep, voffB);
;             PG8_WAIT_V(6); PG8_BAR; PG8_MMA(1, 1, At, B1); PG8_BAR;
;             PG8_LDB(B0, 1, 0); PG8_SCHED; PG8_LDA(At, 1, 0); PG8_STAGE(PG8_SA(0, 1), a2 + hstep, voffA);
;             PG8_WAIT_L(8); PG8_BAR; PG8_WAIT_L(0); PG8_MMA(0, 0, At, B0); PG8_BAR; PG8_SCHED;
;             PG8_LDB(B1, 1, 1); PG8_STAGE(PG8_SB(1, 0), b3, voffB);
;             PG8_BAR; PG8_WAIT_L(0); PG8_MMA(0, 1, At, B1); PG8_BAR;
;             PG8_LDA(At, 1, 1); PG8_STAGE(PG8_SA(1, 0), a3, voffA);
	s_add_u32 s22, s12, 0x40000
	s_addc_u32 s23, s13, 0
	s_add_i32 s31, s31, s36
	s_mov_b32 m0, s31
	v_lshl_add_u64 v[130:131], s[22:23], 0, v[178:179]
	global_load_lds_dwordx4 v[130:131], off
	s_add_i32 m0, s31, 0x2000
	v_lshl_add_u64 v[130:131], s[22:23], 0, v[182:183]
	global_load_lds_dwordx4 v[130:131], off
	s_waitcnt vmcnt(6)
	s_barrier
	v_mfma_f32_16x16x32_bf16 v[90:93], v[192:195], v[146:149], 0
	v_mfma_f32_16x16x32_bf16 v[24:27], v[200:203], v[146:149], 0
	v_mfma_f32_16x16x32_bf16 v[82:85], v[192:195], v[154:157], 0
	v_mfma_f32_16x16x32_bf16 v[16:19], v[200:203], v[154:157], 0
	v_mfma_f32_16x16x32_bf16 v[74:77], v[192:195], v[162:165], 0
	v_mfma_f32_16x16x32_bf16 v[8:11], v[200:203], v[162:165], 0
	v_mfma_f32_16x16x32_bf16 v[66:69], v[192:195], v[170:173], 0
	v_mfma_f32_16x16x32_bf16 v[0:3], v[200:203], v[170:173], 0
	v_mfma_f32_16x16x32_bf16 v[90:93], v[196:199], v[150:153], v[90:93]
	v_mfma_f32_16x16x32_bf16 v[24:27], v[204:207], v[150:153], v[24:27]
	v_mfma_f32_16x16x32_bf16 v[82:85], v[196:199], v[158:161], v[82:85]
	v_mfma_f32_16x16x32_bf16 v[16:19], v[204:207], v[158:161], v[16:19]
	v_mfma_f32_16x16x32_bf16 v[74:77], v[196:199], v[166:169], v[74:77]
	v_mfma_f32_16x16x32_bf16 v[8:11], v[204:207], v[166:169], v[8:11]
	v_mfma_f32_16x16x32_bf16 v[66:69], v[196:199], v[188:191], v[66:69]
	v_mfma_f32_16x16x32_bf16 v[0:3], v[204:207], v[188:191], v[0:3]
	s_add_i32 s22, 0, 0x18000
	v_add_u32_e32 v48, s22, v250
	s_barrier
	ds_read_b128 v[130:133], v48
	ds_read_b128 v[134:137], v48 offset:1024
	ds_read_b128 v[138:141], v48 offset:2048
	ds_read_b128 v[142:145], v48 offset:3072
	s_add_u32 s16, s16, 0x40000
	s_addc_u32 s17, s17, 0
	s_mov_b32 m0, s11
	v_lshl_add_u64 v[192:193], s[16:17], 0, v[176:177]
	ds_read_b128 v[146:149], v242 offset:32768
	ds_read_b128 v[150:153], v242 offset:33792
	ds_read_b128 v[154:157], v242 offset:34816
	ds_read_b128 v[158:161], v242 offset:35840
	ds_read_b128 v[162:165], v242 offset:36864
	ds_read_b128 v[166:169], v242 offset:37888
	ds_read_b128 v[170:173], v242 offset:38912
	ds_read_b128 v[188:191], v242 offset:39936
	global_load_lds_dwordx4 v[192:193], off
	s_mov_b32 m0, s24
	v_lshl_add_u64 v[192:193], s[16:17], 0, v[180:181]
	global_load_lds_dwordx4 v[192:193], off
	s_waitcnt lgkmcnt(8)
	s_barrier
	s_waitcnt lgkmcnt(7)
	v_mfma_f32_16x16x32_bf16 v[126:129], v[130:133], v[146:149], v[126:129]
	v_mfma_f32_16x16x32_bf16 v[62:65], v[138:141], v[146:149], v[62:65]
	s_waitcnt lgkmcnt(5)
	v_mfma_f32_16x16x32_bf16 v[118:121], v[130:133], v[154:157], v[118:121]
	v_mfma_f32_16x16x32_bf16 v[54:57], v[138:141], v[154:157], v[54:57]
	s_waitcnt lgkmcnt(3)
	v_mfma_f32_16x16x32_bf16 v[110:113], v[130:133], v[162:165], v[110:113]
	v_mfma_f32_16x16x32_bf16 v[44:47], v[138:141], v[162:165], v[44:47]
	s_waitcnt lgkmcnt(1)
	v_mfma_f32_16x16x32_bf16 v[102:105], v[130:133], v[170:173], v[102:105]
	v_mfma_f32_16x16x32_bf16 v[36:39], v[138:141], v[170:173], v[36:39]
	v_mfma_f32_16x16x32_bf16 v[126:129], v[134:137], v[150:153], v[126:129]
	v_mfma_f32_16x16x32_bf16 v[62:65], v[142:145], v[150:153], v[62:65]
	v_mfma_f32_16x16x32_bf16 v[118:121], v[134:137], v[158:161], v[118:121]
	v_mfma_f32_16x16x32_bf16 v[54:57], v[142:145], v[158:161], v[54:57]
	v_mfma_f32_16x16x32_bf16 v[110:113], v[134:137], v[166:169], v[110:113]
	v_mfma_f32_16x16x32_bf16 v[44:47], v[142:145], v[166:169], v[44:47]
	s_waitcnt lgkmcnt(0)
	v_mfma_f32_16x16x32_bf16 v[102:105], v[134:137], v[188:191], v[102:105]
	v_mfma_f32_16x16x32_bf16 v[36:39], v[142:145], v[188:191], v[36:39]
	s_barrier
	s_add_i32 s16, 0, 0x1c000
	s_add_i32 s17, s22, s36
	v_add_u32_e32 v48, s16, v250
	v_lshl_add_u64 v[208:209], v[208:209], 0, s[0:1]
	s_mov_b32 m0, s17
	ds_read_b128 v[192:195], v48
	ds_read_b128 v[196:199], v48 offset:1024
	ds_read_b128 v[200:203], v48 offset:2048
	ds_read_b128 v[204:207], v48 offset:3072
	global_load_lds_dwordx4 v[208:209], off
	s_add_i32 m0, s17, 0x2000
	v_lshl_add_u64 v[208:209], v[210:211], 0, s[0:1]
	global_load_lds_dwordx4 v[208:209], off
	s_barrier
	s_waitcnt lgkmcnt(3)
	v_mfma_f32_16x16x32_bf16 v[122:125], v[192:195], v[146:149], v[122:125]
	s_waitcnt lgkmcnt(1)
	v_mfma_f32_16x16x32_bf16 v[58:61], v[200:203], v[146:149], v[58:61]
	v_mfma_f32_16x16x32_bf16 v[114:117], v[192:195], v[154:157], v[114:117]
	v_mfma_f32_16x16x32_bf16 v[50:53], v[200:203], v[154:157], v[50:53]
	v_mfma_f32_16x16x32_bf16 v[106:109], v[192:195], v[162:165], v[106:109]
	v_mfma_f32_16x16x32_bf16 v[40:43], v[200:203], v[162:165], v[40:43]
	v_mfma_f32_16x16x32_bf16 v[98:101], v[192:195], v[170:173], v[98:101]
	v_mfma_f32_16x16x32_bf16 v[32:35], v[200:203], v[170:173], v[32:35]
	v_mfma_f32_16x16x32_bf16 v[122:125], v[196:199], v[150:153], v[122:125]
	s_waitcnt lgkmcnt(0)
	v_mfma_f32_16x16x32_bf16 v[58:61], v[204:207], v[150:153], v[58:61]
	v_mfma_f32_16x16x32_bf16 v[114:117], v[196:199], v[158:161], v[114:117]
	v_mfma_f32_16x16x32_bf16 v[50:53], v[204:207], v[158:161], v[50:53]
	v_mfma_f32_16x16x32_bf16 v[106:109], v[196:199], v[166:169], v[106:109]
	v_mfma_f32_16x16x32_bf16 v[40:43], v[204:207], v[166:169], v[40:43]
	v_mfma_f32_16x16x32_bf16 v[98:101], v[196:199], v[188:191], v[98:101]
	v_mfma_f32_16x16x32_bf16 v[32:35], v[204:207], v[188:191], v[32:35]
	s_mov_b32 m0, s25
	v_lshl_add_u64 v[208:209], v[212:213], 0, s[0:1]
	s_barrier
	ds_read_b128 v[146:149], v242 offset:49152
	ds_read_b128 v[150:153], v242 offset:50176
	ds_read_b128 v[154:157], v242 offset:51200
	ds_read_b128 v[158:161], v242 offset:52224
	ds_read_b128 v[162:165], v242 offset:53248
	ds_read_b128 v[166:169], v242 offset:54272
	ds_read_b128 v[170:173], v242 offset:55296
	ds_read_b128 v[188:191], v242 offset:56320
	global_load_lds_dwordx4 v[208:209], off
	s_mov_b32 m0, s18
	v_lshl_add_u64 v[208:209], v[214:215], 0, s[0:1]
	global_load_lds_dwordx4 v[208:209], off
	s_barrier
; #define PG8_STAGE(bufoff, gbase, voff) do { _Pragma("unroll") for (int _i = 0; _i < 2; ++_i) \
;         __builtin_amdgcn_global_load_lds((const unsigned*)((const char*)(gbase) + (voff)[_i]), (PG8_LAS unsigned*)(lds + (bufoff) + ldsw + _i * 8192), 16, 0, 0); } while (0)
; #define PG8_LDA(dst, b, h) do { _Pragma("unroll") for (int m = 0; m < 4; ++m) _Pragma("unroll") for (int k = 0; k < 2; ++k) dst[m][k] = *(const PG8_LAS bf16x8*)(lds + PG8_SA(b, h) + aoff + m * 2048 + k * 1024); } while (0)
; #define PG8_LDB(dst, b, h) do { _Pragma("unroll") for (int n = 0; n < 2; ++n) _Pragma("unroll") for (int k = 0; k < 2; ++k) dst[n][k] = *(const PG8_LAS bf16x8*)(lds + PG8_SB(b, h) + boff + n * 2048 + k * 1024); } while (0)
; #define PG8_WAIT_V(n) asm volatile("s_waitcnt vmcnt(" #n ")" ::: "memory")
; #define PG8_WAIT_L(n) asm volatile("s_waitcnt lgkmcnt(" #n ")" ::: "memory")
; #define PG8_BAR __builtin_amdgcn_s_barrier()
; #define PG8_SCHED __builtin_amdgcn_sched_barrier(0)
; template <class Epi, class Sched>
; __device__ __forceinline__ void gemm_phase(PG8_LAS unsigned char* lds, const Gemm g, const Sched& S, const Epi& E) {
;     ...
;             PG8_LDB(B0, 0, 0); PG8_SCHED; PG8_LDA(At, 0, 0); PG8_STAGE(PG8_SA(1, 1), a1 + hstep, voffA);
;             PG8_WAIT_L(8); PG8_BAR; PG8_WAIT_L(0); PG8_MMA(0, 0, At, B0); PG8_BAR; PG8_SCHED;
;             PG8_LDB(B1, 0, 1); PG8_STAGE(PG8_SB(0, 0), b2, voffB);
;             PG8_BAR; PG8_WAIT_L(0); PG8_MMA(0, 1, At, B1); PG8_BAR;
;             PG8_LDA(At, 0, 1); PG8_STAGE(PG8_SA(0, 0), a2, voffA);
;             PG8_BAR; PG8_WAIT_L(0); PG8_MMA(1, 0, At, B0); PG8_BAR; PG8_SCHED;
;             PG8_STAGE(PG8_SB(0, 1), b2 + hstep, voffB);
;             PG8_WAIT_V(6); PG8_BAR; PG8_MMA(1, 1, At, B1); PG8_BAR;
;             PG8_LDB(B0, 1, 0); PG8_SCHED; PG8_LDA(At, 1, 0); PG8_STAGE(PG8_SA(0, 1), a2 + hstep, voffA);
;             PG8_WAIT_L(8); PG8_BAR; PG8_WAIT_L(0); PG8_MMA(0, 0, At, B0); PG8_BAR; PG8_SCHED;
;             PG8_LDB(B1, 1, 1); PG8_STAGE(PG8_SB(1, 0), b3, voffB);
;             PG8_BAR; PG8_WAIT_L(0); PG8_MMA(0, 1, At, B1); PG8_BAR;
;             PG8_LDA(At, 1, 1); PG8_STAGE(PG8_SA(1, 0), a3, voffA);
;             PG8_BAR; PG8_WAIT_L(0); PG8_MMA(1, 0, At, B0); PG8_BAR; PG8_SCHED;
;             PG8_STAGE(PG8_SB(1, 1), b3 + hstep, voffB);
;             PG8_WAIT_V(6); PG8_BAR; PG8_MMA(1, 1, At, B1); PG8_BAR;
	s_waitcnt lgkmcnt(7)
	v_mfma_f32_16x16x32_bf16 v[94:97], v[130:133], v[146:149], v[94:97]
	v_mfma_f32_16x16x32_bf16 v[28:31], v[138:141], v[146:149], v[28:31]
	s_waitcnt lgkmcnt(5)
	v_mfma_f32_16x16x32_bf16 v[86:89], v[130:133], v[154:157], v[86:89]
	v_mfma_f32_16x16x32_bf16 v[20:23], v[138:141], v[154:157], v[20:23]
	s_waitcnt lgkmcnt(3)
	v_mfma_f32_16x16x32_bf16 v[78:81], v[130:133], v[162:165], v[78:81]
	v_mfma_f32_16x16x32_bf16 v[12:15], v[138:141], v[162:165], v[12:15]
	s_waitcnt lgkmcnt(1)
	v_mfma_f32_16x16x32_bf16 v[70:73], v[130:133], v[170:173], v[70:73]
	v_mfma_f32_16x16x32_bf16 v[4:7], v[138:141], v[170:173], v[4:7]
	v_mfma_f32_16x16x32_bf16 v[94:97], v[134:137], v[150:153], v[94:97]
	v_mfma_f32_16x16x32_bf16 v[28:31], v[142:145], v[150:153], v[28:31]
	v_mfma_f32_16x16x32_bf16 v[86:89], v[134:137], v[158:161], v[86:89]
	v_mfma_f32_16x16x32_bf16 v[20:23], v[142:145], v[158:161], v[20:23]
	v_mfma_f32_16x16x32_bf16 v[78:81], v[134:137], v[166:169], v[78:81]
	v_mfma_f32_16x16x32_bf16 v[12:15], v[142:145], v[166:169], v[12:15]
	s_waitcnt lgkmcnt(0)
	v_mfma_f32_16x16x32_bf16 v[70:73], v[134:137], v[188:191], v[70:73]
	v_mfma_f32_16x16x32_bf16 v[4:7], v[142:145], v[188:191], v[4:7]
	s_barrier
	s_add_u32 s12, s12, 0x40080
	s_addc_u32 s13, s13, 0
	s_add_i32 s16, s16, s36
	s_mov_b32 m0, s16
	v_lshl_add_u64 v[130:131], s[12:13], 0, v[178:179]
	global_load_lds_dwordx4 v[130:131], off
	s_add_i32 m0, s16, 0x2000
	v_lshl_add_u64 v[130:131], s[12:13], 0, v[182:183]
	global_load_lds_dwordx4 v[130:131], off
	s_waitcnt vmcnt(6)
	s_barrier
	v_mfma_f32_16x16x32_bf16 v[90:93], v[192:195], v[146:149], v[90:93]
	v_mfma_f32_16x16x32_bf16 v[24:27], v[200:203], v[146:149], v[24:27]
	v_mfma_f32_16x16x32_bf16 v[82:85], v[192:195], v[154:157], v[82:85]
	v_mfma_f32_16x16x32_bf16 v[16:19], v[200:203], v[154:157], v[16:19]
	v_mfma_f32_16x16x32_bf16 v[74:77], v[192:195], v[162:165], v[74:77]
	v_mfma_f32_16x16x32_bf16 v[8:11], v[200:203], v[162:165], v[8:11]
	v_mfma_f32_16x16x32_bf16 v[66:69], v[192:195], v[170:173], v[66:69]
	v_mfma_f32_16x16x32_bf16 v[0:3], v[200:203], v[170:173], v[0:3]
	v_mfma_f32_16x16x32_bf16 v[90:93], v[196:199], v[150:153], v[90:93]
	v_mfma_f32_16x16x32_bf16 v[24:27], v[204:207], v[150:153], v[24:27]
	v_mfma_f32_16x16x32_bf16 v[82:85], v[196:199], v[158:161], v[82:85]
	v_mfma_f32_16x16x32_bf16 v[16:19], v[204:207], v[158:161], v[16:19]
	v_mfma_f32_16x16x32_bf16 v[74:77], v[196:199], v[166:169], v[74:77]
	v_mfma_f32_16x16x32_bf16 v[8:11], v[204:207], v[166:169], v[8:11]
	v_mfma_f32_16x16x32_bf16 v[66:69], v[196:199], v[188:191], v[66:69]
	v_mfma_f32_16x16x32_bf16 v[0:3], v[204:207], v[188:191], v[0:3]
	s_add_i32 s30, s30, 2
	s_add_u32 s6, s6, 0x100
	s_addc_u32 s7, s7, 0
	s_add_u32 s27, s27, 0x100
	s_addc_u32 s29, s29, 0
	s_cmp_gt_u32 s30, 13
	s_barrier
	s_cbranch_scc1 .Lkpeel_exit_388
.LBB0_388:
	s_add_u32 s12, s6, 0xfffc0080
	s_addc_u32 s13, s7, -1
	s_add_i32 s22, 0, 0x10000
	v_add_u32_e32 v48, s22, v250
	ds_read_b128 v[130:133], v48
	ds_read_b128 v[134:137], v48 offset:1024
	ds_read_b128 v[138:141], v48 offset:2048
	ds_read_b128 v[142:145], v48 offset:3072
	s_cmp_eq_u32 s30, 12
	s_cselect_b32 s17, s9, s13
	s_cselect_b32 s16, s8, s12
	s_cselect_b32 s13, s3, s29
	s_cselect_b32 s12, s26, s27
	v_lshl_add_u64 v[192:193], s[6:7], 0, v[184:185]
	s_add_i32 m0, s37, 0xc000
	ds_read_b128 v[146:149], v242
	ds_read_b128 v[150:153], v242 offset:1024
	ds_read_b128 v[154:157], v242 offset:2048
	ds_read_b128 v[158:161], v242 offset:3072
	ds_read_b128 v[162:165], v242 offset:4096
	ds_read_b128 v[166:169], v242 offset:5120
	ds_read_b128 v[170:173], v242 offset:6144
	ds_read_b128 v[188:191], v242 offset:7168
	global_load_lds_dwordx4 v[192:193], off
	s_add_i32 m0, s37, 0xe000
	v_lshl_add_u64 v[192:193], s[6:7], 0, v[186:187]
	global_load_lds_dwordx4 v[192:193], off
	s_waitcnt lgkmcnt(8)
	s_barrier
	s_waitcnt lgkmcnt(7)
	v_mfma_f32_16x16x32_bf16 v[126:129], v[130:133], v[146:149], v[126:129]
	v_mfma_f32_16x16x32_bf16 v[62:65], v[138:141], v[146:149], v[62:65]
	s_waitcnt lgkmcnt(5)
	v_mfma_f32_16x16x32_bf16 v[118:121], v[130:133], v[154:157], v[118:121]
	v_mfma_f32_16x16x32_bf16 v[54:57], v[138:141], v[154:157], v[54:57]
	s_waitcnt lgkmcnt(3)
	v_mfma_f32_16x16x32_bf16 v[110:113], v[130:133], v[162:165], v[110:113]
	v_mfma_f32_16x16x32_bf16 v[44:47], v[138:141], v[162:165], v[44:47]
	s_waitcnt lgkmcnt(1)
	v_mfma_f32_16x16x32_bf16 v[102:105], v[130:133], v[170:173], v[102:105]
	v_mfma_f32_16x16x32_bf16 v[36:39], v[138:141], v[170:173], v[36:39]
	v_mfma_f32_16x16x32_bf16 v[126:129], v[134:137], v[150:153], v[126:129]
	v_mfma_f32_16x16x32_bf16 v[62:65], v[142:145], v[150:153], v[62:65]
	v_mfma_f32_16x16x32_bf16 v[118:121], v[134:137], v[158:161], v[118:121]
	v_mfma_f32_16x16x32_bf16 v[54:57], v[142:145], v[158:161], v[54:57]
	v_mfma_f32_16x16x32_bf16 v[110:113], v[134:137], v[166:169], v[110:113]
	v_mfma_f32_16x16x32_bf16 v[44:47], v[142:145], v[166:169], v[44:47]
	s_waitcnt lgkmcnt(0)
	v_mfma_f32_16x16x32_bf16 v[102:105], v[134:137], v[188:191], v[102:105]
	v_mfma_f32_16x16x32_bf16 v[36:39], v[142:145], v[188:191], v[36:39]
	s_barrier
	s_add_i32 s31, 0, 0x14000
	s_add_i32 s22, s22, s36
	v_add_u32_e32 v48, s31, v250
	v_lshl_add_u64 v[208:209], s[12:13], 0, v[178:179]
	s_mov_b32 m0, s22
	ds_read_b128 v[192:195], v48
	ds_read_b128 v[196:199], v48 offset:1024
	ds_read_b128 v[200:203], v48 offset:2048
	ds_read_b128 v[204:207], v48 offset:3072
	global_load_lds_dwordx4 v[208:209], off
	s_add_i32 m0, s22, 0x2000
	v_lshl_add_u64 v[210:211], s[12:13], 0, v[182:183]
	global_load_lds_dwordx4 v[210:211], off
	s_barrier
; #define PG8_STAGE(bufoff, gbase, voff) do { _Pragma("unroll") for (int _i = 0; _i < 2; ++_i) \
;         __builtin_amdgcn_global_load_lds((const unsigned*)((const char*)(gbase) + (voff)[_i]), (PG8_LAS unsigned*)(lds + (bufoff) + ldsw + _i * 8192), 16, 0, 0); } while (0)
; #define PG8_LDA(dst, b, h) do { _Pragma("unroll") for (int m = 0; m < 4; ++m) _Pragma("unroll") for (int k = 0; k < 2; ++k) dst[m][k] = *(const PG8_LAS bf16x8*)(lds + PG8_SA(b, h) + aoff + m * 2048 + k * 1024); } while (0)
; #define PG8_LDB(dst, b, h) do { _Pragma("unroll") for (int n = 0; n < 2; ++n) _Pragma("unroll") for (int k = 0; k < 2; ++k) dst[n][k] = *(const PG8_LAS bf16x8*)(lds + PG8_SB(b, h) + boff + n * 2048 + k * 1024); } while (0)
; #define PG8_MMA(ai, bj, At, Bt) do { __builtin_amdgcn_s_setprio(1); _Pragma("unroll") for (int m = 0; m < 4; ++m) _Pragma("unroll") for (int n = 0; n < 2; ++n) _Pragma("unroll") for (int k = 0; k < 2; ++k) \
;         acc[ai][bj][m][n] = __builtin_amdgcn_mfma_f32_16x16x32_bf16(Bt[n][k], At[m][k], acc[ai][bj][m][n], 0, 0, 0); __builtin_amdgcn_s_setprio(0); } while (0)
; #define PG8_WAIT_V(n) asm volatile("s_waitcnt vmcnt(" #n ")" ::: "memory")
; #define PG8_WAIT_L(n) asm volatile("s_waitcnt lgkmcnt(" #n ")" ::: "memory")
; #define PG8_BAR __builtin_amdgcn_s_barrier()
; #define PG8_SCHED __builtin_amdgcn_sched_barrier(0)
; template <class Epi, class Sched>
; __device__ __forceinline__ void gemm_phase(PG8_LAS unsigned char* lds, const Gemm g, const Sched& S, const Epi& E) {
;     ...
;             PG8_BAR; PG8_WAIT_L(0); PG8_MMA(0, 1, At, B1); PG8_BAR;
;             PG8_LDA(At, 0, 1); PG8_STAGE(PG8_SA(0, 0), a2, voffA);
;             PG8_BAR; PG8_WAIT_L(0); PG8_MMA(1, 0, At, B0); PG8_BAR; PG8_SCHED;
;             PG8_STAGE(PG8_SB(0, 1), b2 + hstep, voffB);
;             PG8_WAIT_V(6); PG8_BAR; PG8_MMA(1, 1, At, B1); PG8_BAR;
;             PG8_LDB(B0, 1, 0); PG8_SCHED; PG8_LDA(At, 1, 0); PG8_STAGE(PG8_SA(0, 1), a2 + hstep, voffA);
;             PG8_WAIT_L(8); PG8_BAR; PG8_WAIT_L(0); PG8_MMA(0, 0, At, B0); PG8_BAR; PG8_SCHED;
	s_waitcnt lgkmcnt(3)
	v_mfma_f32_16x16x32_bf16 v[122:125], v[192:195], v[146:149], v[122:125]
	s_waitcnt lgkmcnt(1)
	v_mfma_f32_16x16x32_bf16 v[58:61], v[200:203], v[146:149], v[58:61]
	v_mfma_f32_16x16x32_bf16 v[114:117], v[192:195], v[154:157], v[114:117]
	v_mfma_f32_16x16x32_bf16 v[50:53], v[200:203], v[154:157], v[50:53]
	v_mfma_f32_16x16x32_bf16 v[106:109], v[192:195], v[162:165], v[106:109]
	v_mfma_f32_16x16x32_bf16 v[40:43], v[200:203], v[162:165], v[40:43]
	v_mfma_f32_16x16x32_bf16 v[98:101], v[192:195], v[170:173], v[98:101]
	v_mfma_f32_16x16x32_bf16 v[32:35], v[200:203], v[170:173], v[32:35]
	v_mfma_f32_16x16x32_bf16 v[122:125], v[196:199], v[150:153], v[122:125]
	s_waitcnt lgkmcnt(0)
	v_mfma_f32_16x16x32_bf16 v[58:61], v[204:207], v[150:153], v[58:61]
	v_mfma_f32_16x16x32_bf16 v[114:117], v[196:199], v[158:161], v[114:117]
	v_mfma_f32_16x16x32_bf16 v[50:53], v[204:207], v[158:161], v[50:53]
	v_mfma_f32_16x16x32_bf16 v[106:109], v[196:199], v[166:169], v[106:109]
	v_mfma_f32_16x16x32_bf16 v[40:43], v[204:207], v[166:169], v[40:43]
	v_mfma_f32_16x16x32_bf16 v[98:101], v[196:199], v[188:191], v[98:101]
	v_mfma_f32_16x16x32_bf16 v[32:35], v[204:207], v[188:191], v[32:35]
	s_mov_b32 m0, s37
	v_lshl_add_u64 v[212:213], s[16:17], 0, v[176:177]
	s_barrier
	ds_read_b128 v[146:149], v242 offset:16384
	ds_read_b128 v[150:153], v242 offset:17408
	ds_read_b128 v[154:157], v242 offset:18432
	ds_read_b128 v[158:161], v242 offset:19456
	ds_read_b128 v[162:165], v242 offset:20480
	ds_read_b128 v[166:169], v242 offset:21504
	ds_read_b128 v[170:173], v242 offset:22528
	ds_read_b128 v[188:191], v242 offset:23552
	global_load_lds_dwordx4 v[212:213], off
	s_mov_b32 m0, s10
	v_lshl_add_u64 v[214:215], s[16:17], 0, v[180:181]
	global_load_lds_dwordx4 v[214:215], off
	s_barrier
	s_waitcnt lgkmcnt(7)
	v_mfma_f32_16x16x32_bf16 v[94:97], v[130:133], v[146:149], v[94:97]
	v_mfma_f32_16x16x32_bf16 v[28:31], v[138:141], v[146:149], v[28:31]
	s_waitcnt lgkmcnt(5)
	v_mfma_f32_16x16x32_bf16 v[86:89], v[130:133], v[154:157], v[86:89]
	v_mfma_f32_16x16x32_bf16 v[20:23], v[138:141], v[154:157], v[20:23]
	s_waitcnt lgkmcnt(3)
	v_mfma_f32_16x16x32_bf16 v[78:81], v[130:133], v[162:165], v[78:81]
	v_mfma_f32_16x16x32_bf16 v[12:15], v[138:141], v[162:165], v[12:15]
	s_waitcnt lgkmcnt(1)
	v_mfma_f32_16x16x32_bf16 v[70:73], v[130:133], v[170:173], v[70:73]
	v_mfma_f32_16x16x32_bf16 v[4:7], v[138:141], v[170:173], v[4:7]
	v_mfma_f32_16x16x32_bf16 v[94:97], v[134:137], v[150:153], v[94:97]
	v_mfma_f32_16x16x32_bf16 v[28:31], v[142:145], v[150:153], v[28:31]
	v_mfma_f32_16x16x32_bf16 v[86:89], v[134:137], v[158:161], v[86:89]
	v_mfma_f32_16x16x32_bf16 v[20:23], v[142:145], v[158:161], v[20:23]
	v_mfma_f32_16x16x32_bf16 v[78:81], v[134:137], v[166:169], v[78:81]
	v_mfma_f32_16x16x32_bf16 v[12:15], v[142:145], v[166:169], v[12:15]
	s_waitcnt lgkmcnt(0)
	v_mfma_f32_16x16x32_bf16 v[70:73], v[134:137], v[188:191], v[70:73]
	v_mfma_f32_16x16x32_bf16 v[4:7], v[142:145], v[188:191], v[4:7]
	s_barrier
	s_add_u32 s22, s12, 0x40000
	s_addc_u32 s23, s13, 0
	s_add_i32 s31, s31, s36
	s_mov_b32 m0, s31
	v_lshl_add_u64 v[130:131], s[22:23], 0, v[178:179]
	global_load_lds_dwordx4 v[130:131], off
	s_add_i32 m0, s31, 0x2000
	v_lshl_add_u64 v[130:131], s[22:23], 0, v[182:183]
	global_load_lds_dwordx4 v[130:131], off
	s_waitcnt vmcnt(6)
	s_barrier
	v_mfma_f32_16x16x32_bf16 v[90:93], v[192:195], v[146:149], v[90:93]
	v_mfma_f32_16x16x32_bf16 v[24:27], v[200:203], v[146:149], v[24:27]
	v_mfma_f32_16x16x32_bf16 v[82:85], v[192:195], v[154:157], v[82:85]
	v_mfma_f32_16x16x32_bf16 v[16:19], v[200:203], v[154:157], v[16:19]
	v_mfma_f32_16x16x32_bf16 v[74:77], v[192:195], v[162:165], v[74:77]
	v_mfma_f32_16x16x32_bf16 v[8:11], v[200:203], v[162:165], v[8:11]
	v_mfma_f32_16x16x32_bf16 v[66:69], v[192:195], v[170:173], v[66:69]
	v_mfma_f32_16x16x32_bf16 v[0:3], v[200:203], v[170:173], v[0:3]
	v_mfma_f32_16x16x32_bf16 v[90:93], v[196:199], v[150:153], v[90:93]
	v_mfma_f32_16x16x32_bf16 v[24:27], v[204:207], v[150:153], v[24:27]
	v_mfma_f32_16x16x32_bf16 v[82:85], v[196:199], v[158:161], v[82:85]
	v_mfma_f32_16x16x32_bf16 v[16:19], v[204:207], v[158:161], v[16:19]
	v_mfma_f32_16x16x32_bf16 v[74:77], v[196:199], v[166:169], v[74:77]
	v_mfma_f32_16x16x32_bf16 v[8:11], v[204:207], v[166:169], v[8:11]
	v_mfma_f32_16x16x32_bf16 v[66:69], v[196:199], v[188:191], v[66:69]
	v_mfma_f32_16x16x32_bf16 v[0:3], v[204:207], v[188:191], v[0:3]
	s_add_i32 s22, 0, 0x18000
	v_add_u32_e32 v48, s22, v250
	s_barrier
	ds_read_b128 v[130:133], v48
	ds_read_b128 v[134:137], v48 offset:1024
	ds_read_b128 v[138:141], v48 offset:2048
	ds_read_b128 v[142:145], v48 offset:3072
	s_add_u32 s16, s16, 0x40000
	s_addc_u32 s17, s17, 0
	s_mov_b32 m0, s11
	v_lshl_add_u64 v[192:193], s[16:17], 0, v[176:177]
	ds_read_b128 v[146:149], v242 offset:32768
	ds_read_b128 v[150:153], v242 offset:33792
	ds_read_b128 v[154:157], v242 offset:34816
	ds_read_b128 v[158:161], v242 offset:35840
	ds_read_b128 v[162:165], v242 offset:36864
	ds_read_b128 v[166:169], v242 offset:37888
	ds_read_b128 v[170:173], v242 offset:38912
	ds_read_b128 v[188:191], v242 offset:39936
	global_load_lds_dwordx4 v[192:193], off
	s_mov_b32 m0, s24
	v_lshl_add_u64 v[192:193], s[16:17], 0, v[180:181]
	global_load_lds_dwordx4 v[192:193], off
	s_waitcnt lgkmcnt(8)
	s_barrier
; #define PG8_STAGE(bufoff, gbase, voff) do { _Pragma("unroll") for (int _i = 0; _i < 2; ++_i) \
;         __builtin_amdgcn_global_load_lds((const unsigned*)((const char*)(gbase) + (voff)[_i]), (PG8_LAS unsigned*)(lds + (bufoff) + ldsw + _i * 8192), 16, 0, 0); } while (0)
; #define PG8_LDA(dst, b, h) do { _Pragma("unroll") for (int m = 0; m < 4; ++m) _Pragma("unroll") for (int k = 0; k < 2; ++k) dst[m][k] = *(const PG8_LAS bf16x8*)(lds + PG8_SA(b, h) + aoff + m * 2048 + k * 1024); } while (0)
; #define PG8_LDB(dst, b, h) do { _Pragma("unroll") for (int n = 0; n < 2; ++n) _Pragma("unroll") for (int k = 0; k < 2; ++k) dst[n][k] = *(const PG8_LAS bf16x8*)(lds + PG8_SB(b, h) + boff + n * 2048 + k * 1024); } while (0)
; #define PG8_MMA(ai, bj, At, Bt) do { __builtin_amdgcn_s_setprio(1); _Pragma("unroll") for (int m = 0; m < 4; ++m) _Pragma("unroll") for (int n = 0; n < 2; ++n) _Pragma("unroll") for (int k = 0; k < 2; ++k) \
;         acc[ai][bj][m][n] = __builtin_amdgcn_mfma_f32_16x16x32_bf16(Bt[n][k], At[m][k], acc[ai][bj][m][n], 0, 0, 0); __builtin_amdgcn_s_setprio(0); } while (0)
; #define PG8_WAIT_V(n) asm volatile("s_waitcnt vmcnt(" #n ")" ::: "memory")
; #define PG8_WAIT_L(n) asm volatile("s_waitcnt lgkmcnt(" #n ")" ::: "memory")
; #define PG8_BAR __builtin_amdgcn_s_barrier()
; #define PG8_SCHED __builtin_amdgcn_sched_barrier(0)
; template <class Epi, class Sched>
; __device__ __forceinline__ void gemm_phase(PG8_LAS unsigned char* lds, const Gemm g, const Sched& S, const Epi& E) {
;     ...
;             PG8_WAIT_L(8); PG8_BAR; PG8_WAIT_L(0); PG8_MMA(0, 0, At, B0); PG8_BAR; PG8_SCHED;
;             PG8_LDB(B1, 1, 1); PG8_STAGE(PG8_SB(1, 0), b3, voffB);
;             PG8_BAR; PG8_WAIT_L(0); PG8_MMA(0, 1, At, B1); PG8_BAR;
;             PG8_LDA(At, 1, 1); PG8_STAGE(PG8_SA(1, 0), a3, voffA);
;             PG8_BAR; PG8_WAIT_L(0); PG8_MMA(1, 0, At, B0); PG8_BAR; PG8_SCHED;
;             PG8_STAGE(PG8_SB(1, 1), b3 + hstep, voffB);
;             PG8_WAIT_V(6); PG8_BAR; PG8_MMA(1, 1, At, B1); PG8_BAR;
;         }
	s_waitcnt lgkmcnt(7)
	v_mfma_f32_16x16x32_bf16 v[126:129], v[130:133], v[146:149], v[126:129]
	v_mfma_f32_16x16x32_bf16 v[62:65], v[138:141], v[146:149], v[62:65]
	s_waitcnt lgkmcnt(5)
	v_mfma_f32_16x16x32_bf16 v[118:121], v[130:133], v[154:157], v[118:121]
	v_mfma_f32_16x16x32_bf16 v[54:57], v[138:141], v[154:157], v[54:57]
	s_waitcnt lgkmcnt(3)
	v_mfma_f32_16x16x32_bf16 v[110:113], v[130:133], v[162:165], v[110:113]
	v_mfma_f32_16x16x32_bf16 v[44:47], v[138:141], v[162:165], v[44:47]
	s_waitcnt lgkmcnt(1)
	v_mfma_f32_16x16x32_bf16 v[102:105], v[130:133], v[170:173], v[102:105]
	v_mfma_f32_16x16x32_bf16 v[36:39], v[138:141], v[170:173], v[36:39]
	v_mfma_f32_16x16x32_bf16 v[126:129], v[134:137], v[150:153], v[126:129]
	v_mfma_f32_16x16x32_bf16 v[62:65], v[142:145], v[150:153], v[62:65]
	v_mfma_f32_16x16x32_bf16 v[118:121], v[134:137], v[158:161], v[118:121]
	v_mfma_f32_16x16x32_bf16 v[54:57], v[142:145], v[158:161], v[54:57]
	v_mfma_f32_16x16x32_bf16 v[110:113], v[134:137], v[166:169], v[110:113]
	v_mfma_f32_16x16x32_bf16 v[44:47], v[142:145], v[166:169], v[44:47]
	s_waitcnt lgkmcnt(0)
	v_mfma_f32_16x16x32_bf16 v[102:105], v[134:137], v[188:191], v[102:105]
	v_mfma_f32_16x16x32_bf16 v[36:39], v[142:145], v[188:191], v[36:39]
	s_barrier
	s_add_i32 s16, 0, 0x1c000
	s_add_i32 s17, s22, s36
	v_add_u32_e32 v48, s16, v250
	v_lshl_add_u64 v[208:209], v[208:209], 0, s[0:1]
	s_mov_b32 m0, s17
	ds_read_b128 v[192:195], v48
	ds_read_b128 v[196:199], v48 offset:1024
	ds_read_b128 v[200:203], v48 offset:2048
	ds_read_b128 v[204:207], v48 offset:3072
	global_load_lds_dwordx4 v[208:209], off
	s_add_i32 m0, s17, 0x2000
	v_lshl_add_u64 v[208:209], v[210:211], 0, s[0:1]
	global_load_lds_dwordx4 v[208:209], off
	s_barrier
	s_waitcnt lgkmcnt(3)
	v_mfma_f32_16x16x32_bf16 v[122:125], v[192:195], v[146:149], v[122:125]
	s_waitcnt lgkmcnt(1)
	v_mfma_f32_16x16x32_bf16 v[58:61], v[200:203], v[146:149], v[58:61]
	v_mfma_f32_16x16x32_bf16 v[114:117], v[192:195], v[154:157], v[114:117]
	v_mfma_f32_16x16x32_bf16 v[50:53], v[200:203], v[154:157], v[50:53]
	v_mfma_f32_16x16x32_bf16 v[106:109], v[192:195], v[162:165], v[106:109]
	v_mfma_f32_16x16x32_bf16 v[40:43], v[200:203], v[162:165], v[40:43]
	v_mfma_f32_16x16x32_bf16 v[98:101], v[192:195], v[170:173], v[98:101]
	v_mfma_f32_16x16x32_bf16 v[32:35], v[200:203], v[170:173], v[32:35]
	v_mfma_f32_16x16x32_bf16 v[122:125], v[196:199], v[150:153], v[122:125]
	s_waitcnt lgkmcnt(0)
	v_mfma_f32_16x16x32_bf16 v[58:61], v[204:207], v[150:153], v[58:61]
	v_mfma_f32_16x16x32_bf16 v[114:117], v[196:199], v[158:161], v[114:117]
	v_mfma_f32_16x16x32_bf16 v[50:53], v[204:207], v[158:161], v[50:53]
	v_mfma_f32_16x16x32_bf16 v[106:109], v[196:199], v[166:169], v[106:109]
	v_mfma_f32_16x16x32_bf16 v[40:43], v[204:207], v[166:169], v[40:43]
	v_mfma_f32_16x16x32_bf16 v[98:101], v[196:199], v[188:191], v[98:101]
	v_mfma_f32_16x16x32_bf16 v[32:35], v[204:207], v[188:191], v[32:35]
	s_mov_b32 m0, s25
	v_lshl_add_u64 v[208:209], v[212:213], 0, s[0:1]
	s_barrier
	ds_read_b128 v[146:149], v242 offset:49152
	ds_read_b128 v[150:153], v242 offset:50176
	ds_read_b128 v[154:157], v242 offset:51200
	ds_read_b128 v[158:161], v242 offset:52224
	ds_read_b128 v[162:165], v242 offset:53248
	ds_read_b128 v[166:169], v242 offset:54272
	ds_read_b128 v[170:173], v242 offset:55296
	ds_read_b128 v[188:191], v242 offset:56320
	global_load_lds_dwordx4 v[208:209], off
	s_mov_b32 m0, s18
	v_lshl_add_u64 v[208:209], v[214:215], 0, s[0:1]
	global_load_lds_dwordx4 v[208:209], off
	s_barrier
	s_waitcnt lgkmcnt(7)
	v_mfma_f32_16x16x32_bf16 v[94:97], v[130:133], v[146:149], v[94:97]
	v_mfma_f32_16x16x32_bf16 v[28:31], v[138:141], v[146:149], v[28:31]
	s_waitcnt lgkmcnt(5)
	v_mfma_f32_16x16x32_bf16 v[86:89], v[130:133], v[154:157], v[86:89]
	v_mfma_f32_16x16x32_bf16 v[20:23], v[138:141], v[154:157], v[20:23]
	s_waitcnt lgkmcnt(3)
	v_mfma_f32_16x16x32_bf16 v[78:81], v[130:133], v[162:165], v[78:81]
	v_mfma_f32_16x16x32_bf16 v[12:15], v[138:141], v[162:165], v[12:15]
	s_waitcnt lgkmcnt(1)
	v_mfma_f32_16x16x32_bf16 v[70:73], v[130:133], v[170:173], v[70:73]
	v_mfma_f32_16x16x32_bf16 v[4:7], v[138:141], v[170:173], v[4:7]
	v_mfma_f32_16x16x32_bf16 v[94:97], v[134:137], v[150:153], v[94:97]
	v_mfma_f32_16x16x32_bf16 v[28:31], v[142:145], v[150:153], v[28:31]
	v_mfma_f32_16x16x32_bf16 v[86:89], v[134:137], v[158:161], v[86:89]
	v_mfma_f32_16x16x32_bf16 v[20:23], v[142:145], v[158:161], v[20:23]
	v_mfma_f32_16x16x32_bf16 v[78:81], v[134:137], v[166:169], v[78:81]
	v_mfma_f32_16x16x32_bf16 v[12:15], v[142:145], v[166:169], v[12:15]
	s_waitcnt lgkmcnt(0)
	v_mfma_f32_16x16x32_bf16 v[70:73], v[134:137], v[188:191], v[70:73]
	v_mfma_f32_16x16x32_bf16 v[4:7], v[142:145], v[188:191], v[4:7]
	s_barrier
	s_add_u32 s12, s12, 0x40080
	s_addc_u32 s13, s13, 0
	s_add_i32 s16, s16, s36
	s_mov_b32 m0, s16
	v_lshl_add_u64 v[130:131], s[12:13], 0, v[178:179]
	global_load_lds_dwordx4 v[130:131], off
	s_add_i32 m0, s16, 0x2000
	v_lshl_add_u64 v[130:131], s[12:13], 0, v[182:183]
	global_load_lds_dwordx4 v[130:131], off
	s_waitcnt vmcnt(6)
	s_barrier
	v_mfma_f32_16x16x32_bf16 v[90:93], v[192:195], v[146:149], v[90:93]
	v_mfma_f32_16x16x32_bf16 v[24:27], v[200:203], v[146:149], v[24:27]
	v_mfma_f32_16x16x32_bf16 v[82:85], v[192:195], v[154:157], v[82:85]
	v_mfma_f32_16x16x32_bf16 v[16:19], v[200:203], v[154:157], v[16:19]
	v_mfma_f32_16x16x32_bf16 v[74:77], v[192:195], v[162:165], v[74:77]
	v_mfma_f32_16x16x32_bf16 v[8:11], v[200:203], v[162:165], v[8:11]
	v_mfma_f32_16x16x32_bf16 v[66:69], v[192:195], v[170:173], v[66:69]
	v_mfma_f32_16x16x32_bf16 v[0:3], v[200:203], v[170:173], v[0:3]
	v_mfma_f32_16x16x32_bf16 v[90:93], v[196:199], v[150:153], v[90:93]
	v_mfma_f32_16x16x32_bf16 v[24:27], v[204:207], v[150:153], v[24:27]
	v_mfma_f32_16x16x32_bf16 v[82:85], v[196:199], v[158:161], v[82:85]
	v_mfma_f32_16x16x32_bf16 v[16:19], v[204:207], v[158:161], v[16:19]
	v_mfma_f32_16x16x32_bf16 v[74:77], v[196:199], v[166:169], v[74:77]
	v_mfma_f32_16x16x32_bf16 v[8:11], v[204:207], v[166:169], v[8:11]
	v_mfma_f32_16x16x32_bf16 v[66:69], v[196:199], v[188:191], v[66:69]
	v_mfma_f32_16x16x32_bf16 v[0:3], v[204:207], v[188:191], v[0:3]
	s_add_i32 s30, s30, 2
	s_add_u32 s6, s6, 0x100
	s_addc_u32 s7, s7, 0
	s_add_u32 s27, s27, 0x100
	s_addc_u32 s29, s29, 0
	s_cmp_gt_u32 s30, 13
	s_barrier
	s_cbranch_scc0 .LBB0_388
